# all K-loop s_setprio dropped, one static s_setprio 1 for waves 4-7 at kernel entry
# speedup vs baseline: 1.0051x; 1.0051x over previous
_Z9trunk_fwd4Args:
	v_readfirstlane_b32 s4, v0
	s_nop 3
	s_cmpk_lt_u32 s4, 0x100
	s_cbranch_scc1 .Lmy_prio_done
	s_setprio 1
.Lmy_prio_done:
	s_load_dword s33, s[0:1], 0x128
	v_writelane_b32 v254, s2, 0
	s_add_u32 s2, s0, 0x128
	s_addc_u32 s3, s1, 0
	v_writelane_b32 v254, s2, 1
	s_nop 1
	v_writelane_b32 v254, s3, 2
	s_movk_i32 s2, 0x80
	v_cmp_gt_u32_e32 vcc, s2, v0
	s_and_saveexec_b64 s[2:3], vcc
	v_lshl_add_u32 v1, v0, 2, 0
	v_add_u32_e32 v1, 0x23e00, v1
	v_mov_b32_e32 v2, 0
	ds_write_b32 v1, v2
	s_or_b64 exec, exec, s[2:3]
	s_load_dwordx2 s[2:3], s[0:1], 0x118
	s_waitcnt lgkmcnt(0)
	s_barrier
	s_getreg_b32 s4, hwreg(HW_REG_XCC_ID, 0, 4)
	s_add_u32 s10, s2, 0x4000
	s_addc_u32 s11, s3, 0
	s_and_b32 s20, s4, 15
	v_cmp_eq_u32_e32 vcc, 0, v0
	s_and_saveexec_b64 s[4:5], vcc
	s_cbranch_execz .LBB0_5
	s_mov_b64 s[6:7], exec
	v_mbcnt_lo_u32_b32 v1, s6, 0
	v_mbcnt_hi_u32_b32 v1, s7, v1
	v_cmp_eq_u32_e32 vcc, 0, v1
	s_and_b64 s[8:9], exec, vcc
	s_mov_b64 exec, s[8:9]
	s_cbranch_execz .LBB0_5
	s_lshl_b32 s8, s20, 8
	s_bcnt1_i32_b64 s6, s[6:7]
	v_mov_b32_e32 v1, s8
	v_mov_b32_e32 v2, s6
	global_atomic_add v1, v2, s[10:11] offset:1024

.LBB0_552:
	s_add_u32 s54, s44, 0xfff80080
	s_addc_u32 s55, s45, -1
	s_waitcnt lgkmcnt(0)
	s_add_i32 s82, 0, 0x10000
	s_cmp_eq_u32 s76, 28
	s_cselect_b32 s57, s41, s55
	s_cselect_b32 s56, s43, s54
	v_add_u32_e32 v161, s82, v159
	s_cselect_b32 s55, s35, s75
	s_cselect_b32 s54, s47, s74
	s_add_i32 vcc_lo, 0, 0x14000
	ds_read_b128 v[144:147], v161
	ds_read_b128 v[148:151], v161 offset:1024
	ds_read_b128 v[152:155], v161 offset:2048
	ds_read_b128 v[162:165], v161 offset:3072
	v_add_u32_e32 v161, vcc_lo, v159
	ds_read_b128 v[166:169], v161
	ds_read_b128 v[170:173], v161 offset:1024
	ds_read_b128 v[174:177], v161 offset:2048
	ds_read_b128 v[190:193], v161 offset:3072
	v_lshl_add_u64 v[178:179], s[44:45], 0, v[140:141]
	s_add_i32 m0, s58, 0xc000
	ds_read_b128 v[194:197], v160
	ds_read_b128 v[198:201], v160 offset:1024
	ds_read_b128 v[202:205], v160 offset:2048
	ds_read_b128 v[206:209], v160 offset:3072
	ds_read_b128 v[210:213], v160 offset:4096
	ds_read_b128 v[214:217], v160 offset:5120
	ds_read_b128 v[218:221], v160 offset:6144
	ds_read_b128 v[238:241], v160 offset:7168
	global_load_lds_dwordx4 v[178:179], off
	v_lshl_add_u64 v[178:179], s[44:45], 0, v[142:143]
	s_add_i32 m0, s58, 0xe000
	s_nop 0
	global_load_lds_dwordx4 v[178:179], off
	s_waitcnt vmcnt(8)
	s_waitcnt lgkmcnt(0)
	s_barrier
	s_waitcnt lgkmcnt(0)
	v_mfma_f32_16x16x32_bf16 v[126:129], v[144:147], v[194:197], v[126:129]
	v_mfma_f32_16x16x32_bf16 v[122:125], v[152:155], v[194:197], v[122:125]
	v_mfma_f32_16x16x32_bf16 v[110:113], v[144:147], v[202:205], v[110:113]
	v_mfma_f32_16x16x32_bf16 v[106:109], v[152:155], v[202:205], v[106:109]
	v_mfma_f32_16x16x32_bf16 v[94:97], v[144:147], v[210:213], v[94:97]
	v_mfma_f32_16x16x32_bf16 v[90:93], v[152:155], v[210:213], v[90:93]
	v_mfma_f32_16x16x32_bf16 v[78:81], v[144:147], v[218:221], v[78:81]
	v_mfma_f32_16x16x32_bf16 v[74:77], v[152:155], v[218:221], v[74:77]
	v_mfma_f32_16x16x32_bf16 v[126:129], v[148:151], v[198:201], v[126:129]
	v_mfma_f32_16x16x32_bf16 v[122:125], v[162:165], v[198:201], v[122:125]
	v_mfma_f32_16x16x32_bf16 v[110:113], v[148:151], v[206:209], v[110:113]
	v_mfma_f32_16x16x32_bf16 v[106:109], v[162:165], v[206:209], v[106:109]
	v_mfma_f32_16x16x32_bf16 v[94:97], v[148:151], v[214:217], v[94:97]
	v_mfma_f32_16x16x32_bf16 v[90:93], v[162:165], v[214:217], v[90:93]
	v_mfma_f32_16x16x32_bf16 v[78:81], v[148:151], v[238:241], v[78:81]
	v_mfma_f32_16x16x32_bf16 v[74:77], v[162:165], v[238:241], v[74:77]
	v_mfma_f32_16x16x32_bf16 v[118:121], v[166:169], v[194:197], v[118:121]
	v_mfma_f32_16x16x32_bf16 v[114:117], v[174:177], v[194:197], v[114:117]
	v_mfma_f32_16x16x32_bf16 v[102:105], v[166:169], v[202:205], v[102:105]
	v_mfma_f32_16x16x32_bf16 v[98:101], v[174:177], v[202:205], v[98:101]
	v_mfma_f32_16x16x32_bf16 v[86:89], v[166:169], v[210:213], v[86:89]
	v_mfma_f32_16x16x32_bf16 v[82:85], v[174:177], v[210:213], v[82:85]
	v_mfma_f32_16x16x32_bf16 v[70:73], v[166:169], v[218:221], v[70:73]
	v_mfma_f32_16x16x32_bf16 v[66:69], v[174:177], v[218:221], v[66:69]
	v_mfma_f32_16x16x32_bf16 v[118:121], v[170:173], v[198:201], v[118:121]
	v_mfma_f32_16x16x32_bf16 v[114:117], v[190:193], v[198:201], v[114:117]
	v_mfma_f32_16x16x32_bf16 v[102:105], v[170:173], v[206:209], v[102:105]
	v_mfma_f32_16x16x32_bf16 v[98:101], v[190:193], v[206:209], v[98:101]
	v_mfma_f32_16x16x32_bf16 v[86:89], v[170:173], v[214:217], v[86:89]
	v_mfma_f32_16x16x32_bf16 v[82:85], v[190:193], v[214:217], v[82:85]
	v_mfma_f32_16x16x32_bf16 v[70:73], v[170:173], v[238:241], v[70:73]
	v_mfma_f32_16x16x32_bf16 v[66:69], v[190:193], v[238:241], v[66:69]
	s_barrier
	s_add_i32 s82, s82, s9
	v_lshl_add_u64 v[178:179], s[54:55], 0, v[134:135]
	s_mov_b32 m0, s82
	ds_read_b128 v[194:197], v160 offset:16384
	ds_read_b128 v[198:201], v160 offset:17408
	ds_read_b128 v[202:205], v160 offset:18432
	ds_read_b128 v[206:209], v160 offset:19456
	ds_read_b128 v[210:213], v160 offset:20480
	ds_read_b128 v[214:217], v160 offset:21504
	ds_read_b128 v[218:221], v160 offset:22528
	ds_read_b128 v[238:241], v160 offset:23552
	global_load_lds_dwordx4 v[178:179], off
	s_add_i32 m0, s82, 0x2000
	s_add_u32 s82, s54, 0x80000
	v_lshl_add_u64 v[222:223], s[54:55], 0, v[138:139]
	s_addc_u32 s83, s55, 0
	s_add_i32 vcc_lo, vcc_lo, s9
	global_load_lds_dwordx4 v[222:223], off
	v_lshl_add_u64 v[242:243], s[82:83], 0, v[134:135]
	s_mov_b32 m0, vcc_lo
	v_lshl_add_u64 v[244:245], s[56:57], 0, v[136:137]
	global_load_lds_dwordx4 v[242:243], off
	v_lshl_add_u64 v[242:243], s[82:83], 0, v[138:139]
	s_add_i32 m0, vcc_lo, 0x2000
	s_nop 0
	global_load_lds_dwordx4 v[242:243], off
	v_lshl_add_u64 v[242:243], s[56:57], 0, v[132:133]
	s_mov_b32 m0, s58
	s_nop 0
	global_load_lds_dwordx4 v[242:243], off
	s_mov_b32 m0, s59
	s_nop 0
	global_load_lds_dwordx4 v[244:245], off
	s_waitcnt vmcnt(8)
	s_waitcnt lgkmcnt(0)
	s_barrier
	s_waitcnt lgkmcnt(0)
	v_mfma_f32_16x16x32_bf16 v[62:65], v[144:147], v[194:197], v[62:65]
	v_mfma_f32_16x16x32_bf16 v[58:61], v[152:155], v[194:197], v[58:61]
	v_mfma_f32_16x16x32_bf16 v[46:49], v[144:147], v[202:205], v[46:49]
	v_mfma_f32_16x16x32_bf16 v[42:45], v[152:155], v[202:205], v[42:45]
	v_mfma_f32_16x16x32_bf16 v[30:33], v[144:147], v[210:213], v[30:33]
	v_mfma_f32_16x16x32_bf16 v[26:29], v[152:155], v[210:213], v[26:29]
	v_mfma_f32_16x16x32_bf16 v[14:17], v[144:147], v[218:221], v[14:17]
	v_mfma_f32_16x16x32_bf16 v[10:13], v[152:155], v[218:221], v[10:13]
	v_mfma_f32_16x16x32_bf16 v[62:65], v[148:151], v[198:201], v[62:65]
	v_mfma_f32_16x16x32_bf16 v[58:61], v[162:165], v[198:201], v[58:61]
	v_mfma_f32_16x16x32_bf16 v[46:49], v[148:151], v[206:209], v[46:49]
	v_mfma_f32_16x16x32_bf16 v[42:45], v[162:165], v[206:209], v[42:45]
	v_mfma_f32_16x16x32_bf16 v[30:33], v[148:151], v[214:217], v[30:33]
	v_mfma_f32_16x16x32_bf16 v[26:29], v[162:165], v[214:217], v[26:29]
	v_mfma_f32_16x16x32_bf16 v[14:17], v[148:151], v[238:241], v[14:17]
	v_mfma_f32_16x16x32_bf16 v[10:13], v[162:165], v[238:241], v[10:13]
	v_mfma_f32_16x16x32_bf16 v[54:57], v[166:169], v[194:197], v[54:57]
	v_mfma_f32_16x16x32_bf16 v[50:53], v[174:177], v[194:197], v[50:53]
	v_mfma_f32_16x16x32_bf16 v[38:41], v[166:169], v[202:205], v[38:41]
	v_mfma_f32_16x16x32_bf16 v[34:37], v[174:177], v[202:205], v[34:37]
	v_mfma_f32_16x16x32_bf16 v[22:25], v[166:169], v[210:213], v[22:25]
	v_mfma_f32_16x16x32_bf16 v[18:21], v[174:177], v[210:213], v[18:21]
	v_mfma_f32_16x16x32_bf16 v[6:9], v[166:169], v[218:221], v[6:9]
	v_mfma_f32_16x16x32_bf16 v[2:5], v[174:177], v[218:221], v[2:5]
	v_mfma_f32_16x16x32_bf16 v[54:57], v[170:173], v[198:201], v[54:57]
	v_mfma_f32_16x16x32_bf16 v[50:53], v[190:193], v[198:201], v[50:53]
	v_mfma_f32_16x16x32_bf16 v[38:41], v[170:173], v[206:209], v[38:41]
	v_mfma_f32_16x16x32_bf16 v[34:37], v[190:193], v[206:209], v[34:37]
	v_mfma_f32_16x16x32_bf16 v[22:25], v[170:173], v[214:217], v[22:25]
	v_mfma_f32_16x16x32_bf16 v[18:21], v[190:193], v[214:217], v[18:21]
	v_mfma_f32_16x16x32_bf16 v[6:9], v[170:173], v[238:241], v[6:9]
	v_mfma_f32_16x16x32_bf16 v[2:5], v[190:193], v[238:241], v[2:5]
	s_barrier
	s_add_i32 s82, 0, 0x18000
	v_add_u32_e32 v161, s82, v159
	s_add_i32 s83, 0, 0x1c000
	ds_read_b128 v[144:147], v161
	ds_read_b128 v[148:151], v161 offset:1024
	ds_read_b128 v[152:155], v161 offset:2048
	ds_read_b128 v[162:165], v161 offset:3072
	v_add_u32_e32 v161, s83, v159
	ds_read_b128 v[166:169], v161
	ds_read_b128 v[170:173], v161 offset:1024
	ds_read_b128 v[174:177], v161 offset:2048
	ds_read_b128 v[190:193], v161 offset:3072
	s_add_u32 s56, s56, 0x80000
	s_addc_u32 s57, s57, 0
	s_mov_b32 m0, s60
	v_lshl_add_u64 v[246:247], s[56:57], 0, v[132:133]
	ds_read_b128 v[194:197], v160 offset:32768
	ds_read_b128 v[198:201], v160 offset:33792
	ds_read_b128 v[202:205], v160 offset:34816
	ds_read_b128 v[206:209], v160 offset:35840
	ds_read_b128 v[210:213], v160 offset:36864
	ds_read_b128 v[214:217], v160 offset:37888
	ds_read_b128 v[218:221], v160 offset:38912
	ds_read_b128 v[238:241], v160 offset:39936
	global_load_lds_dwordx4 v[246:247], off
	v_lshl_add_u64 v[246:247], s[56:57], 0, v[136:137]
	s_mov_b32 m0, s61
	s_nop 0
	global_load_lds_dwordx4 v[246:247], off
	s_waitcnt vmcnt(8)
	s_waitcnt lgkmcnt(0)
	s_barrier
	s_waitcnt lgkmcnt(0)
	v_mfma_f32_16x16x32_bf16 v[126:129], v[144:147], v[194:197], v[126:129]
	v_mfma_f32_16x16x32_bf16 v[122:125], v[152:155], v[194:197], v[122:125]
	v_mfma_f32_16x16x32_bf16 v[110:113], v[144:147], v[202:205], v[110:113]
	v_mfma_f32_16x16x32_bf16 v[106:109], v[152:155], v[202:205], v[106:109]
	v_mfma_f32_16x16x32_bf16 v[94:97], v[144:147], v[210:213], v[94:97]
	v_mfma_f32_16x16x32_bf16 v[90:93], v[152:155], v[210:213], v[90:93]
	v_mfma_f32_16x16x32_bf16 v[78:81], v[144:147], v[218:221], v[78:81]
	v_mfma_f32_16x16x32_bf16 v[74:77], v[152:155], v[218:221], v[74:77]
	v_mfma_f32_16x16x32_bf16 v[126:129], v[148:151], v[198:201], v[126:129]
	v_mfma_f32_16x16x32_bf16 v[122:125], v[162:165], v[198:201], v[122:125]
	v_mfma_f32_16x16x32_bf16 v[110:113], v[148:151], v[206:209], v[110:113]
	v_mfma_f32_16x16x32_bf16 v[106:109], v[162:165], v[206:209], v[106:109]
	v_mfma_f32_16x16x32_bf16 v[94:97], v[148:151], v[214:217], v[94:97]
	v_mfma_f32_16x16x32_bf16 v[90:93], v[162:165], v[214:217], v[90:93]
	v_mfma_f32_16x16x32_bf16 v[78:81], v[148:151], v[238:241], v[78:81]
	v_mfma_f32_16x16x32_bf16 v[74:77], v[162:165], v[238:241], v[74:77]
	v_mfma_f32_16x16x32_bf16 v[118:121], v[166:169], v[194:197], v[118:121]
	v_mfma_f32_16x16x32_bf16 v[114:117], v[174:177], v[194:197], v[114:117]
	v_mfma_f32_16x16x32_bf16 v[102:105], v[166:169], v[202:205], v[102:105]
	v_mfma_f32_16x16x32_bf16 v[98:101], v[174:177], v[202:205], v[98:101]
	v_mfma_f32_16x16x32_bf16 v[86:89], v[166:169], v[210:213], v[86:89]
	v_mfma_f32_16x16x32_bf16 v[82:85], v[174:177], v[210:213], v[82:85]
	v_mfma_f32_16x16x32_bf16 v[70:73], v[166:169], v[218:221], v[70:73]
	v_mfma_f32_16x16x32_bf16 v[66:69], v[174:177], v[218:221], v[66:69]
	v_mfma_f32_16x16x32_bf16 v[118:121], v[170:173], v[198:201], v[118:121]
	v_mfma_f32_16x16x32_bf16 v[114:117], v[190:193], v[198:201], v[114:117]
	v_mfma_f32_16x16x32_bf16 v[102:105], v[170:173], v[206:209], v[102:105]
	v_mfma_f32_16x16x32_bf16 v[98:101], v[190:193], v[206:209], v[98:101]
	v_mfma_f32_16x16x32_bf16 v[86:89], v[170:173], v[214:217], v[86:89]
	v_mfma_f32_16x16x32_bf16 v[82:85], v[190:193], v[214:217], v[82:85]
	v_mfma_f32_16x16x32_bf16 v[70:73], v[170:173], v[238:241], v[70:73]
	v_mfma_f32_16x16x32_bf16 v[66:69], v[190:193], v[238:241], v[66:69]
	s_barrier
	s_add_i32 s56, s82, s9
	v_lshl_add_u64 v[178:179], v[178:179], 0, s[16:17]
	s_mov_b32 m0, s56
	ds_read_b128 v[194:197], v160 offset:49152
	ds_read_b128 v[198:201], v160 offset:50176
	ds_read_b128 v[202:205], v160 offset:51200
	ds_read_b128 v[206:209], v160 offset:52224
	ds_read_b128 v[210:213], v160 offset:53248
	ds_read_b128 v[214:217], v160 offset:54272
	ds_read_b128 v[218:221], v160 offset:55296
	ds_read_b128 v[238:241], v160 offset:56320
	global_load_lds_dwordx4 v[178:179], off
	s_add_i32 m0, s56, 0x2000
	s_add_u32 s54, s54, 0x80080
	v_lshl_add_u64 v[178:179], v[222:223], 0, s[16:17]
	s_addc_u32 s55, s55, 0
	s_add_i32 s56, s83, s9
	global_load_lds_dwordx4 v[178:179], off
	v_lshl_add_u64 v[178:179], s[54:55], 0, v[134:135]
	s_mov_b32 m0, s56
	s_nop 0
	global_load_lds_dwordx4 v[178:179], off
	v_lshl_add_u64 v[178:179], s[54:55], 0, v[138:139]
	s_add_i32 m0, s56, 0x2000
	s_nop 0
	global_load_lds_dwordx4 v[178:179], off
	v_lshl_add_u64 v[178:179], v[242:243], 0, s[16:17]
	s_mov_b32 m0, s64
	s_nop 0
	global_load_lds_dwordx4 v[178:179], off
	v_lshl_add_u64 v[178:179], v[244:245], 0, s[16:17]
	s_mov_b32 m0, s69
	s_nop 0
	global_load_lds_dwordx4 v[178:179], off
	s_waitcnt vmcnt(8)
	s_waitcnt lgkmcnt(0)
	s_barrier
	s_waitcnt lgkmcnt(0)
	v_mfma_f32_16x16x32_bf16 v[62:65], v[144:147], v[194:197], v[62:65]
	v_mfma_f32_16x16x32_bf16 v[58:61], v[152:155], v[194:197], v[58:61]
	v_mfma_f32_16x16x32_bf16 v[46:49], v[144:147], v[202:205], v[46:49]
	v_mfma_f32_16x16x32_bf16 v[42:45], v[152:155], v[202:205], v[42:45]
	v_mfma_f32_16x16x32_bf16 v[30:33], v[144:147], v[210:213], v[30:33]
	v_mfma_f32_16x16x32_bf16 v[26:29], v[152:155], v[210:213], v[26:29]
	v_mfma_f32_16x16x32_bf16 v[14:17], v[144:147], v[218:221], v[14:17]
	v_mfma_f32_16x16x32_bf16 v[10:13], v[152:155], v[218:221], v[10:13]
	v_mfma_f32_16x16x32_bf16 v[62:65], v[148:151], v[198:201], v[62:65]
	v_mfma_f32_16x16x32_bf16 v[58:61], v[162:165], v[198:201], v[58:61]
	v_mfma_f32_16x16x32_bf16 v[46:49], v[148:151], v[206:209], v[46:49]
	v_mfma_f32_16x16x32_bf16 v[42:45], v[162:165], v[206:209], v[42:45]
	v_mfma_f32_16x16x32_bf16 v[30:33], v[148:151], v[214:217], v[30:33]
	v_mfma_f32_16x16x32_bf16 v[26:29], v[162:165], v[214:217], v[26:29]
	v_mfma_f32_16x16x32_bf16 v[14:17], v[148:151], v[238:241], v[14:17]
	v_mfma_f32_16x16x32_bf16 v[10:13], v[162:165], v[238:241], v[10:13]
	v_mfma_f32_16x16x32_bf16 v[54:57], v[166:169], v[194:197], v[54:57]
	v_mfma_f32_16x16x32_bf16 v[50:53], v[174:177], v[194:197], v[50:53]
	v_mfma_f32_16x16x32_bf16 v[38:41], v[166:169], v[202:205], v[38:41]
	v_mfma_f32_16x16x32_bf16 v[34:37], v[174:177], v[202:205], v[34:37]
	v_mfma_f32_16x16x32_bf16 v[22:25], v[166:169], v[210:213], v[22:25]
	v_mfma_f32_16x16x32_bf16 v[18:21], v[174:177], v[210:213], v[18:21]
	v_mfma_f32_16x16x32_bf16 v[6:9], v[166:169], v[218:221], v[6:9]
	v_mfma_f32_16x16x32_bf16 v[2:5], v[174:177], v[218:221], v[2:5]
	v_mfma_f32_16x16x32_bf16 v[54:57], v[170:173], v[198:201], v[54:57]
	v_mfma_f32_16x16x32_bf16 v[50:53], v[190:193], v[198:201], v[50:53]
	v_mfma_f32_16x16x32_bf16 v[38:41], v[170:173], v[206:209], v[38:41]
	v_mfma_f32_16x16x32_bf16 v[34:37], v[190:193], v[206:209], v[34:37]
	v_mfma_f32_16x16x32_bf16 v[22:25], v[170:173], v[214:217], v[22:25]
	v_mfma_f32_16x16x32_bf16 v[18:21], v[190:193], v[214:217], v[18:21]
	v_mfma_f32_16x16x32_bf16 v[6:9], v[170:173], v[238:241], v[6:9]
	v_mfma_f32_16x16x32_bf16 v[2:5], v[190:193], v[238:241], v[2:5]
	s_barrier
	s_add_i32 s76, s76, 2
	s_add_u32 s44, s44, 0x100
	s_addc_u32 s45, s45, 0
	s_add_u32 s74, s74, 0x100
	s_addc_u32 s75, s75, 0
	s_cmp_gt_u32 s76, 29
	s_cbranch_scc0 .LBB0_552
	s_and_b64 vcc, exec, s[30:31]
	s_cbranch_vccz .LBB0_555
	s_barrier

.LBB0_824:
	s_add_i32 s64, s40, 2
	s_add_u32 s69, s34, 0x80
	s_addc_u32 s41, s35, 0
	s_add_i32 s74, 0, 0x10000
	s_cmp_eq_u32 s57, s40
	s_cselect_b32 s41, s29, s41
	s_cselect_b32 s40, s28, s69
	v_add_u32_e32 v148, s74, v146
	s_cselect_b32 s71, s31, s63
	s_cselect_b32 s70, s30, s62
	s_add_i32 s69, 0, 0x14000
	ds_read_b128 v[154:157], v148
	ds_read_b128 v[158:161], v148 offset:1024
	ds_read_b128 v[162:165], v148 offset:2048
	ds_read_b128 v[166:169], v148 offset:3072
	v_add_u32_e32 v148, s69, v146
	ds_read_b128 v[170:173], v148
	ds_read_b128 v[174:177], v148 offset:1024
	ds_read_b128 v[190:193], v148 offset:2048
	ds_read_b128 v[194:197], v148 offset:3072
	v_lshl_add_u64 v[148:149], s[34:35], 0, v[140:141]
	s_add_i32 m0, s45, 0xc000
	ds_read_b128 v[198:201], v147
	ds_read_b128 v[202:205], v147 offset:1024
	ds_read_b128 v[206:209], v147 offset:2048
	ds_read_b128 v[210:213], v147 offset:3072
	ds_read_b128 v[214:217], v147 offset:4096
	ds_read_b128 v[218:221], v147 offset:5120
	ds_read_b128 v[238:241], v147 offset:6144
	ds_read_b128 v[242:245], v147 offset:7168
	global_load_lds_dwordx4 v[148:149], off
	v_lshl_add_u64 v[148:149], s[34:35], 0, v[142:143]
	s_add_i32 m0, s45, 0xe000
	s_nop 0
	global_load_lds_dwordx4 v[148:149], off
	s_waitcnt vmcnt(8)
	s_waitcnt lgkmcnt(0)
	s_barrier
	s_waitcnt lgkmcnt(0)
	v_mfma_f32_16x16x32_bf16 v[126:129], v[154:157], v[198:201], v[126:129]
	v_mfma_f32_16x16x32_bf16 v[122:125], v[162:165], v[198:201], v[122:125]
	v_mfma_f32_16x16x32_bf16 v[110:113], v[154:157], v[206:209], v[110:113]
	v_mfma_f32_16x16x32_bf16 v[106:109], v[162:165], v[206:209], v[106:109]
	v_mfma_f32_16x16x32_bf16 v[94:97], v[154:157], v[214:217], v[94:97]
	v_mfma_f32_16x16x32_bf16 v[90:93], v[162:165], v[214:217], v[90:93]
	v_mfma_f32_16x16x32_bf16 v[78:81], v[154:157], v[238:241], v[78:81]
	v_mfma_f32_16x16x32_bf16 v[74:77], v[162:165], v[238:241], v[74:77]
	v_mfma_f32_16x16x32_bf16 v[126:129], v[158:161], v[202:205], v[126:129]
	v_mfma_f32_16x16x32_bf16 v[122:125], v[166:169], v[202:205], v[122:125]
	v_mfma_f32_16x16x32_bf16 v[110:113], v[158:161], v[210:213], v[110:113]
	v_mfma_f32_16x16x32_bf16 v[106:109], v[166:169], v[210:213], v[106:109]
	v_mfma_f32_16x16x32_bf16 v[94:97], v[158:161], v[218:221], v[94:97]
	v_mfma_f32_16x16x32_bf16 v[90:93], v[166:169], v[218:221], v[90:93]
	v_mfma_f32_16x16x32_bf16 v[78:81], v[158:161], v[242:245], v[78:81]
	v_mfma_f32_16x16x32_bf16 v[74:77], v[166:169], v[242:245], v[74:77]
	v_mfma_f32_16x16x32_bf16 v[118:121], v[170:173], v[198:201], v[118:121]
	v_mfma_f32_16x16x32_bf16 v[114:117], v[190:193], v[198:201], v[114:117]
	v_mfma_f32_16x16x32_bf16 v[102:105], v[170:173], v[206:209], v[102:105]
	v_mfma_f32_16x16x32_bf16 v[98:101], v[190:193], v[206:209], v[98:101]
	v_mfma_f32_16x16x32_bf16 v[86:89], v[170:173], v[214:217], v[86:89]
	v_mfma_f32_16x16x32_bf16 v[82:85], v[190:193], v[214:217], v[82:85]
	v_mfma_f32_16x16x32_bf16 v[70:73], v[170:173], v[238:241], v[70:73]
	v_mfma_f32_16x16x32_bf16 v[66:69], v[190:193], v[238:241], v[66:69]
	v_mfma_f32_16x16x32_bf16 v[118:121], v[174:177], v[202:205], v[118:121]
	v_mfma_f32_16x16x32_bf16 v[114:117], v[194:197], v[202:205], v[114:117]
	v_mfma_f32_16x16x32_bf16 v[102:105], v[174:177], v[210:213], v[102:105]
	v_mfma_f32_16x16x32_bf16 v[98:101], v[194:197], v[210:213], v[98:101]
	v_mfma_f32_16x16x32_bf16 v[86:89], v[174:177], v[218:221], v[86:89]
	v_mfma_f32_16x16x32_bf16 v[82:85], v[194:197], v[218:221], v[82:85]
	v_mfma_f32_16x16x32_bf16 v[70:73], v[174:177], v[242:245], v[70:73]
	v_mfma_f32_16x16x32_bf16 v[66:69], v[194:197], v[242:245], v[66:69]
	s_barrier
	s_add_i32 s74, s74, s44
	v_lshl_add_u64 v[148:149], s[70:71], 0, v[136:137]
	s_mov_b32 m0, s74
	ds_read_b128 v[198:201], v147 offset:16384
	ds_read_b128 v[202:205], v147 offset:17408
	ds_read_b128 v[206:209], v147 offset:18432
	ds_read_b128 v[210:213], v147 offset:19456
	ds_read_b128 v[214:217], v147 offset:20480
	ds_read_b128 v[218:221], v147 offset:21504
	ds_read_b128 v[238:241], v147 offset:22528
	ds_read_b128 v[242:245], v147 offset:23552
	global_load_lds_dwordx4 v[148:149], off
	s_add_i32 m0, s74, 0x2000
	v_lshl_add_u64 v[178:179], s[70:71], 0, v[132:133]
	s_add_u32 s70, s70, s10
	s_addc_u32 s71, s71, s11
	s_add_i32 s69, s69, s44
	global_load_lds_dwordx4 v[178:179], off
	v_lshl_add_u64 v[222:223], s[70:71], 0, v[136:137]
	s_mov_b32 m0, s69
	v_lshl_add_u64 v[246:247], s[70:71], 0, v[132:133]
	global_load_lds_dwordx4 v[222:223], off
	s_add_i32 m0, s69, 0x2000
	v_lshl_add_u64 v[248:249], s[40:41], 0, v[138:139]
	global_load_lds_dwordx4 v[246:247], off
	s_mov_b32 m0, s45
	v_lshl_add_u64 v[250:251], s[40:41], 0, v[134:135]
	global_load_lds_dwordx4 v[248:249], off
	s_mov_b32 m0, s46
	s_nop 0
	global_load_lds_dwordx4 v[250:251], off
	s_waitcnt vmcnt(8)
	s_waitcnt lgkmcnt(0)
	s_barrier
	s_waitcnt lgkmcnt(0)
	v_mfma_f32_16x16x32_bf16 v[62:65], v[154:157], v[198:201], v[62:65]
	v_mfma_f32_16x16x32_bf16 v[58:61], v[162:165], v[198:201], v[58:61]
	v_mfma_f32_16x16x32_bf16 v[46:49], v[154:157], v[206:209], v[46:49]
	v_mfma_f32_16x16x32_bf16 v[42:45], v[162:165], v[206:209], v[42:45]
	v_mfma_f32_16x16x32_bf16 v[30:33], v[154:157], v[214:217], v[30:33]
	v_mfma_f32_16x16x32_bf16 v[26:29], v[162:165], v[214:217], v[26:29]
	v_mfma_f32_16x16x32_bf16 v[14:17], v[154:157], v[238:241], v[14:17]
	v_mfma_f32_16x16x32_bf16 v[10:13], v[162:165], v[238:241], v[10:13]
	v_mfma_f32_16x16x32_bf16 v[62:65], v[158:161], v[202:205], v[62:65]
	v_mfma_f32_16x16x32_bf16 v[58:61], v[166:169], v[202:205], v[58:61]
	v_mfma_f32_16x16x32_bf16 v[46:49], v[158:161], v[210:213], v[46:49]
	v_mfma_f32_16x16x32_bf16 v[42:45], v[166:169], v[210:213], v[42:45]
	v_mfma_f32_16x16x32_bf16 v[30:33], v[158:161], v[218:221], v[30:33]
	v_mfma_f32_16x16x32_bf16 v[26:29], v[166:169], v[218:221], v[26:29]
	v_mfma_f32_16x16x32_bf16 v[14:17], v[158:161], v[242:245], v[14:17]
	v_mfma_f32_16x16x32_bf16 v[10:13], v[166:169], v[242:245], v[10:13]
	v_mfma_f32_16x16x32_bf16 v[54:57], v[170:173], v[198:201], v[54:57]
	v_mfma_f32_16x16x32_bf16 v[50:53], v[190:193], v[198:201], v[50:53]
	v_mfma_f32_16x16x32_bf16 v[38:41], v[170:173], v[206:209], v[38:41]
	v_mfma_f32_16x16x32_bf16 v[34:37], v[190:193], v[206:209], v[34:37]
	v_mfma_f32_16x16x32_bf16 v[22:25], v[170:173], v[214:217], v[22:25]
	v_mfma_f32_16x16x32_bf16 v[18:21], v[190:193], v[214:217], v[18:21]
	v_mfma_f32_16x16x32_bf16 v[6:9], v[170:173], v[238:241], v[6:9]
	v_mfma_f32_16x16x32_bf16 v[2:5], v[190:193], v[238:241], v[2:5]
	v_mfma_f32_16x16x32_bf16 v[54:57], v[174:177], v[202:205], v[54:57]
	v_mfma_f32_16x16x32_bf16 v[50:53], v[194:197], v[202:205], v[50:53]
	v_mfma_f32_16x16x32_bf16 v[38:41], v[174:177], v[210:213], v[38:41]
	v_mfma_f32_16x16x32_bf16 v[34:37], v[194:197], v[210:213], v[34:37]
	v_mfma_f32_16x16x32_bf16 v[22:25], v[174:177], v[218:221], v[22:25]
	v_mfma_f32_16x16x32_bf16 v[18:21], v[194:197], v[218:221], v[18:21]
	v_mfma_f32_16x16x32_bf16 v[6:9], v[174:177], v[242:245], v[6:9]
	v_mfma_f32_16x16x32_bf16 v[2:5], v[194:197], v[242:245], v[2:5]
	s_barrier
	s_add_i32 s69, 0, 0x18000
	v_add_u32_e32 v151, s69, v146
	s_add_i32 s70, 0, 0x1c000
	ds_read_b128 v[154:157], v151
	ds_read_b128 v[158:161], v151 offset:1024
	ds_read_b128 v[162:165], v151 offset:2048
	ds_read_b128 v[166:169], v151 offset:3072
	v_add_u32_e32 v151, s70, v146
	ds_read_b128 v[170:173], v151
	ds_read_b128 v[174:177], v151 offset:1024
	ds_read_b128 v[190:193], v151 offset:2048
	ds_read_b128 v[194:197], v151 offset:3072
	s_add_u32 s40, s40, s10
	s_addc_u32 s41, s41, s11
	s_mov_b32 m0, s47
	v_lshl_add_u64 v[252:253], s[40:41], 0, v[138:139]
	ds_read_b128 v[198:201], v147 offset:32768
	ds_read_b128 v[202:205], v147 offset:33792
	ds_read_b128 v[206:209], v147 offset:34816
	ds_read_b128 v[210:213], v147 offset:35840
	ds_read_b128 v[214:217], v147 offset:36864
	ds_read_b128 v[218:221], v147 offset:37888
	ds_read_b128 v[238:241], v147 offset:38912
	ds_read_b128 v[242:245], v147 offset:39936
	global_load_lds_dwordx4 v[252:253], off
	v_lshl_add_u64 v[252:253], s[40:41], 0, v[134:135]
	s_mov_b32 m0, s48
	s_nop 0
	global_load_lds_dwordx4 v[252:253], off
	s_waitcnt vmcnt(8)
	s_waitcnt lgkmcnt(0)
	s_barrier
	s_waitcnt lgkmcnt(0)
	v_mfma_f32_16x16x32_bf16 v[126:129], v[154:157], v[198:201], v[126:129]
	v_mfma_f32_16x16x32_bf16 v[122:125], v[162:165], v[198:201], v[122:125]
	v_mfma_f32_16x16x32_bf16 v[110:113], v[154:157], v[206:209], v[110:113]
	v_mfma_f32_16x16x32_bf16 v[106:109], v[162:165], v[206:209], v[106:109]
	v_mfma_f32_16x16x32_bf16 v[94:97], v[154:157], v[214:217], v[94:97]
	v_mfma_f32_16x16x32_bf16 v[90:93], v[162:165], v[214:217], v[90:93]
	v_mfma_f32_16x16x32_bf16 v[78:81], v[154:157], v[238:241], v[78:81]
	v_mfma_f32_16x16x32_bf16 v[74:77], v[162:165], v[238:241], v[74:77]
	v_mfma_f32_16x16x32_bf16 v[126:129], v[158:161], v[202:205], v[126:129]
	v_mfma_f32_16x16x32_bf16 v[122:125], v[166:169], v[202:205], v[122:125]
	v_mfma_f32_16x16x32_bf16 v[110:113], v[158:161], v[210:213], v[110:113]
	v_mfma_f32_16x16x32_bf16 v[106:109], v[166:169], v[210:213], v[106:109]
	v_mfma_f32_16x16x32_bf16 v[94:97], v[158:161], v[218:221], v[94:97]
	v_mfma_f32_16x16x32_bf16 v[90:93], v[166:169], v[218:221], v[90:93]
	v_mfma_f32_16x16x32_bf16 v[78:81], v[158:161], v[242:245], v[78:81]
	v_mfma_f32_16x16x32_bf16 v[74:77], v[166:169], v[242:245], v[74:77]
	v_mfma_f32_16x16x32_bf16 v[118:121], v[170:173], v[198:201], v[118:121]
	v_mfma_f32_16x16x32_bf16 v[114:117], v[190:193], v[198:201], v[114:117]
	v_mfma_f32_16x16x32_bf16 v[102:105], v[170:173], v[206:209], v[102:105]
	v_mfma_f32_16x16x32_bf16 v[98:101], v[190:193], v[206:209], v[98:101]
	v_mfma_f32_16x16x32_bf16 v[86:89], v[170:173], v[214:217], v[86:89]
	v_mfma_f32_16x16x32_bf16 v[82:85], v[190:193], v[214:217], v[82:85]
	v_mfma_f32_16x16x32_bf16 v[70:73], v[170:173], v[238:241], v[70:73]
	v_mfma_f32_16x16x32_bf16 v[66:69], v[190:193], v[238:241], v[66:69]
	v_mfma_f32_16x16x32_bf16 v[118:121], v[174:177], v[202:205], v[118:121]
	v_mfma_f32_16x16x32_bf16 v[114:117], v[194:197], v[202:205], v[114:117]
	v_mfma_f32_16x16x32_bf16 v[102:105], v[174:177], v[210:213], v[102:105]
	v_mfma_f32_16x16x32_bf16 v[98:101], v[194:197], v[210:213], v[98:101]
	v_mfma_f32_16x16x32_bf16 v[86:89], v[174:177], v[218:221], v[86:89]
	v_mfma_f32_16x16x32_bf16 v[82:85], v[194:197], v[218:221], v[82:85]
	v_mfma_f32_16x16x32_bf16 v[70:73], v[174:177], v[242:245], v[70:73]
	v_mfma_f32_16x16x32_bf16 v[66:69], v[194:197], v[242:245], v[66:69]
	s_barrier
	s_add_i32 s40, s69, s44
	v_lshl_add_u64 v[148:149], v[148:149], 0, s[16:17]
	s_mov_b32 m0, s40
	ds_read_b128 v[198:201], v147 offset:49152
	ds_read_b128 v[202:205], v147 offset:50176
	ds_read_b128 v[206:209], v147 offset:51200
	ds_read_b128 v[210:213], v147 offset:52224
	ds_read_b128 v[214:217], v147 offset:53248
	ds_read_b128 v[218:221], v147 offset:54272
	ds_read_b128 v[238:241], v147 offset:55296
	ds_read_b128 v[242:245], v147 offset:56320
	global_load_lds_dwordx4 v[148:149], off
	v_lshl_add_u64 v[148:149], v[178:179], 0, s[16:17]
	s_add_i32 m0, s40, 0x2000
	s_add_i32 s40, s70, s44
	global_load_lds_dwordx4 v[148:149], off
	v_lshl_add_u64 v[148:149], v[222:223], 0, s[16:17]
	s_mov_b32 m0, s40
	s_nop 0
	global_load_lds_dwordx4 v[148:149], off
	v_lshl_add_u64 v[148:149], v[246:247], 0, s[16:17]
	s_add_i32 m0, s40, 0x2000
	s_nop 0
	global_load_lds_dwordx4 v[148:149], off
	v_lshl_add_u64 v[148:149], v[248:249], 0, s[16:17]
	s_mov_b32 m0, s49
	s_nop 0
	global_load_lds_dwordx4 v[148:149], off
	v_lshl_add_u64 v[148:149], v[250:251], 0, s[16:17]
	s_mov_b32 m0, s50
	s_nop 0
	global_load_lds_dwordx4 v[148:149], off
	s_waitcnt vmcnt(8)
	s_waitcnt lgkmcnt(0)
	s_barrier
	s_waitcnt lgkmcnt(0)
	v_mfma_f32_16x16x32_bf16 v[62:65], v[154:157], v[198:201], v[62:65]
	v_mfma_f32_16x16x32_bf16 v[58:61], v[162:165], v[198:201], v[58:61]
	v_mfma_f32_16x16x32_bf16 v[46:49], v[154:157], v[206:209], v[46:49]
	v_mfma_f32_16x16x32_bf16 v[42:45], v[162:165], v[206:209], v[42:45]
	v_mfma_f32_16x16x32_bf16 v[30:33], v[154:157], v[214:217], v[30:33]
	v_mfma_f32_16x16x32_bf16 v[26:29], v[162:165], v[214:217], v[26:29]
	v_mfma_f32_16x16x32_bf16 v[14:17], v[154:157], v[238:241], v[14:17]
	v_mfma_f32_16x16x32_bf16 v[10:13], v[162:165], v[238:241], v[10:13]
	v_mfma_f32_16x16x32_bf16 v[62:65], v[158:161], v[202:205], v[62:65]
	v_mfma_f32_16x16x32_bf16 v[58:61], v[166:169], v[202:205], v[58:61]
	v_mfma_f32_16x16x32_bf16 v[46:49], v[158:161], v[210:213], v[46:49]
	v_mfma_f32_16x16x32_bf16 v[42:45], v[166:169], v[210:213], v[42:45]
	v_mfma_f32_16x16x32_bf16 v[30:33], v[158:161], v[218:221], v[30:33]
	v_mfma_f32_16x16x32_bf16 v[26:29], v[166:169], v[218:221], v[26:29]
	v_mfma_f32_16x16x32_bf16 v[14:17], v[158:161], v[242:245], v[14:17]
	v_mfma_f32_16x16x32_bf16 v[10:13], v[166:169], v[242:245], v[10:13]
	v_mfma_f32_16x16x32_bf16 v[54:57], v[170:173], v[198:201], v[54:57]
	v_mfma_f32_16x16x32_bf16 v[50:53], v[190:193], v[198:201], v[50:53]
	v_mfma_f32_16x16x32_bf16 v[38:41], v[170:173], v[206:209], v[38:41]
	v_mfma_f32_16x16x32_bf16 v[34:37], v[190:193], v[206:209], v[34:37]
	v_mfma_f32_16x16x32_bf16 v[22:25], v[170:173], v[214:217], v[22:25]
	v_mfma_f32_16x16x32_bf16 v[18:21], v[190:193], v[214:217], v[18:21]
	v_mfma_f32_16x16x32_bf16 v[6:9], v[170:173], v[238:241], v[6:9]
	v_mfma_f32_16x16x32_bf16 v[2:5], v[190:193], v[238:241], v[2:5]
	v_mfma_f32_16x16x32_bf16 v[54:57], v[174:177], v[202:205], v[54:57]
	v_mfma_f32_16x16x32_bf16 v[50:53], v[194:197], v[202:205], v[50:53]
	v_mfma_f32_16x16x32_bf16 v[38:41], v[174:177], v[210:213], v[38:41]
	v_mfma_f32_16x16x32_bf16 v[34:37], v[194:197], v[210:213], v[34:37]
	v_mfma_f32_16x16x32_bf16 v[22:25], v[174:177], v[218:221], v[22:25]
	v_mfma_f32_16x16x32_bf16 v[18:21], v[194:197], v[218:221], v[18:21]
	v_mfma_f32_16x16x32_bf16 v[6:9], v[174:177], v[242:245], v[6:9]
	v_mfma_f32_16x16x32_bf16 v[2:5], v[194:197], v[242:245], v[2:5]
	s_barrier
	s_add_u32 s34, s34, 0x100
	s_addc_u32 s35, s35, 0
	s_add_u32 s62, s62, 0x100
	s_addc_u32 s63, s63, 0
	s_cmp_ge_i32 s64, s51
	s_mov_b32 s40, s64
	s_cbranch_scc0 .LBB0_824
	v_readlane_b32 s64, v255, 40
	s_mov_b32 s68, 0xff61b1e6
	s_mov_b32 s74, 0x24600000
	s_mov_b32 s69, 0xcf800000

.LBB0_937:
	s_add_u32 s34, s30, 0x100
	s_addc_u32 s35, s31, 0
	s_add_i32 s61, 0, 0x10000
	s_cmp_eq_u32 s60, 20
	s_cselect_b32 s43, s27, s35
	s_cselect_b32 s42, s26, s34
	s_cselect_b32 s41, s29, s59
	s_cselect_b32 s40, s28, s58
	s_add_i32 s62, 0, 0x14000
	v_add_u32_e32 v156, s61, v150
	v_add_u32_e32 v172, s62, v150
	ds_read_b128 v[140:143], v156
	ds_read_b128 v[144:147], v156 offset:1024
	ds_read_b128 v[152:155], v156 offset:2048
	ds_read_b128 v[156:159], v156 offset:3072
	ds_read_b128 v[160:163], v172
	ds_read_b128 v[164:167], v172 offset:1024
	ds_read_b128 v[168:171], v172 offset:2048
	ds_read_b128 v[172:175], v172 offset:3072
	v_lshl_add_u64 v[218:219], s[30:31], 0, v[136:137]
	s_add_i32 m0, s44, 0xc000
	ds_read_b128 v[176:179], v151
	ds_read_b128 v[190:193], v151 offset:1024
	ds_read_b128 v[194:197], v151 offset:2048
	ds_read_b128 v[198:201], v151 offset:3072
	ds_read_b128 v[202:205], v151 offset:4096
	ds_read_b128 v[206:209], v151 offset:5120
	ds_read_b128 v[210:213], v151 offset:6144
	ds_read_b128 v[214:217], v151 offset:7168
	global_load_lds_dwordx4 v[218:219], off
	v_lshl_add_u64 v[218:219], s[30:31], 0, v[138:139]
	s_add_i32 m0, s44, 0xe000
	s_nop 0
	global_load_lds_dwordx4 v[218:219], off
	s_waitcnt vmcnt(8)
	s_waitcnt lgkmcnt(0)
	s_barrier
	s_waitcnt lgkmcnt(0)
	v_mfma_f32_16x16x32_bf16 v[126:129], v[140:143], v[176:179], v[126:129]
	v_mfma_f32_16x16x32_bf16 v[122:125], v[152:155], v[176:179], v[122:125]
	v_mfma_f32_16x16x32_bf16 v[110:113], v[140:143], v[194:197], v[110:113]
	v_mfma_f32_16x16x32_bf16 v[106:109], v[152:155], v[194:197], v[106:109]
	v_mfma_f32_16x16x32_bf16 v[94:97], v[140:143], v[202:205], v[94:97]
	v_mfma_f32_16x16x32_bf16 v[90:93], v[152:155], v[202:205], v[90:93]
	v_mfma_f32_16x16x32_bf16 v[78:81], v[140:143], v[210:213], v[78:81]
	v_mfma_f32_16x16x32_bf16 v[74:77], v[152:155], v[210:213], v[74:77]
	v_mfma_f32_16x16x32_bf16 v[126:129], v[144:147], v[190:193], v[126:129]
	v_mfma_f32_16x16x32_bf16 v[122:125], v[156:159], v[190:193], v[122:125]
	v_mfma_f32_16x16x32_bf16 v[110:113], v[144:147], v[198:201], v[110:113]
	v_mfma_f32_16x16x32_bf16 v[106:109], v[156:159], v[198:201], v[106:109]
	v_mfma_f32_16x16x32_bf16 v[94:97], v[144:147], v[206:209], v[94:97]
	v_mfma_f32_16x16x32_bf16 v[90:93], v[156:159], v[206:209], v[90:93]
	v_mfma_f32_16x16x32_bf16 v[78:81], v[144:147], v[214:217], v[78:81]
	v_mfma_f32_16x16x32_bf16 v[74:77], v[156:159], v[214:217], v[74:77]
	v_mfma_f32_16x16x32_bf16 v[118:121], v[160:163], v[176:179], v[118:121]
	v_mfma_f32_16x16x32_bf16 v[114:117], v[168:171], v[176:179], v[114:117]
	v_mfma_f32_16x16x32_bf16 v[102:105], v[160:163], v[194:197], v[102:105]
	v_mfma_f32_16x16x32_bf16 v[98:101], v[168:171], v[194:197], v[98:101]
	v_mfma_f32_16x16x32_bf16 v[86:89], v[160:163], v[202:205], v[86:89]
	v_mfma_f32_16x16x32_bf16 v[82:85], v[168:171], v[202:205], v[82:85]
	v_mfma_f32_16x16x32_bf16 v[70:73], v[160:163], v[210:213], v[70:73]
	v_mfma_f32_16x16x32_bf16 v[66:69], v[168:171], v[210:213], v[66:69]
	v_mfma_f32_16x16x32_bf16 v[118:121], v[164:167], v[190:193], v[118:121]
	v_mfma_f32_16x16x32_bf16 v[114:117], v[172:175], v[190:193], v[114:117]
	v_mfma_f32_16x16x32_bf16 v[102:105], v[164:167], v[198:201], v[102:105]
	v_mfma_f32_16x16x32_bf16 v[98:101], v[172:175], v[198:201], v[98:101]
	v_mfma_f32_16x16x32_bf16 v[86:89], v[164:167], v[206:209], v[86:89]
	v_mfma_f32_16x16x32_bf16 v[82:85], v[172:175], v[206:209], v[82:85]
	v_mfma_f32_16x16x32_bf16 v[70:73], v[164:167], v[214:217], v[70:73]
	v_mfma_f32_16x16x32_bf16 v[66:69], v[172:175], v[214:217], v[66:69]
	s_barrier
	s_add_i32 s30, s61, s21
	v_lshl_add_u64 v[218:219], s[40:41], 0, v[180:181]
	s_mov_b32 m0, s30
	ds_read_b128 v[176:179], v151 offset:16384
	ds_read_b128 v[190:193], v151 offset:17408
	ds_read_b128 v[194:197], v151 offset:18432
	ds_read_b128 v[198:201], v151 offset:19456
	ds_read_b128 v[202:205], v151 offset:20480
	ds_read_b128 v[206:209], v151 offset:21504
	ds_read_b128 v[210:213], v151 offset:22528
	ds_read_b128 v[214:217], v151 offset:23552
	global_load_lds_dwordx4 v[218:219], off
	s_add_i32 m0, s30, 0x2000
	s_add_u32 s30, s40, 0x60000
	v_lshl_add_u64 v[220:221], s[40:41], 0, v[134:135]
	s_addc_u32 s31, s41, 0
	s_add_i32 s61, s62, s21
	global_load_lds_dwordx4 v[220:221], off
	v_lshl_add_u64 v[222:223], s[30:31], 0, v[180:181]
	s_mov_b32 m0, s61
	v_lshl_add_u64 v[238:239], s[42:43], 0, v[132:133]
	global_load_lds_dwordx4 v[222:223], off
	v_lshl_add_u64 v[222:223], s[30:31], 0, v[134:135]
	s_add_i32 m0, s61, 0x2000
	s_nop 0
	global_load_lds_dwordx4 v[222:223], off
	v_lshl_add_u64 v[222:223], s[42:43], 0, v[130:131]
	s_mov_b32 m0, s44
	s_nop 0
	global_load_lds_dwordx4 v[222:223], off
	s_mov_b32 m0, s45
	s_nop 0
	global_load_lds_dwordx4 v[238:239], off
	s_waitcnt vmcnt(8)
	s_waitcnt lgkmcnt(0)
	s_barrier
	s_waitcnt lgkmcnt(0)
	v_mfma_f32_16x16x32_bf16 v[62:65], v[140:143], v[176:179], v[62:65]
	v_mfma_f32_16x16x32_bf16 v[58:61], v[152:155], v[176:179], v[58:61]
	v_mfma_f32_16x16x32_bf16 v[46:49], v[140:143], v[194:197], v[46:49]
	v_mfma_f32_16x16x32_bf16 v[42:45], v[152:155], v[194:197], v[42:45]
	v_mfma_f32_16x16x32_bf16 v[30:33], v[140:143], v[202:205], v[30:33]
	v_mfma_f32_16x16x32_bf16 v[26:29], v[152:155], v[202:205], v[26:29]
	v_mfma_f32_16x16x32_bf16 v[14:17], v[140:143], v[210:213], v[14:17]
	v_mfma_f32_16x16x32_bf16 v[10:13], v[152:155], v[210:213], v[10:13]
	v_mfma_f32_16x16x32_bf16 v[62:65], v[144:147], v[190:193], v[62:65]
	v_mfma_f32_16x16x32_bf16 v[58:61], v[156:159], v[190:193], v[58:61]
	v_mfma_f32_16x16x32_bf16 v[46:49], v[144:147], v[198:201], v[46:49]
	v_mfma_f32_16x16x32_bf16 v[42:45], v[156:159], v[198:201], v[42:45]
	v_mfma_f32_16x16x32_bf16 v[30:33], v[144:147], v[206:209], v[30:33]
	v_mfma_f32_16x16x32_bf16 v[26:29], v[156:159], v[206:209], v[26:29]
	v_mfma_f32_16x16x32_bf16 v[14:17], v[144:147], v[214:217], v[14:17]
	v_mfma_f32_16x16x32_bf16 v[10:13], v[156:159], v[214:217], v[10:13]
	v_mfma_f32_16x16x32_bf16 v[54:57], v[160:163], v[176:179], v[54:57]
	v_mfma_f32_16x16x32_bf16 v[50:53], v[168:171], v[176:179], v[50:53]
	v_mfma_f32_16x16x32_bf16 v[38:41], v[160:163], v[194:197], v[38:41]
	v_mfma_f32_16x16x32_bf16 v[34:37], v[168:171], v[194:197], v[34:37]
	v_mfma_f32_16x16x32_bf16 v[22:25], v[160:163], v[202:205], v[22:25]
	v_mfma_f32_16x16x32_bf16 v[18:21], v[168:171], v[202:205], v[18:21]
	v_mfma_f32_16x16x32_bf16 v[6:9], v[160:163], v[210:213], v[6:9]
	v_mfma_f32_16x16x32_bf16 v[2:5], v[168:171], v[210:213], v[2:5]
	v_mfma_f32_16x16x32_bf16 v[54:57], v[164:167], v[190:193], v[54:57]
	v_mfma_f32_16x16x32_bf16 v[50:53], v[172:175], v[190:193], v[50:53]
	v_mfma_f32_16x16x32_bf16 v[38:41], v[164:167], v[198:201], v[38:41]
	v_mfma_f32_16x16x32_bf16 v[34:37], v[172:175], v[198:201], v[34:37]
	v_mfma_f32_16x16x32_bf16 v[22:25], v[164:167], v[206:209], v[22:25]
	v_mfma_f32_16x16x32_bf16 v[18:21], v[172:175], v[206:209], v[18:21]
	v_mfma_f32_16x16x32_bf16 v[6:9], v[164:167], v[214:217], v[6:9]
	v_mfma_f32_16x16x32_bf16 v[2:5], v[172:175], v[214:217], v[2:5]
	s_barrier
	s_add_i32 s61, 0, 0x18000
	s_add_i32 s62, 0, 0x1c000
	v_add_u32_e32 v156, s61, v150
	v_add_u32_e32 v172, s62, v150
	ds_read_b128 v[140:143], v156
	ds_read_b128 v[144:147], v156 offset:1024
	ds_read_b128 v[152:155], v156 offset:2048
	ds_read_b128 v[156:159], v156 offset:3072
	ds_read_b128 v[160:163], v172
	ds_read_b128 v[164:167], v172 offset:1024
	ds_read_b128 v[168:171], v172 offset:2048
	ds_read_b128 v[172:175], v172 offset:3072
	s_add_u32 s30, s42, 0x60000
	s_addc_u32 s31, s43, 0
	s_mov_b32 m0, s46
	v_lshl_add_u64 v[240:241], s[30:31], 0, v[130:131]
	ds_read_b128 v[176:179], v151 offset:32768
	ds_read_b128 v[190:193], v151 offset:33792
	ds_read_b128 v[194:197], v151 offset:34816
	ds_read_b128 v[198:201], v151 offset:35840
	ds_read_b128 v[202:205], v151 offset:36864
	ds_read_b128 v[206:209], v151 offset:37888
	ds_read_b128 v[210:213], v151 offset:38912
	ds_read_b128 v[214:217], v151 offset:39936
	global_load_lds_dwordx4 v[240:241], off
	v_lshl_add_u64 v[240:241], s[30:31], 0, v[132:133]
	s_mov_b32 m0, s47
	s_nop 0
	global_load_lds_dwordx4 v[240:241], off
	s_waitcnt vmcnt(8)
	s_waitcnt lgkmcnt(0)
	s_barrier
	s_waitcnt lgkmcnt(0)
	v_mfma_f32_16x16x32_bf16 v[126:129], v[140:143], v[176:179], v[126:129]
	v_mfma_f32_16x16x32_bf16 v[122:125], v[152:155], v[176:179], v[122:125]
	v_mfma_f32_16x16x32_bf16 v[110:113], v[140:143], v[194:197], v[110:113]
	v_mfma_f32_16x16x32_bf16 v[106:109], v[152:155], v[194:197], v[106:109]
	v_mfma_f32_16x16x32_bf16 v[94:97], v[140:143], v[202:205], v[94:97]
	v_mfma_f32_16x16x32_bf16 v[90:93], v[152:155], v[202:205], v[90:93]
	v_mfma_f32_16x16x32_bf16 v[78:81], v[140:143], v[210:213], v[78:81]
	v_mfma_f32_16x16x32_bf16 v[74:77], v[152:155], v[210:213], v[74:77]
	v_mfma_f32_16x16x32_bf16 v[126:129], v[144:147], v[190:193], v[126:129]
	v_mfma_f32_16x16x32_bf16 v[122:125], v[156:159], v[190:193], v[122:125]
	v_mfma_f32_16x16x32_bf16 v[110:113], v[144:147], v[198:201], v[110:113]
	v_mfma_f32_16x16x32_bf16 v[106:109], v[156:159], v[198:201], v[106:109]
	v_mfma_f32_16x16x32_bf16 v[94:97], v[144:147], v[206:209], v[94:97]
	v_mfma_f32_16x16x32_bf16 v[90:93], v[156:159], v[206:209], v[90:93]
	v_mfma_f32_16x16x32_bf16 v[78:81], v[144:147], v[214:217], v[78:81]
	v_mfma_f32_16x16x32_bf16 v[74:77], v[156:159], v[214:217], v[74:77]
	v_mfma_f32_16x16x32_bf16 v[118:121], v[160:163], v[176:179], v[118:121]
	v_mfma_f32_16x16x32_bf16 v[114:117], v[168:171], v[176:179], v[114:117]
	v_mfma_f32_16x16x32_bf16 v[102:105], v[160:163], v[194:197], v[102:105]
	v_mfma_f32_16x16x32_bf16 v[98:101], v[168:171], v[194:197], v[98:101]
	v_mfma_f32_16x16x32_bf16 v[86:89], v[160:163], v[202:205], v[86:89]
	v_mfma_f32_16x16x32_bf16 v[82:85], v[168:171], v[202:205], v[82:85]
	v_mfma_f32_16x16x32_bf16 v[70:73], v[160:163], v[210:213], v[70:73]
	v_mfma_f32_16x16x32_bf16 v[66:69], v[168:171], v[210:213], v[66:69]
	v_mfma_f32_16x16x32_bf16 v[118:121], v[164:167], v[190:193], v[118:121]
	v_mfma_f32_16x16x32_bf16 v[114:117], v[172:175], v[190:193], v[114:117]
	v_mfma_f32_16x16x32_bf16 v[102:105], v[164:167], v[198:201], v[102:105]
	v_mfma_f32_16x16x32_bf16 v[98:101], v[172:175], v[198:201], v[98:101]
	v_mfma_f32_16x16x32_bf16 v[86:89], v[164:167], v[206:209], v[86:89]
	v_mfma_f32_16x16x32_bf16 v[82:85], v[172:175], v[206:209], v[82:85]
	v_mfma_f32_16x16x32_bf16 v[70:73], v[164:167], v[214:217], v[70:73]
	v_mfma_f32_16x16x32_bf16 v[66:69], v[172:175], v[214:217], v[66:69]
	s_barrier
	s_add_i32 s30, s61, s21
	v_lshl_add_u64 v[218:219], v[218:219], 0, s[16:17]
	s_mov_b32 m0, s30
	ds_read_b128 v[176:179], v151 offset:49152
	ds_read_b128 v[190:193], v151 offset:50176
	ds_read_b128 v[194:197], v151 offset:51200
	ds_read_b128 v[198:201], v151 offset:52224
	ds_read_b128 v[202:205], v151 offset:53248
	ds_read_b128 v[206:209], v151 offset:54272
	ds_read_b128 v[210:213], v151 offset:55296
	ds_read_b128 v[214:217], v151 offset:56320
	global_load_lds_dwordx4 v[218:219], off
	s_add_i32 m0, s30, 0x2000
	s_add_u32 s30, s40, 0x60080
	v_lshl_add_u64 v[218:219], v[220:221], 0, s[16:17]
	s_addc_u32 s31, s41, 0
	s_add_i32 s40, s62, s21
	global_load_lds_dwordx4 v[218:219], off
	v_lshl_add_u64 v[218:219], s[30:31], 0, v[180:181]
	s_mov_b32 m0, s40
	s_nop 0
	global_load_lds_dwordx4 v[218:219], off
	v_lshl_add_u64 v[218:219], s[30:31], 0, v[134:135]
	s_add_i32 m0, s40, 0x2000
	s_nop 0
	global_load_lds_dwordx4 v[218:219], off
	v_lshl_add_u64 v[218:219], v[222:223], 0, s[16:17]
	s_mov_b32 m0, s49
	s_nop 0
	global_load_lds_dwordx4 v[218:219], off
	v_lshl_add_u64 v[218:219], v[238:239], 0, s[16:17]
	s_mov_b32 m0, s50
	s_nop 0
	global_load_lds_dwordx4 v[218:219], off
	s_waitcnt vmcnt(8)
	s_waitcnt lgkmcnt(0)
	s_barrier
	s_waitcnt lgkmcnt(0)
	v_mfma_f32_16x16x32_bf16 v[62:65], v[140:143], v[176:179], v[62:65]
	v_mfma_f32_16x16x32_bf16 v[58:61], v[152:155], v[176:179], v[58:61]
	v_mfma_f32_16x16x32_bf16 v[46:49], v[140:143], v[194:197], v[46:49]
	v_mfma_f32_16x16x32_bf16 v[42:45], v[152:155], v[194:197], v[42:45]
	v_mfma_f32_16x16x32_bf16 v[30:33], v[140:143], v[202:205], v[30:33]
	v_mfma_f32_16x16x32_bf16 v[26:29], v[152:155], v[202:205], v[26:29]
	v_mfma_f32_16x16x32_bf16 v[14:17], v[140:143], v[210:213], v[14:17]
	v_mfma_f32_16x16x32_bf16 v[10:13], v[152:155], v[210:213], v[10:13]
	v_mfma_f32_16x16x32_bf16 v[62:65], v[144:147], v[190:193], v[62:65]
	v_mfma_f32_16x16x32_bf16 v[58:61], v[156:159], v[190:193], v[58:61]
	v_mfma_f32_16x16x32_bf16 v[46:49], v[144:147], v[198:201], v[46:49]
	v_mfma_f32_16x16x32_bf16 v[42:45], v[156:159], v[198:201], v[42:45]
	v_mfma_f32_16x16x32_bf16 v[30:33], v[144:147], v[206:209], v[30:33]
	v_mfma_f32_16x16x32_bf16 v[26:29], v[156:159], v[206:209], v[26:29]
	v_mfma_f32_16x16x32_bf16 v[14:17], v[144:147], v[214:217], v[14:17]
	v_mfma_f32_16x16x32_bf16 v[10:13], v[156:159], v[214:217], v[10:13]
	v_mfma_f32_16x16x32_bf16 v[54:57], v[160:163], v[176:179], v[54:57]
	v_mfma_f32_16x16x32_bf16 v[50:53], v[168:171], v[176:179], v[50:53]
	v_mfma_f32_16x16x32_bf16 v[38:41], v[160:163], v[194:197], v[38:41]
	v_mfma_f32_16x16x32_bf16 v[34:37], v[168:171], v[194:197], v[34:37]
	v_mfma_f32_16x16x32_bf16 v[22:25], v[160:163], v[202:205], v[22:25]
	v_mfma_f32_16x16x32_bf16 v[18:21], v[168:171], v[202:205], v[18:21]
	v_mfma_f32_16x16x32_bf16 v[6:9], v[160:163], v[210:213], v[6:9]
	v_mfma_f32_16x16x32_bf16 v[2:5], v[168:171], v[210:213], v[2:5]
	v_mfma_f32_16x16x32_bf16 v[54:57], v[164:167], v[190:193], v[54:57]
	v_mfma_f32_16x16x32_bf16 v[50:53], v[172:175], v[190:193], v[50:53]
	v_mfma_f32_16x16x32_bf16 v[38:41], v[164:167], v[198:201], v[38:41]
	v_mfma_f32_16x16x32_bf16 v[34:37], v[172:175], v[198:201], v[34:37]
	v_mfma_f32_16x16x32_bf16 v[22:25], v[164:167], v[206:209], v[22:25]
	v_mfma_f32_16x16x32_bf16 v[18:21], v[172:175], v[206:209], v[18:21]
	v_mfma_f32_16x16x32_bf16 v[6:9], v[164:167], v[214:217], v[6:9]
	v_mfma_f32_16x16x32_bf16 v[2:5], v[172:175], v[214:217], v[2:5]
	s_barrier
	s_add_i32 s60, s60, 2
	s_add_u32 s58, s58, 0x100
	s_addc_u32 s59, s59, 0
	s_cmp_gt_u32 s60, 21
	s_mov_b64 s[30:31], s[34:35]
	s_cbranch_scc0 .LBB0_937
	s_and_b64 vcc, exec, s[24:25]
	s_cbranch_vccz .LBB0_940
	s_barrier

.LBB0_1018:
	s_add_u32 s40, s38, 0xfff80080
	s_addc_u32 s41, s39, -1
	s_add_i32 s51, 0, 0x10000
	s_cmp_eq_u32 s49, 28
	s_cselect_b32 s43, s11, s41
	s_cselect_b32 s42, s37, s40
	s_cselect_b32 s41, s44, s47
	s_cselect_b32 s40, s45, s46
	s_add_i32 s83, 0, 0x14000
	v_add_u32_e32 v154, s51, v159
	v_add_u32_e32 v161, s83, v159
	ds_read_b128 v[142:145], v154
	ds_read_b128 v[146:149], v154 offset:1024
	ds_read_b128 v[150:153], v154 offset:2048
	ds_read_b128 v[154:157], v154 offset:3072
	ds_read_b128 v[162:165], v161
	ds_read_b128 v[166:169], v161 offset:1024
	ds_read_b128 v[170:173], v161 offset:2048
	ds_read_b128 v[174:177], v161 offset:3072
	v_lshl_add_u64 v[178:179], s[38:39], 0, v[138:139]
	s_add_i32 m0, s61, 0xc000
	ds_read_b128 v[190:193], v160
	ds_read_b128 v[194:197], v160 offset:1024
	ds_read_b128 v[198:201], v160 offset:2048
	ds_read_b128 v[202:205], v160 offset:3072
	ds_read_b128 v[206:209], v160 offset:4096
	ds_read_b128 v[210:213], v160 offset:5120
	ds_read_b128 v[214:217], v160 offset:6144
	ds_read_b128 v[218:221], v160 offset:7168
	global_load_lds_dwordx4 v[178:179], off
	v_lshl_add_u64 v[178:179], s[38:39], 0, v[140:141]
	s_add_i32 m0, s61, 0xe000
	s_nop 0
	global_load_lds_dwordx4 v[178:179], off
	s_waitcnt vmcnt(8)
	s_waitcnt lgkmcnt(0)
	s_barrier
	s_waitcnt lgkmcnt(0)
	v_mfma_f32_16x16x32_bf16 v[126:129], v[142:145], v[190:193], v[126:129]
	v_mfma_f32_16x16x32_bf16 v[122:125], v[150:153], v[190:193], v[122:125]
	v_mfma_f32_16x16x32_bf16 v[110:113], v[142:145], v[198:201], v[110:113]
	v_mfma_f32_16x16x32_bf16 v[106:109], v[150:153], v[198:201], v[106:109]
	v_mfma_f32_16x16x32_bf16 v[94:97], v[142:145], v[206:209], v[94:97]
	v_mfma_f32_16x16x32_bf16 v[90:93], v[150:153], v[206:209], v[90:93]
	v_mfma_f32_16x16x32_bf16 v[78:81], v[142:145], v[214:217], v[78:81]
	v_mfma_f32_16x16x32_bf16 v[74:77], v[150:153], v[214:217], v[74:77]
	v_mfma_f32_16x16x32_bf16 v[126:129], v[146:149], v[194:197], v[126:129]
	v_mfma_f32_16x16x32_bf16 v[122:125], v[154:157], v[194:197], v[122:125]
	v_mfma_f32_16x16x32_bf16 v[110:113], v[146:149], v[202:205], v[110:113]
	v_mfma_f32_16x16x32_bf16 v[106:109], v[154:157], v[202:205], v[106:109]
	v_mfma_f32_16x16x32_bf16 v[94:97], v[146:149], v[210:213], v[94:97]
	v_mfma_f32_16x16x32_bf16 v[90:93], v[154:157], v[210:213], v[90:93]
	v_mfma_f32_16x16x32_bf16 v[78:81], v[146:149], v[218:221], v[78:81]
	v_mfma_f32_16x16x32_bf16 v[74:77], v[154:157], v[218:221], v[74:77]
	v_mfma_f32_16x16x32_bf16 v[118:121], v[162:165], v[190:193], v[118:121]
	v_mfma_f32_16x16x32_bf16 v[114:117], v[170:173], v[190:193], v[114:117]
	v_mfma_f32_16x16x32_bf16 v[102:105], v[162:165], v[198:201], v[102:105]
	v_mfma_f32_16x16x32_bf16 v[98:101], v[170:173], v[198:201], v[98:101]
	v_mfma_f32_16x16x32_bf16 v[86:89], v[162:165], v[206:209], v[86:89]
	v_mfma_f32_16x16x32_bf16 v[82:85], v[170:173], v[206:209], v[82:85]
	v_mfma_f32_16x16x32_bf16 v[70:73], v[162:165], v[214:217], v[70:73]
	v_mfma_f32_16x16x32_bf16 v[66:69], v[170:173], v[214:217], v[66:69]
	v_mfma_f32_16x16x32_bf16 v[118:121], v[166:169], v[194:197], v[118:121]
	v_mfma_f32_16x16x32_bf16 v[114:117], v[174:177], v[194:197], v[114:117]
	v_mfma_f32_16x16x32_bf16 v[102:105], v[166:169], v[202:205], v[102:105]
	v_mfma_f32_16x16x32_bf16 v[98:101], v[174:177], v[202:205], v[98:101]
	v_mfma_f32_16x16x32_bf16 v[86:89], v[166:169], v[210:213], v[86:89]
	v_mfma_f32_16x16x32_bf16 v[82:85], v[174:177], v[210:213], v[82:85]
	v_mfma_f32_16x16x32_bf16 v[70:73], v[166:169], v[218:221], v[70:73]
	v_mfma_f32_16x16x32_bf16 v[66:69], v[174:177], v[218:221], v[66:69]
	s_barrier
	s_add_i32 s51, s51, s60
	v_lshl_add_u64 v[178:179], s[40:41], 0, v[180:181]
	s_mov_b32 m0, s51
	ds_read_b128 v[190:193], v160 offset:16384
	ds_read_b128 v[194:197], v160 offset:17408
	ds_read_b128 v[198:201], v160 offset:18432
	ds_read_b128 v[202:205], v160 offset:19456
	ds_read_b128 v[206:209], v160 offset:20480
	ds_read_b128 v[210:213], v160 offset:21504
	ds_read_b128 v[214:217], v160 offset:22528
	ds_read_b128 v[218:221], v160 offset:23552
	global_load_lds_dwordx4 v[178:179], off
	s_add_i32 m0, s51, 0x2000
	s_add_u32 vcc_lo, s40, 0x80000
	v_lshl_add_u64 v[222:223], s[40:41], 0, v[136:137]
	s_addc_u32 vcc_hi, s41, 0
	s_add_i32 s51, s83, s60
	global_load_lds_dwordx4 v[222:223], off
	v_lshl_add_u64 v[238:239], vcc, 0, v[180:181]
	s_mov_b32 m0, s51
	v_lshl_add_u64 v[240:241], s[42:43], 0, v[134:135]
	global_load_lds_dwordx4 v[238:239], off
	v_lshl_add_u64 v[238:239], vcc, 0, v[136:137]
	s_add_i32 m0, s51, 0x2000
	s_nop 0
	global_load_lds_dwordx4 v[238:239], off
	v_lshl_add_u64 v[238:239], s[42:43], 0, v[132:133]
	s_mov_b32 m0, s61
	s_nop 0
	global_load_lds_dwordx4 v[238:239], off
	s_mov_b32 m0, s62
	s_nop 0
	global_load_lds_dwordx4 v[240:241], off
	s_waitcnt vmcnt(8)
	s_waitcnt lgkmcnt(0)
	s_barrier
	s_waitcnt lgkmcnt(0)
	v_mfma_f32_16x16x32_bf16 v[62:65], v[142:145], v[190:193], v[62:65]
	v_mfma_f32_16x16x32_bf16 v[58:61], v[150:153], v[190:193], v[58:61]
	v_mfma_f32_16x16x32_bf16 v[46:49], v[142:145], v[198:201], v[46:49]
	v_mfma_f32_16x16x32_bf16 v[42:45], v[150:153], v[198:201], v[42:45]
	v_mfma_f32_16x16x32_bf16 v[30:33], v[142:145], v[206:209], v[30:33]
	v_mfma_f32_16x16x32_bf16 v[26:29], v[150:153], v[206:209], v[26:29]
	v_mfma_f32_16x16x32_bf16 v[14:17], v[142:145], v[214:217], v[14:17]
	v_mfma_f32_16x16x32_bf16 v[10:13], v[150:153], v[214:217], v[10:13]
	v_mfma_f32_16x16x32_bf16 v[62:65], v[146:149], v[194:197], v[62:65]
	v_mfma_f32_16x16x32_bf16 v[58:61], v[154:157], v[194:197], v[58:61]
	v_mfma_f32_16x16x32_bf16 v[46:49], v[146:149], v[202:205], v[46:49]
	v_mfma_f32_16x16x32_bf16 v[42:45], v[154:157], v[202:205], v[42:45]
	v_mfma_f32_16x16x32_bf16 v[30:33], v[146:149], v[210:213], v[30:33]
	v_mfma_f32_16x16x32_bf16 v[26:29], v[154:157], v[210:213], v[26:29]
	v_mfma_f32_16x16x32_bf16 v[14:17], v[146:149], v[218:221], v[14:17]
	v_mfma_f32_16x16x32_bf16 v[10:13], v[154:157], v[218:221], v[10:13]
	v_mfma_f32_16x16x32_bf16 v[54:57], v[162:165], v[190:193], v[54:57]
	v_mfma_f32_16x16x32_bf16 v[50:53], v[170:173], v[190:193], v[50:53]
	v_mfma_f32_16x16x32_bf16 v[38:41], v[162:165], v[198:201], v[38:41]
	v_mfma_f32_16x16x32_bf16 v[34:37], v[170:173], v[198:201], v[34:37]
	v_mfma_f32_16x16x32_bf16 v[22:25], v[162:165], v[206:209], v[22:25]
	v_mfma_f32_16x16x32_bf16 v[18:21], v[170:173], v[206:209], v[18:21]
	v_mfma_f32_16x16x32_bf16 v[6:9], v[162:165], v[214:217], v[6:9]
	v_mfma_f32_16x16x32_bf16 v[2:5], v[170:173], v[214:217], v[2:5]
	v_mfma_f32_16x16x32_bf16 v[54:57], v[166:169], v[194:197], v[54:57]
	v_mfma_f32_16x16x32_bf16 v[50:53], v[174:177], v[194:197], v[50:53]
	v_mfma_f32_16x16x32_bf16 v[38:41], v[166:169], v[202:205], v[38:41]
	v_mfma_f32_16x16x32_bf16 v[34:37], v[174:177], v[202:205], v[34:37]
	v_mfma_f32_16x16x32_bf16 v[22:25], v[166:169], v[210:213], v[22:25]
	v_mfma_f32_16x16x32_bf16 v[18:21], v[174:177], v[210:213], v[18:21]
	v_mfma_f32_16x16x32_bf16 v[6:9], v[166:169], v[218:221], v[6:9]
	v_mfma_f32_16x16x32_bf16 v[2:5], v[174:177], v[218:221], v[2:5]
	s_barrier
	s_add_i32 s51, 0, 0x18000
	s_add_i32 s83, 0, 0x1c000
	v_add_u32_e32 v154, s51, v159
	v_add_u32_e32 v161, s83, v159
	ds_read_b128 v[142:145], v154
	ds_read_b128 v[146:149], v154 offset:1024
	ds_read_b128 v[150:153], v154 offset:2048
	ds_read_b128 v[154:157], v154 offset:3072
	ds_read_b128 v[162:165], v161
	ds_read_b128 v[166:169], v161 offset:1024
	ds_read_b128 v[170:173], v161 offset:2048
	ds_read_b128 v[174:177], v161 offset:3072
	s_add_u32 s42, s42, 0x80000
	s_addc_u32 s43, s43, 0
	s_mov_b32 m0, s63
	v_lshl_add_u64 v[242:243], s[42:43], 0, v[132:133]
	ds_read_b128 v[190:193], v160 offset:32768
	ds_read_b128 v[194:197], v160 offset:33792
	ds_read_b128 v[198:201], v160 offset:34816
	ds_read_b128 v[202:205], v160 offset:35840
	ds_read_b128 v[206:209], v160 offset:36864
	ds_read_b128 v[210:213], v160 offset:37888
	ds_read_b128 v[214:217], v160 offset:38912
	ds_read_b128 v[218:221], v160 offset:39936
	global_load_lds_dwordx4 v[242:243], off
	v_lshl_add_u64 v[242:243], s[42:43], 0, v[134:135]
	s_mov_b32 m0, s64
	s_nop 0
	global_load_lds_dwordx4 v[242:243], off
	s_waitcnt vmcnt(8)
	s_waitcnt lgkmcnt(0)
	s_barrier
	s_waitcnt lgkmcnt(0)
	v_mfma_f32_16x16x32_bf16 v[126:129], v[142:145], v[190:193], v[126:129]
	v_mfma_f32_16x16x32_bf16 v[122:125], v[150:153], v[190:193], v[122:125]
	v_mfma_f32_16x16x32_bf16 v[110:113], v[142:145], v[198:201], v[110:113]
	v_mfma_f32_16x16x32_bf16 v[106:109], v[150:153], v[198:201], v[106:109]
	v_mfma_f32_16x16x32_bf16 v[94:97], v[142:145], v[206:209], v[94:97]
	v_mfma_f32_16x16x32_bf16 v[90:93], v[150:153], v[206:209], v[90:93]
	v_mfma_f32_16x16x32_bf16 v[78:81], v[142:145], v[214:217], v[78:81]
	v_mfma_f32_16x16x32_bf16 v[74:77], v[150:153], v[214:217], v[74:77]
	v_mfma_f32_16x16x32_bf16 v[126:129], v[146:149], v[194:197], v[126:129]
	v_mfma_f32_16x16x32_bf16 v[122:125], v[154:157], v[194:197], v[122:125]
	v_mfma_f32_16x16x32_bf16 v[110:113], v[146:149], v[202:205], v[110:113]
	v_mfma_f32_16x16x32_bf16 v[106:109], v[154:157], v[202:205], v[106:109]
	v_mfma_f32_16x16x32_bf16 v[94:97], v[146:149], v[210:213], v[94:97]
	v_mfma_f32_16x16x32_bf16 v[90:93], v[154:157], v[210:213], v[90:93]
	v_mfma_f32_16x16x32_bf16 v[78:81], v[146:149], v[218:221], v[78:81]
	v_mfma_f32_16x16x32_bf16 v[74:77], v[154:157], v[218:221], v[74:77]
	v_mfma_f32_16x16x32_bf16 v[118:121], v[162:165], v[190:193], v[118:121]
	v_mfma_f32_16x16x32_bf16 v[114:117], v[170:173], v[190:193], v[114:117]
	v_mfma_f32_16x16x32_bf16 v[102:105], v[162:165], v[198:201], v[102:105]
	v_mfma_f32_16x16x32_bf16 v[98:101], v[170:173], v[198:201], v[98:101]
	v_mfma_f32_16x16x32_bf16 v[86:89], v[162:165], v[206:209], v[86:89]
	v_mfma_f32_16x16x32_bf16 v[82:85], v[170:173], v[206:209], v[82:85]
	v_mfma_f32_16x16x32_bf16 v[70:73], v[162:165], v[214:217], v[70:73]
	v_mfma_f32_16x16x32_bf16 v[66:69], v[170:173], v[214:217], v[66:69]
	v_mfma_f32_16x16x32_bf16 v[118:121], v[166:169], v[194:197], v[118:121]
	v_mfma_f32_16x16x32_bf16 v[114:117], v[174:177], v[194:197], v[114:117]
	v_mfma_f32_16x16x32_bf16 v[102:105], v[166:169], v[202:205], v[102:105]
	v_mfma_f32_16x16x32_bf16 v[98:101], v[174:177], v[202:205], v[98:101]
	v_mfma_f32_16x16x32_bf16 v[86:89], v[166:169], v[210:213], v[86:89]
	v_mfma_f32_16x16x32_bf16 v[82:85], v[174:177], v[210:213], v[82:85]
	v_mfma_f32_16x16x32_bf16 v[70:73], v[166:169], v[218:221], v[70:73]
	v_mfma_f32_16x16x32_bf16 v[66:69], v[174:177], v[218:221], v[66:69]
	s_barrier
	s_add_i32 s42, s51, s60
	v_lshl_add_u64 v[178:179], v[178:179], 0, s[16:17]
	s_mov_b32 m0, s42
	ds_read_b128 v[190:193], v160 offset:49152
	ds_read_b128 v[194:197], v160 offset:50176
	ds_read_b128 v[198:201], v160 offset:51200
	ds_read_b128 v[202:205], v160 offset:52224
	ds_read_b128 v[206:209], v160 offset:53248
	ds_read_b128 v[210:213], v160 offset:54272
	ds_read_b128 v[214:217], v160 offset:55296
	ds_read_b128 v[218:221], v160 offset:56320
	global_load_lds_dwordx4 v[178:179], off
	s_add_i32 m0, s42, 0x2000
	s_add_u32 s40, s40, 0x80080
	v_lshl_add_u64 v[178:179], v[222:223], 0, s[16:17]
	s_addc_u32 s41, s41, 0
	s_add_i32 s42, s83, s60
	global_load_lds_dwordx4 v[178:179], off
	v_lshl_add_u64 v[178:179], s[40:41], 0, v[180:181]
	s_mov_b32 m0, s42
	s_nop 0
	global_load_lds_dwordx4 v[178:179], off
	v_lshl_add_u64 v[178:179], s[40:41], 0, v[136:137]
	s_add_i32 m0, s42, 0x2000
	s_nop 0
	global_load_lds_dwordx4 v[178:179], off
	v_lshl_add_u64 v[178:179], v[238:239], 0, s[16:17]
	s_mov_b32 m0, s74
	s_nop 0
	global_load_lds_dwordx4 v[178:179], off
	v_lshl_add_u64 v[178:179], v[240:241], 0, s[16:17]
	s_mov_b32 m0, s75
	s_nop 0
	global_load_lds_dwordx4 v[178:179], off
	s_waitcnt vmcnt(8)
	s_waitcnt lgkmcnt(0)
	s_barrier
	s_waitcnt lgkmcnt(0)
	v_mfma_f32_16x16x32_bf16 v[62:65], v[142:145], v[190:193], v[62:65]
	v_mfma_f32_16x16x32_bf16 v[58:61], v[150:153], v[190:193], v[58:61]
	v_mfma_f32_16x16x32_bf16 v[46:49], v[142:145], v[198:201], v[46:49]
	v_mfma_f32_16x16x32_bf16 v[42:45], v[150:153], v[198:201], v[42:45]
	v_mfma_f32_16x16x32_bf16 v[30:33], v[142:145], v[206:209], v[30:33]
	v_mfma_f32_16x16x32_bf16 v[26:29], v[150:153], v[206:209], v[26:29]
	v_mfma_f32_16x16x32_bf16 v[14:17], v[142:145], v[214:217], v[14:17]
	v_mfma_f32_16x16x32_bf16 v[10:13], v[150:153], v[214:217], v[10:13]
	v_mfma_f32_16x16x32_bf16 v[62:65], v[146:149], v[194:197], v[62:65]
	v_mfma_f32_16x16x32_bf16 v[58:61], v[154:157], v[194:197], v[58:61]
	v_mfma_f32_16x16x32_bf16 v[46:49], v[146:149], v[202:205], v[46:49]
	v_mfma_f32_16x16x32_bf16 v[42:45], v[154:157], v[202:205], v[42:45]
	v_mfma_f32_16x16x32_bf16 v[30:33], v[146:149], v[210:213], v[30:33]
	v_mfma_f32_16x16x32_bf16 v[26:29], v[154:157], v[210:213], v[26:29]
	v_mfma_f32_16x16x32_bf16 v[14:17], v[146:149], v[218:221], v[14:17]
	v_mfma_f32_16x16x32_bf16 v[10:13], v[154:157], v[218:221], v[10:13]
	v_mfma_f32_16x16x32_bf16 v[54:57], v[162:165], v[190:193], v[54:57]
	v_mfma_f32_16x16x32_bf16 v[50:53], v[170:173], v[190:193], v[50:53]
	v_mfma_f32_16x16x32_bf16 v[38:41], v[162:165], v[198:201], v[38:41]
	v_mfma_f32_16x16x32_bf16 v[34:37], v[170:173], v[198:201], v[34:37]
	v_mfma_f32_16x16x32_bf16 v[22:25], v[162:165], v[206:209], v[22:25]
	v_mfma_f32_16x16x32_bf16 v[18:21], v[170:173], v[206:209], v[18:21]
	v_mfma_f32_16x16x32_bf16 v[6:9], v[162:165], v[214:217], v[6:9]
	v_mfma_f32_16x16x32_bf16 v[2:5], v[170:173], v[214:217], v[2:5]
	v_mfma_f32_16x16x32_bf16 v[54:57], v[166:169], v[194:197], v[54:57]
	v_mfma_f32_16x16x32_bf16 v[50:53], v[174:177], v[194:197], v[50:53]
	v_mfma_f32_16x16x32_bf16 v[38:41], v[166:169], v[202:205], v[38:41]
	v_mfma_f32_16x16x32_bf16 v[34:37], v[174:177], v[202:205], v[34:37]
	v_mfma_f32_16x16x32_bf16 v[22:25], v[166:169], v[210:213], v[22:25]
	v_mfma_f32_16x16x32_bf16 v[18:21], v[174:177], v[210:213], v[18:21]
	v_mfma_f32_16x16x32_bf16 v[6:9], v[166:169], v[218:221], v[6:9]
	v_mfma_f32_16x16x32_bf16 v[2:5], v[174:177], v[218:221], v[2:5]
	s_barrier
	s_add_i32 s49, s49, 2
	s_add_u32 s38, s38, 0x100
	s_addc_u32 s39, s39, 0
	s_add_u32 s46, s46, 0x100
	s_addc_u32 s47, s47, 0
	s_cmp_gt_u32 s49, 29
	s_cbranch_scc0 .LBB0_1018
	s_and_b64 vcc, exec, s[34:35]
	s_cbranch_vccz .LBB0_1021
	s_barrier

.LBB0_1230:
	s_add_u32 s38, s36, 0xfff80080
	s_addc_u32 s39, s37, -1
	s_add_i32 s64, 0, 0x10000
	s_cmp_eq_u32 s63, 28
	s_cselect_b32 s41, s57, s39
	s_cselect_b32 s40, s58, s38
	v_add_u32_e32 v155, s64, v153
	s_cselect_b32 s39, s59, s62
	s_cselect_b32 s38, s60, s61
	s_add_i32 s74, 0, 0x14000
	ds_read_b128 v[140:143], v155
	ds_read_b128 v[144:147], v155 offset:1024
	ds_read_b128 v[148:151], v155 offset:2048
	ds_read_b128 v[156:159], v155 offset:3072
	v_add_u32_e32 v155, s74, v153
	ds_read_b128 v[160:163], v155
	ds_read_b128 v[164:167], v155 offset:1024
	ds_read_b128 v[168:171], v155 offset:2048
	ds_read_b128 v[172:175], v155 offset:3072
	v_lshl_add_u64 v[218:219], s[36:37], 0, v[136:137]
	s_add_i32 m0, s11, 0xc000
	ds_read_b128 v[176:179], v154
	ds_read_b128 v[190:193], v154 offset:1024
	ds_read_b128 v[194:197], v154 offset:2048
	ds_read_b128 v[198:201], v154 offset:3072
	ds_read_b128 v[202:205], v154 offset:4096
	ds_read_b128 v[206:209], v154 offset:5120
	ds_read_b128 v[210:213], v154 offset:6144
	ds_read_b128 v[214:217], v154 offset:7168
	global_load_lds_dwordx4 v[218:219], off
	v_lshl_add_u64 v[218:219], s[36:37], 0, v[138:139]
	s_add_i32 m0, s11, 0xe000
	s_nop 0
	global_load_lds_dwordx4 v[218:219], off
	s_waitcnt vmcnt(8)
	s_waitcnt lgkmcnt(0)
	s_barrier
	s_waitcnt lgkmcnt(0)
	v_mfma_f32_16x16x32_bf16 v[126:129], v[140:143], v[176:179], v[126:129]
	v_mfma_f32_16x16x32_bf16 v[122:125], v[148:151], v[176:179], v[122:125]
	v_mfma_f32_16x16x32_bf16 v[110:113], v[140:143], v[194:197], v[110:113]
	v_mfma_f32_16x16x32_bf16 v[106:109], v[148:151], v[194:197], v[106:109]
	v_mfma_f32_16x16x32_bf16 v[94:97], v[140:143], v[202:205], v[94:97]
	v_mfma_f32_16x16x32_bf16 v[90:93], v[148:151], v[202:205], v[90:93]
	v_mfma_f32_16x16x32_bf16 v[78:81], v[140:143], v[210:213], v[78:81]
	v_mfma_f32_16x16x32_bf16 v[74:77], v[148:151], v[210:213], v[74:77]
	v_mfma_f32_16x16x32_bf16 v[126:129], v[144:147], v[190:193], v[126:129]
	v_mfma_f32_16x16x32_bf16 v[122:125], v[156:159], v[190:193], v[122:125]
	v_mfma_f32_16x16x32_bf16 v[110:113], v[144:147], v[198:201], v[110:113]
	v_mfma_f32_16x16x32_bf16 v[106:109], v[156:159], v[198:201], v[106:109]
	v_mfma_f32_16x16x32_bf16 v[94:97], v[144:147], v[206:209], v[94:97]
	v_mfma_f32_16x16x32_bf16 v[90:93], v[156:159], v[206:209], v[90:93]
	v_mfma_f32_16x16x32_bf16 v[78:81], v[144:147], v[214:217], v[78:81]
	v_mfma_f32_16x16x32_bf16 v[74:77], v[156:159], v[214:217], v[74:77]
	v_mfma_f32_16x16x32_bf16 v[118:121], v[160:163], v[176:179], v[118:121]
	v_mfma_f32_16x16x32_bf16 v[114:117], v[168:171], v[176:179], v[114:117]
	v_mfma_f32_16x16x32_bf16 v[102:105], v[160:163], v[194:197], v[102:105]
	v_mfma_f32_16x16x32_bf16 v[98:101], v[168:171], v[194:197], v[98:101]
	v_mfma_f32_16x16x32_bf16 v[86:89], v[160:163], v[202:205], v[86:89]
	v_mfma_f32_16x16x32_bf16 v[82:85], v[168:171], v[202:205], v[82:85]
	v_mfma_f32_16x16x32_bf16 v[70:73], v[160:163], v[210:213], v[70:73]
	v_mfma_f32_16x16x32_bf16 v[66:69], v[168:171], v[210:213], v[66:69]
	v_mfma_f32_16x16x32_bf16 v[118:121], v[164:167], v[190:193], v[118:121]
	v_mfma_f32_16x16x32_bf16 v[114:117], v[172:175], v[190:193], v[114:117]
	v_mfma_f32_16x16x32_bf16 v[102:105], v[164:167], v[198:201], v[102:105]
	v_mfma_f32_16x16x32_bf16 v[98:101], v[172:175], v[198:201], v[98:101]
	v_mfma_f32_16x16x32_bf16 v[86:89], v[164:167], v[206:209], v[86:89]
	v_mfma_f32_16x16x32_bf16 v[82:85], v[172:175], v[206:209], v[82:85]
	v_mfma_f32_16x16x32_bf16 v[70:73], v[164:167], v[214:217], v[70:73]
	v_mfma_f32_16x16x32_bf16 v[66:69], v[172:175], v[214:217], v[66:69]
	s_barrier
	s_add_i32 s64, s64, s43
	v_lshl_add_u64 v[218:219], s[38:39], 0, v[134:135]
	s_mov_b32 m0, s64
	ds_read_b128 v[176:179], v154 offset:16384
	ds_read_b128 v[190:193], v154 offset:17408
	ds_read_b128 v[194:197], v154 offset:18432
	ds_read_b128 v[198:201], v154 offset:19456
	ds_read_b128 v[202:205], v154 offset:20480
	ds_read_b128 v[206:209], v154 offset:21504
	ds_read_b128 v[210:213], v154 offset:22528
	ds_read_b128 v[214:217], v154 offset:23552
	global_load_lds_dwordx4 v[218:219], off
	s_add_i32 m0, s64, 0x2000
	s_add_u32 s70, s38, 0x80000
	v_lshl_add_u64 v[220:221], s[38:39], 0, v[132:133]
	s_addc_u32 s71, s39, 0
	s_add_i32 s64, s74, s43
	global_load_lds_dwordx4 v[220:221], off
	v_lshl_add_u64 v[222:223], s[70:71], 0, v[134:135]
	s_mov_b32 m0, s64
	v_lshl_add_u64 v[238:239], s[40:41], 0, v[132:133]
	global_load_lds_dwordx4 v[222:223], off
	v_lshl_add_u64 v[222:223], s[70:71], 0, v[132:133]
	s_add_i32 m0, s64, 0x2000
	s_nop 0
	global_load_lds_dwordx4 v[222:223], off
	v_lshl_add_u64 v[222:223], s[40:41], 0, v[134:135]
	s_mov_b32 m0, s11
	s_nop 0
	global_load_lds_dwordx4 v[222:223], off
	s_mov_b32 m0, s45
	s_nop 0
	global_load_lds_dwordx4 v[238:239], off
	s_waitcnt vmcnt(8)
	s_waitcnt lgkmcnt(0)
	s_barrier
	s_waitcnt lgkmcnt(0)
	v_mfma_f32_16x16x32_bf16 v[62:65], v[140:143], v[176:179], v[62:65]
	v_mfma_f32_16x16x32_bf16 v[58:61], v[148:151], v[176:179], v[58:61]
	v_mfma_f32_16x16x32_bf16 v[46:49], v[140:143], v[194:197], v[46:49]
	v_mfma_f32_16x16x32_bf16 v[42:45], v[148:151], v[194:197], v[42:45]
	v_mfma_f32_16x16x32_bf16 v[30:33], v[140:143], v[202:205], v[30:33]
	v_mfma_f32_16x16x32_bf16 v[26:29], v[148:151], v[202:205], v[26:29]
	v_mfma_f32_16x16x32_bf16 v[14:17], v[140:143], v[210:213], v[14:17]
	v_mfma_f32_16x16x32_bf16 v[10:13], v[148:151], v[210:213], v[10:13]
	v_mfma_f32_16x16x32_bf16 v[62:65], v[144:147], v[190:193], v[62:65]
	v_mfma_f32_16x16x32_bf16 v[58:61], v[156:159], v[190:193], v[58:61]
	v_mfma_f32_16x16x32_bf16 v[46:49], v[144:147], v[198:201], v[46:49]
	v_mfma_f32_16x16x32_bf16 v[42:45], v[156:159], v[198:201], v[42:45]
	v_mfma_f32_16x16x32_bf16 v[30:33], v[144:147], v[206:209], v[30:33]
	v_mfma_f32_16x16x32_bf16 v[26:29], v[156:159], v[206:209], v[26:29]
	v_mfma_f32_16x16x32_bf16 v[14:17], v[144:147], v[214:217], v[14:17]
	v_mfma_f32_16x16x32_bf16 v[10:13], v[156:159], v[214:217], v[10:13]
	v_mfma_f32_16x16x32_bf16 v[54:57], v[160:163], v[176:179], v[54:57]
	v_mfma_f32_16x16x32_bf16 v[50:53], v[168:171], v[176:179], v[50:53]
	v_mfma_f32_16x16x32_bf16 v[38:41], v[160:163], v[194:197], v[38:41]
	v_mfma_f32_16x16x32_bf16 v[34:37], v[168:171], v[194:197], v[34:37]
	v_mfma_f32_16x16x32_bf16 v[22:25], v[160:163], v[202:205], v[22:25]
	v_mfma_f32_16x16x32_bf16 v[18:21], v[168:171], v[202:205], v[18:21]
	v_mfma_f32_16x16x32_bf16 v[6:9], v[160:163], v[210:213], v[6:9]
	v_mfma_f32_16x16x32_bf16 v[2:5], v[168:171], v[210:213], v[2:5]
	v_mfma_f32_16x16x32_bf16 v[54:57], v[164:167], v[190:193], v[54:57]
	v_mfma_f32_16x16x32_bf16 v[50:53], v[172:175], v[190:193], v[50:53]
	v_mfma_f32_16x16x32_bf16 v[38:41], v[164:167], v[198:201], v[38:41]
	v_mfma_f32_16x16x32_bf16 v[34:37], v[172:175], v[198:201], v[34:37]
	v_mfma_f32_16x16x32_bf16 v[22:25], v[164:167], v[206:209], v[22:25]
	v_mfma_f32_16x16x32_bf16 v[18:21], v[172:175], v[206:209], v[18:21]
	v_mfma_f32_16x16x32_bf16 v[6:9], v[164:167], v[214:217], v[6:9]
	v_mfma_f32_16x16x32_bf16 v[2:5], v[172:175], v[214:217], v[2:5]
	s_barrier
	s_add_i32 s64, 0, 0x18000
	v_add_u32_e32 v155, s64, v153
	s_add_i32 s70, 0, 0x1c000
	ds_read_b128 v[140:143], v155
	ds_read_b128 v[144:147], v155 offset:1024
	ds_read_b128 v[148:151], v155 offset:2048
	ds_read_b128 v[156:159], v155 offset:3072
	v_add_u32_e32 v155, s70, v153
	ds_read_b128 v[160:163], v155
	ds_read_b128 v[164:167], v155 offset:1024
	ds_read_b128 v[168:171], v155 offset:2048
	ds_read_b128 v[172:175], v155 offset:3072
	s_add_u32 s40, s40, 0x80000
	s_addc_u32 s41, s41, 0
	s_mov_b32 m0, s46
	v_lshl_add_u64 v[240:241], s[40:41], 0, v[134:135]
	ds_read_b128 v[176:179], v154 offset:32768
	ds_read_b128 v[190:193], v154 offset:33792
	ds_read_b128 v[194:197], v154 offset:34816
	ds_read_b128 v[198:201], v154 offset:35840
	ds_read_b128 v[202:205], v154 offset:36864
	ds_read_b128 v[206:209], v154 offset:37888
	ds_read_b128 v[210:213], v154 offset:38912
	ds_read_b128 v[214:217], v154 offset:39936
	global_load_lds_dwordx4 v[240:241], off
	v_lshl_add_u64 v[240:241], s[40:41], 0, v[132:133]
	s_mov_b32 m0, s47
	s_nop 0
	global_load_lds_dwordx4 v[240:241], off
	s_waitcnt vmcnt(8)
	s_waitcnt lgkmcnt(0)
	s_barrier
	s_waitcnt lgkmcnt(0)
	v_mfma_f32_16x16x32_bf16 v[126:129], v[140:143], v[176:179], v[126:129]
	v_mfma_f32_16x16x32_bf16 v[122:125], v[148:151], v[176:179], v[122:125]
	v_mfma_f32_16x16x32_bf16 v[110:113], v[140:143], v[194:197], v[110:113]
	v_mfma_f32_16x16x32_bf16 v[106:109], v[148:151], v[194:197], v[106:109]
	v_mfma_f32_16x16x32_bf16 v[94:97], v[140:143], v[202:205], v[94:97]
	v_mfma_f32_16x16x32_bf16 v[90:93], v[148:151], v[202:205], v[90:93]
	v_mfma_f32_16x16x32_bf16 v[78:81], v[140:143], v[210:213], v[78:81]
	v_mfma_f32_16x16x32_bf16 v[74:77], v[148:151], v[210:213], v[74:77]
	v_mfma_f32_16x16x32_bf16 v[126:129], v[144:147], v[190:193], v[126:129]
	v_mfma_f32_16x16x32_bf16 v[122:125], v[156:159], v[190:193], v[122:125]
	v_mfma_f32_16x16x32_bf16 v[110:113], v[144:147], v[198:201], v[110:113]
	v_mfma_f32_16x16x32_bf16 v[106:109], v[156:159], v[198:201], v[106:109]
	v_mfma_f32_16x16x32_bf16 v[94:97], v[144:147], v[206:209], v[94:97]
	v_mfma_f32_16x16x32_bf16 v[90:93], v[156:159], v[206:209], v[90:93]
	v_mfma_f32_16x16x32_bf16 v[78:81], v[144:147], v[214:217], v[78:81]
	v_mfma_f32_16x16x32_bf16 v[74:77], v[156:159], v[214:217], v[74:77]
	v_mfma_f32_16x16x32_bf16 v[118:121], v[160:163], v[176:179], v[118:121]
	v_mfma_f32_16x16x32_bf16 v[114:117], v[168:171], v[176:179], v[114:117]
	v_mfma_f32_16x16x32_bf16 v[102:105], v[160:163], v[194:197], v[102:105]
	v_mfma_f32_16x16x32_bf16 v[98:101], v[168:171], v[194:197], v[98:101]
	v_mfma_f32_16x16x32_bf16 v[86:89], v[160:163], v[202:205], v[86:89]
	v_mfma_f32_16x16x32_bf16 v[82:85], v[168:171], v[202:205], v[82:85]
	v_mfma_f32_16x16x32_bf16 v[70:73], v[160:163], v[210:213], v[70:73]
	v_mfma_f32_16x16x32_bf16 v[66:69], v[168:171], v[210:213], v[66:69]
	v_mfma_f32_16x16x32_bf16 v[118:121], v[164:167], v[190:193], v[118:121]
	v_mfma_f32_16x16x32_bf16 v[114:117], v[172:175], v[190:193], v[114:117]
	v_mfma_f32_16x16x32_bf16 v[102:105], v[164:167], v[198:201], v[102:105]
	v_mfma_f32_16x16x32_bf16 v[98:101], v[172:175], v[198:201], v[98:101]
	v_mfma_f32_16x16x32_bf16 v[86:89], v[164:167], v[206:209], v[86:89]
	v_mfma_f32_16x16x32_bf16 v[82:85], v[172:175], v[206:209], v[82:85]
	v_mfma_f32_16x16x32_bf16 v[70:73], v[164:167], v[214:217], v[70:73]
	v_mfma_f32_16x16x32_bf16 v[66:69], v[172:175], v[214:217], v[66:69]
	s_barrier
	s_add_i32 s40, s64, s43
	v_lshl_add_u64 v[218:219], v[218:219], 0, s[16:17]
	s_mov_b32 m0, s40
	ds_read_b128 v[176:179], v154 offset:49152
	ds_read_b128 v[190:193], v154 offset:50176
	ds_read_b128 v[194:197], v154 offset:51200
	ds_read_b128 v[198:201], v154 offset:52224
	ds_read_b128 v[202:205], v154 offset:53248
	ds_read_b128 v[206:209], v154 offset:54272
	ds_read_b128 v[210:213], v154 offset:55296
	ds_read_b128 v[214:217], v154 offset:56320
	global_load_lds_dwordx4 v[218:219], off
	s_add_i32 m0, s40, 0x2000
	s_add_u32 s38, s38, 0x80080
	v_lshl_add_u64 v[218:219], v[220:221], 0, s[16:17]
	s_addc_u32 s39, s39, 0
	s_add_i32 s40, s70, s43
	global_load_lds_dwordx4 v[218:219], off
	v_lshl_add_u64 v[218:219], s[38:39], 0, v[134:135]
	s_mov_b32 m0, s40
	s_nop 0
	global_load_lds_dwordx4 v[218:219], off
	v_lshl_add_u64 v[218:219], s[38:39], 0, v[132:133]
	s_add_i32 m0, s40, 0x2000
	s_nop 0
	global_load_lds_dwordx4 v[218:219], off
	v_lshl_add_u64 v[218:219], v[222:223], 0, s[16:17]
	s_mov_b32 m0, s50
	s_nop 0
	global_load_lds_dwordx4 v[218:219], off
	v_lshl_add_u64 v[218:219], v[238:239], 0, s[16:17]
	s_mov_b32 m0, s51
	s_nop 0
	global_load_lds_dwordx4 v[218:219], off
	s_waitcnt vmcnt(8)
	s_waitcnt lgkmcnt(0)
	s_barrier
	s_waitcnt lgkmcnt(0)
	v_mfma_f32_16x16x32_bf16 v[62:65], v[140:143], v[176:179], v[62:65]
	v_mfma_f32_16x16x32_bf16 v[58:61], v[148:151], v[176:179], v[58:61]
	v_mfma_f32_16x16x32_bf16 v[46:49], v[140:143], v[194:197], v[46:49]
	v_mfma_f32_16x16x32_bf16 v[42:45], v[148:151], v[194:197], v[42:45]
	v_mfma_f32_16x16x32_bf16 v[30:33], v[140:143], v[202:205], v[30:33]
	v_mfma_f32_16x16x32_bf16 v[26:29], v[148:151], v[202:205], v[26:29]
	v_mfma_f32_16x16x32_bf16 v[14:17], v[140:143], v[210:213], v[14:17]
	v_mfma_f32_16x16x32_bf16 v[10:13], v[148:151], v[210:213], v[10:13]
	v_mfma_f32_16x16x32_bf16 v[62:65], v[144:147], v[190:193], v[62:65]
	v_mfma_f32_16x16x32_bf16 v[58:61], v[156:159], v[190:193], v[58:61]
	v_mfma_f32_16x16x32_bf16 v[46:49], v[144:147], v[198:201], v[46:49]
	v_mfma_f32_16x16x32_bf16 v[42:45], v[156:159], v[198:201], v[42:45]
	v_mfma_f32_16x16x32_bf16 v[30:33], v[144:147], v[206:209], v[30:33]
	v_mfma_f32_16x16x32_bf16 v[26:29], v[156:159], v[206:209], v[26:29]
	v_mfma_f32_16x16x32_bf16 v[14:17], v[144:147], v[214:217], v[14:17]
	v_mfma_f32_16x16x32_bf16 v[10:13], v[156:159], v[214:217], v[10:13]
	v_mfma_f32_16x16x32_bf16 v[54:57], v[160:163], v[176:179], v[54:57]
	v_mfma_f32_16x16x32_bf16 v[50:53], v[168:171], v[176:179], v[50:53]
	v_mfma_f32_16x16x32_bf16 v[38:41], v[160:163], v[194:197], v[38:41]
	v_mfma_f32_16x16x32_bf16 v[34:37], v[168:171], v[194:197], v[34:37]
	v_mfma_f32_16x16x32_bf16 v[22:25], v[160:163], v[202:205], v[22:25]
	v_mfma_f32_16x16x32_bf16 v[18:21], v[168:171], v[202:205], v[18:21]
	v_mfma_f32_16x16x32_bf16 v[6:9], v[160:163], v[210:213], v[6:9]
	v_mfma_f32_16x16x32_bf16 v[2:5], v[168:171], v[210:213], v[2:5]
	v_mfma_f32_16x16x32_bf16 v[54:57], v[164:167], v[190:193], v[54:57]
	v_mfma_f32_16x16x32_bf16 v[50:53], v[172:175], v[190:193], v[50:53]
	v_mfma_f32_16x16x32_bf16 v[38:41], v[164:167], v[198:201], v[38:41]
	v_mfma_f32_16x16x32_bf16 v[34:37], v[172:175], v[198:201], v[34:37]
	v_mfma_f32_16x16x32_bf16 v[22:25], v[164:167], v[206:209], v[22:25]
	v_mfma_f32_16x16x32_bf16 v[18:21], v[172:175], v[206:209], v[18:21]
	v_mfma_f32_16x16x32_bf16 v[6:9], v[164:167], v[214:217], v[6:9]
	v_mfma_f32_16x16x32_bf16 v[2:5], v[172:175], v[214:217], v[2:5]
	s_barrier
	s_add_i32 s63, s63, 2
	s_add_u32 s36, s36, 0x100
	s_addc_u32 s37, s37, 0
	s_add_u32 s61, s61, 0x100
	s_addc_u32 s62, s62, 0
	s_cmp_gt_u32 s63, 29
	s_cbranch_scc0 .LBB0_1230
	s_and_b64 vcc, exec, s[30:31]
	s_cbranch_vccz .LBB0_1233
	s_barrier

.LBB0_1583:
	s_add_u32 s46, s48, 0xfff80080
	s_addc_u32 s47, s49, -1
	s_add_i32 s68, 0, 0x10000
	s_cmp_eq_u32 s67, 28
	s_cselect_b32 s51, s35, s47
	s_cselect_b32 s50, s39, s46
	s_cselect_b32 s47, s31, s66
	s_cselect_b32 s46, s45, s64
	s_add_i32 s70, 0, 0x14000
	v_add_u32_e32 v162, s68, v152
	v_add_u32_e32 v178, s70, v152
	ds_read_b128 v[144:147], v162
	ds_read_b128 v[154:157], v162 offset:1024
	ds_read_b128 v[158:161], v162 offset:2048
	ds_read_b128 v[162:165], v162 offset:3072
	ds_read_b128 v[166:169], v178
	ds_read_b128 v[170:173], v178 offset:1024
	ds_read_b128 v[174:177], v178 offset:2048
	ds_read_b128 v[190:193], v178 offset:3072
	v_lshl_add_u64 v[178:179], s[48:49], 0, v[140:141]
	s_add_i32 m0, s56, 0xc000
	ds_read_b128 v[194:197], v153
	ds_read_b128 v[198:201], v153 offset:1024
	ds_read_b128 v[202:205], v153 offset:2048
	ds_read_b128 v[206:209], v153 offset:3072
	ds_read_b128 v[210:213], v153 offset:4096
	ds_read_b128 v[214:217], v153 offset:5120
	ds_read_b128 v[218:221], v153 offset:6144
	ds_read_b128 v[238:241], v153 offset:7168
	global_load_lds_dwordx4 v[178:179], off
	v_lshl_add_u64 v[178:179], s[48:49], 0, v[142:143]
	s_add_i32 m0, s56, 0xe000
	s_nop 0
	global_load_lds_dwordx4 v[178:179], off
	s_waitcnt vmcnt(8)
	s_waitcnt lgkmcnt(0)
	s_barrier
	s_waitcnt lgkmcnt(0)
	v_mfma_f32_16x16x32_bf16 v[126:129], v[144:147], v[194:197], v[126:129]
	v_mfma_f32_16x16x32_bf16 v[114:117], v[158:161], v[194:197], v[114:117]
	v_mfma_f32_16x16x32_bf16 v[106:109], v[144:147], v[202:205], v[106:109]
	v_mfma_f32_16x16x32_bf16 v[98:101], v[158:161], v[202:205], v[98:101]
	v_mfma_f32_16x16x32_bf16 v[90:93], v[144:147], v[210:213], v[90:93]
	v_mfma_f32_16x16x32_bf16 v[82:85], v[158:161], v[210:213], v[82:85]
	v_mfma_f32_16x16x32_bf16 v[74:77], v[144:147], v[218:221], v[74:77]
	v_mfma_f32_16x16x32_bf16 v[54:57], v[158:161], v[218:221], v[54:57]
	v_mfma_f32_16x16x32_bf16 v[126:129], v[154:157], v[198:201], v[126:129]
	v_mfma_f32_16x16x32_bf16 v[114:117], v[162:165], v[198:201], v[114:117]
	v_mfma_f32_16x16x32_bf16 v[106:109], v[154:157], v[206:209], v[106:109]
	v_mfma_f32_16x16x32_bf16 v[98:101], v[162:165], v[206:209], v[98:101]
	v_mfma_f32_16x16x32_bf16 v[90:93], v[154:157], v[214:217], v[90:93]
	v_mfma_f32_16x16x32_bf16 v[82:85], v[162:165], v[214:217], v[82:85]
	v_mfma_f32_16x16x32_bf16 v[74:77], v[154:157], v[238:241], v[74:77]
	v_mfma_f32_16x16x32_bf16 v[54:57], v[162:165], v[238:241], v[54:57]
	v_mfma_f32_16x16x32_bf16 v[118:121], v[166:169], v[194:197], v[118:121]
	v_mfma_f32_16x16x32_bf16 v[122:125], v[174:177], v[194:197], v[122:125]
	v_mfma_f32_16x16x32_bf16 v[102:105], v[166:169], v[202:205], v[102:105]
	v_mfma_f32_16x16x32_bf16 v[110:113], v[174:177], v[202:205], v[110:113]
	v_mfma_f32_16x16x32_bf16 v[86:89], v[166:169], v[210:213], v[86:89]
	v_mfma_f32_16x16x32_bf16 v[94:97], v[174:177], v[210:213], v[94:97]
	v_mfma_f32_16x16x32_bf16 v[70:73], v[166:169], v[218:221], v[70:73]
	v_mfma_f32_16x16x32_bf16 v[78:81], v[174:177], v[218:221], v[78:81]
	v_mfma_f32_16x16x32_bf16 v[118:121], v[170:173], v[198:201], v[118:121]
	v_mfma_f32_16x16x32_bf16 v[122:125], v[190:193], v[198:201], v[122:125]
	v_mfma_f32_16x16x32_bf16 v[102:105], v[170:173], v[206:209], v[102:105]
	v_mfma_f32_16x16x32_bf16 v[110:113], v[190:193], v[206:209], v[110:113]
	v_mfma_f32_16x16x32_bf16 v[86:89], v[170:173], v[214:217], v[86:89]
	v_mfma_f32_16x16x32_bf16 v[94:97], v[190:193], v[214:217], v[94:97]
	v_mfma_f32_16x16x32_bf16 v[70:73], v[170:173], v[238:241], v[70:73]
	v_mfma_f32_16x16x32_bf16 v[78:81], v[190:193], v[238:241], v[78:81]
	s_barrier
	s_add_i32 s68, s68, s8
	v_lshl_add_u64 v[178:179], s[46:47], 0, v[134:135]
	s_mov_b32 m0, s68
	ds_read_b128 v[194:197], v153 offset:16384
	ds_read_b128 v[198:201], v153 offset:17408
	ds_read_b128 v[202:205], v153 offset:18432
	ds_read_b128 v[206:209], v153 offset:19456
	ds_read_b128 v[210:213], v153 offset:20480
	ds_read_b128 v[214:217], v153 offset:21504
	ds_read_b128 v[218:221], v153 offset:22528
	ds_read_b128 v[238:241], v153 offset:23552
	global_load_lds_dwordx4 v[178:179], off
	s_add_i32 m0, s68, 0x2000
	s_add_u32 s68, s46, 0x80000
	v_lshl_add_u64 v[222:223], s[46:47], 0, v[138:139]
	s_addc_u32 s69, s47, 0
	s_add_i32 s70, s70, s8
	global_load_lds_dwordx4 v[222:223], off
	v_lshl_add_u64 v[242:243], s[68:69], 0, v[134:135]
	s_mov_b32 m0, s70
	v_lshl_add_u64 v[244:245], s[50:51], 0, v[136:137]
	global_load_lds_dwordx4 v[242:243], off
	v_lshl_add_u64 v[242:243], s[68:69], 0, v[138:139]
	s_add_i32 m0, s70, 0x2000
	s_nop 0
	global_load_lds_dwordx4 v[242:243], off
	v_lshl_add_u64 v[242:243], s[50:51], 0, v[132:133]
	s_mov_b32 m0, s56
	s_nop 0
	global_load_lds_dwordx4 v[242:243], off
	s_mov_b32 m0, s57
	s_nop 0
	global_load_lds_dwordx4 v[244:245], off
	s_waitcnt vmcnt(8)
	s_waitcnt lgkmcnt(0)
	s_barrier
	s_waitcnt lgkmcnt(0)
	v_mfma_f32_16x16x32_bf16 v[50:53], v[144:147], v[194:197], v[50:53]
	v_mfma_f32_16x16x32_bf16 v[38:41], v[158:161], v[194:197], v[38:41]
	v_mfma_f32_16x16x32_bf16 v[22:25], v[144:147], v[202:205], v[22:25]
	v_mfma_f32_16x16x32_bf16 v[42:45], v[158:161], v[202:205], v[42:45]
	v_mfma_f32_16x16x32_bf16 v[30:33], v[144:147], v[210:213], v[30:33]
	v_mfma_f32_16x16x32_bf16 v[18:21], v[158:161], v[210:213], v[18:21]
	v_mfma_f32_16x16x32_bf16 v[10:13], v[144:147], v[218:221], v[10:13]
	v_mfma_f32_16x16x32_bf16 v[2:5], v[158:161], v[218:221], v[2:5]
	v_mfma_f32_16x16x32_bf16 v[50:53], v[154:157], v[198:201], v[50:53]
	v_mfma_f32_16x16x32_bf16 v[38:41], v[162:165], v[198:201], v[38:41]
	v_mfma_f32_16x16x32_bf16 v[22:25], v[154:157], v[206:209], v[22:25]
	v_mfma_f32_16x16x32_bf16 v[42:45], v[162:165], v[206:209], v[42:45]
	v_mfma_f32_16x16x32_bf16 v[30:33], v[154:157], v[214:217], v[30:33]
	v_mfma_f32_16x16x32_bf16 v[18:21], v[162:165], v[214:217], v[18:21]
	v_mfma_f32_16x16x32_bf16 v[10:13], v[154:157], v[238:241], v[10:13]
	v_mfma_f32_16x16x32_bf16 v[2:5], v[162:165], v[238:241], v[2:5]
	v_mfma_f32_16x16x32_bf16 v[46:49], v[166:169], v[194:197], v[46:49]
	v_mfma_f32_16x16x32_bf16 v[58:61], v[174:177], v[194:197], v[58:61]
	v_mfma_f32_16x16x32_bf16 v[62:65], v[166:169], v[202:205], v[62:65]
	v_mfma_f32_16x16x32_bf16 v[66:69], v[174:177], v[202:205], v[66:69]
	v_mfma_f32_16x16x32_bf16 v[26:29], v[166:169], v[210:213], v[26:29]
	v_mfma_f32_16x16x32_bf16 v[34:37], v[174:177], v[210:213], v[34:37]
	v_mfma_f32_16x16x32_bf16 v[6:9], v[166:169], v[218:221], v[6:9]
	v_mfma_f32_16x16x32_bf16 v[14:17], v[174:177], v[218:221], v[14:17]
	v_mfma_f32_16x16x32_bf16 v[46:49], v[170:173], v[198:201], v[46:49]
	v_mfma_f32_16x16x32_bf16 v[58:61], v[190:193], v[198:201], v[58:61]
	v_mfma_f32_16x16x32_bf16 v[62:65], v[170:173], v[206:209], v[62:65]
	v_mfma_f32_16x16x32_bf16 v[66:69], v[190:193], v[206:209], v[66:69]
	v_mfma_f32_16x16x32_bf16 v[26:29], v[170:173], v[214:217], v[26:29]
	v_mfma_f32_16x16x32_bf16 v[34:37], v[190:193], v[214:217], v[34:37]
	v_mfma_f32_16x16x32_bf16 v[6:9], v[170:173], v[238:241], v[6:9]
	v_mfma_f32_16x16x32_bf16 v[14:17], v[190:193], v[238:241], v[14:17]
	s_barrier
	s_add_i32 s68, 0, 0x18000
	s_add_i32 s69, 0, 0x1c000
	v_add_u32_e32 v162, s68, v152
	v_add_u32_e32 v190, s69, v152
	ds_read_b128 v[144:147], v162
	ds_read_b128 v[154:157], v162 offset:1024
	ds_read_b128 v[158:161], v162 offset:2048
	ds_read_b128 v[162:165], v162 offset:3072
	ds_read_b128 v[166:169], v190
	ds_read_b128 v[170:173], v190 offset:1024
	ds_read_b128 v[174:177], v190 offset:2048
	ds_read_b128 v[190:193], v190 offset:3072
	s_add_u32 s50, s50, 0x80000
	s_addc_u32 s51, s51, 0
	s_mov_b32 m0, s58
	v_lshl_add_u64 v[246:247], s[50:51], 0, v[132:133]
	ds_read_b128 v[194:197], v153 offset:32768
	ds_read_b128 v[198:201], v153 offset:33792
	ds_read_b128 v[202:205], v153 offset:34816
	ds_read_b128 v[206:209], v153 offset:35840
	ds_read_b128 v[210:213], v153 offset:36864
	ds_read_b128 v[214:217], v153 offset:37888
	ds_read_b128 v[218:221], v153 offset:38912
	ds_read_b128 v[238:241], v153 offset:39936
	global_load_lds_dwordx4 v[246:247], off
	v_lshl_add_u64 v[246:247], s[50:51], 0, v[136:137]
	s_mov_b32 m0, s59
	s_nop 0
	global_load_lds_dwordx4 v[246:247], off
	s_waitcnt vmcnt(8)
	s_waitcnt lgkmcnt(0)
	s_barrier
	s_waitcnt lgkmcnt(0)
	v_mfma_f32_16x16x32_bf16 v[126:129], v[144:147], v[194:197], v[126:129]
	v_mfma_f32_16x16x32_bf16 v[114:117], v[158:161], v[194:197], v[114:117]
	v_mfma_f32_16x16x32_bf16 v[106:109], v[144:147], v[202:205], v[106:109]
	v_mfma_f32_16x16x32_bf16 v[98:101], v[158:161], v[202:205], v[98:101]
	v_mfma_f32_16x16x32_bf16 v[90:93], v[144:147], v[210:213], v[90:93]
	v_mfma_f32_16x16x32_bf16 v[82:85], v[158:161], v[210:213], v[82:85]
	v_mfma_f32_16x16x32_bf16 v[74:77], v[144:147], v[218:221], v[74:77]
	v_mfma_f32_16x16x32_bf16 v[54:57], v[158:161], v[218:221], v[54:57]
	v_mfma_f32_16x16x32_bf16 v[126:129], v[154:157], v[198:201], v[126:129]
	v_mfma_f32_16x16x32_bf16 v[114:117], v[162:165], v[198:201], v[114:117]
	v_mfma_f32_16x16x32_bf16 v[106:109], v[154:157], v[206:209], v[106:109]
	v_mfma_f32_16x16x32_bf16 v[98:101], v[162:165], v[206:209], v[98:101]
	v_mfma_f32_16x16x32_bf16 v[90:93], v[154:157], v[214:217], v[90:93]
	v_mfma_f32_16x16x32_bf16 v[82:85], v[162:165], v[214:217], v[82:85]
	v_mfma_f32_16x16x32_bf16 v[74:77], v[154:157], v[238:241], v[74:77]
	v_mfma_f32_16x16x32_bf16 v[54:57], v[162:165], v[238:241], v[54:57]
	v_mfma_f32_16x16x32_bf16 v[118:121], v[166:169], v[194:197], v[118:121]
	v_mfma_f32_16x16x32_bf16 v[122:125], v[174:177], v[194:197], v[122:125]
	v_mfma_f32_16x16x32_bf16 v[102:105], v[166:169], v[202:205], v[102:105]
	v_mfma_f32_16x16x32_bf16 v[110:113], v[174:177], v[202:205], v[110:113]
	v_mfma_f32_16x16x32_bf16 v[86:89], v[166:169], v[210:213], v[86:89]
	v_mfma_f32_16x16x32_bf16 v[94:97], v[174:177], v[210:213], v[94:97]
	v_mfma_f32_16x16x32_bf16 v[70:73], v[166:169], v[218:221], v[70:73]
	v_mfma_f32_16x16x32_bf16 v[78:81], v[174:177], v[218:221], v[78:81]
	v_mfma_f32_16x16x32_bf16 v[118:121], v[170:173], v[198:201], v[118:121]
	v_mfma_f32_16x16x32_bf16 v[122:125], v[190:193], v[198:201], v[122:125]
	v_mfma_f32_16x16x32_bf16 v[102:105], v[170:173], v[206:209], v[102:105]
	v_mfma_f32_16x16x32_bf16 v[110:113], v[190:193], v[206:209], v[110:113]
	v_mfma_f32_16x16x32_bf16 v[86:89], v[170:173], v[214:217], v[86:89]
	v_mfma_f32_16x16x32_bf16 v[94:97], v[190:193], v[214:217], v[94:97]
	v_mfma_f32_16x16x32_bf16 v[70:73], v[170:173], v[238:241], v[70:73]
	v_mfma_f32_16x16x32_bf16 v[78:81], v[190:193], v[238:241], v[78:81]
	s_barrier
	s_add_i32 s50, s68, s8
	v_lshl_add_u64 v[178:179], v[178:179], 0, s[16:17]
	s_mov_b32 m0, s50
	ds_read_b128 v[194:197], v153 offset:49152
	ds_read_b128 v[198:201], v153 offset:50176
	ds_read_b128 v[202:205], v153 offset:51200
	ds_read_b128 v[206:209], v153 offset:52224
	ds_read_b128 v[210:213], v153 offset:53248
	ds_read_b128 v[214:217], v153 offset:54272
	ds_read_b128 v[218:221], v153 offset:55296
	ds_read_b128 v[238:241], v153 offset:56320
	global_load_lds_dwordx4 v[178:179], off
	s_add_i32 m0, s50, 0x2000
	s_add_u32 s46, s46, 0x80080
	v_lshl_add_u64 v[178:179], v[222:223], 0, s[16:17]
	s_addc_u32 s47, s47, 0
	s_add_i32 s50, s69, s8
	global_load_lds_dwordx4 v[178:179], off
	v_lshl_add_u64 v[178:179], s[46:47], 0, v[134:135]
	s_mov_b32 m0, s50
	s_nop 0
	global_load_lds_dwordx4 v[178:179], off
	v_lshl_add_u64 v[178:179], s[46:47], 0, v[138:139]
	s_add_i32 m0, s50, 0x2000
	s_nop 0
	global_load_lds_dwordx4 v[178:179], off
	v_lshl_add_u64 v[178:179], v[242:243], 0, s[16:17]
	s_mov_b32 m0, s60
	s_nop 0
	global_load_lds_dwordx4 v[178:179], off
	v_lshl_add_u64 v[178:179], v[244:245], 0, s[16:17]
	s_mov_b32 m0, s61
	s_nop 0
	global_load_lds_dwordx4 v[178:179], off
	s_waitcnt vmcnt(8)
	s_waitcnt lgkmcnt(0)
	s_barrier
	s_waitcnt lgkmcnt(0)
	v_mfma_f32_16x16x32_bf16 v[50:53], v[144:147], v[194:197], v[50:53]
	v_mfma_f32_16x16x32_bf16 v[38:41], v[158:161], v[194:197], v[38:41]
	v_mfma_f32_16x16x32_bf16 v[22:25], v[144:147], v[202:205], v[22:25]
	v_mfma_f32_16x16x32_bf16 v[42:45], v[158:161], v[202:205], v[42:45]
	v_mfma_f32_16x16x32_bf16 v[30:33], v[144:147], v[210:213], v[30:33]
	v_mfma_f32_16x16x32_bf16 v[18:21], v[158:161], v[210:213], v[18:21]
	v_mfma_f32_16x16x32_bf16 v[10:13], v[144:147], v[218:221], v[10:13]
	v_mfma_f32_16x16x32_bf16 v[2:5], v[158:161], v[218:221], v[2:5]
	v_mfma_f32_16x16x32_bf16 v[50:53], v[154:157], v[198:201], v[50:53]
	v_mfma_f32_16x16x32_bf16 v[38:41], v[162:165], v[198:201], v[38:41]
	v_mfma_f32_16x16x32_bf16 v[22:25], v[154:157], v[206:209], v[22:25]
	v_mfma_f32_16x16x32_bf16 v[42:45], v[162:165], v[206:209], v[42:45]
	v_mfma_f32_16x16x32_bf16 v[30:33], v[154:157], v[214:217], v[30:33]
	v_mfma_f32_16x16x32_bf16 v[18:21], v[162:165], v[214:217], v[18:21]
	v_mfma_f32_16x16x32_bf16 v[10:13], v[154:157], v[238:241], v[10:13]
	v_mfma_f32_16x16x32_bf16 v[2:5], v[162:165], v[238:241], v[2:5]
	v_mfma_f32_16x16x32_bf16 v[46:49], v[166:169], v[194:197], v[46:49]
	v_mfma_f32_16x16x32_bf16 v[58:61], v[174:177], v[194:197], v[58:61]
	v_mfma_f32_16x16x32_bf16 v[62:65], v[166:169], v[202:205], v[62:65]
	v_mfma_f32_16x16x32_bf16 v[66:69], v[174:177], v[202:205], v[66:69]
	v_mfma_f32_16x16x32_bf16 v[26:29], v[166:169], v[210:213], v[26:29]
	v_mfma_f32_16x16x32_bf16 v[34:37], v[174:177], v[210:213], v[34:37]
	v_mfma_f32_16x16x32_bf16 v[6:9], v[166:169], v[218:221], v[6:9]
	v_mfma_f32_16x16x32_bf16 v[14:17], v[174:177], v[218:221], v[14:17]
	v_mfma_f32_16x16x32_bf16 v[46:49], v[170:173], v[198:201], v[46:49]
	v_mfma_f32_16x16x32_bf16 v[58:61], v[190:193], v[198:201], v[58:61]
	v_mfma_f32_16x16x32_bf16 v[62:65], v[170:173], v[206:209], v[62:65]
	v_mfma_f32_16x16x32_bf16 v[66:69], v[190:193], v[206:209], v[66:69]
	v_mfma_f32_16x16x32_bf16 v[26:29], v[170:173], v[214:217], v[26:29]
	v_mfma_f32_16x16x32_bf16 v[34:37], v[190:193], v[214:217], v[34:37]
	v_mfma_f32_16x16x32_bf16 v[6:9], v[170:173], v[238:241], v[6:9]
	v_mfma_f32_16x16x32_bf16 v[14:17], v[190:193], v[238:241], v[14:17]
	s_barrier
	s_add_i32 s67, s67, 2
	s_add_u32 s48, s48, 0x100
	s_addc_u32 s49, s49, 0
	s_add_u32 s64, s64, 0x100
	s_addc_u32 s66, s66, 0
	s_cmp_gt_u32 s67, 29
	s_cbranch_scc0 .LBB0_1583
	s_and_b64 vcc, exec, s[28:29]
	s_cbranch_vccz .LBB0_1586
	s_barrier

.LBB0_1685:
	s_add_u32 s42, s40, 0xfff80080
	s_addc_u32 s43, s41, -1
	s_and_b64 s[26:27], s[26:27], exec
	s_cselect_b32 s43, s19, s43
	s_cselect_b32 s42, s45, s42
	s_cselect_b32 s27, s50, s39
	s_cselect_b32 s26, s51, s37
	s_add_i32 s47, 0, 0x10000
	s_add_i32 s69, 0, 0x14000
	v_add_u32_e32 v146, s47, v239
	v_add_u32_e32 v162, s69, v239
	ds_read_b128 v[114:117], v146
	ds_read_b128 v[118:121], v146 offset:1024
	ds_read_b128 v[122:125], v146 offset:2048
	ds_read_b128 v[146:149], v146 offset:3072
	ds_read_b128 v[150:153], v162
	ds_read_b128 v[154:157], v162 offset:1024
	ds_read_b128 v[158:161], v162 offset:2048
	ds_read_b128 v[162:165], v162 offset:3072
	v_lshl_add_u64 v[178:179], s[40:41], 0, v[202:203]
	s_add_i32 m0, s6, 0xc000
	ds_read_b128 v[166:169], v240
	ds_read_b128 v[170:173], v240 offset:1024
	ds_read_b128 v[174:177], v240 offset:2048
	ds_read_b128 v[206:209], v240 offset:3072
	ds_read_b128 v[210:213], v240 offset:4096
	ds_read_b128 v[214:217], v240 offset:5120
	ds_read_b128 v[218:221], v240 offset:6144
	ds_read_b128 v[242:245], v240 offset:7168
	global_load_lds_dwordx4 v[178:179], off
	v_lshl_add_u64 v[178:179], s[40:41], 0, v[204:205]
	s_add_i32 m0, s6, 0xe000
	s_nop 0
	global_load_lds_dwordx4 v[178:179], off
	s_waitcnt vmcnt(8)
	s_waitcnt lgkmcnt(0)
	s_barrier
	s_waitcnt lgkmcnt(0)
	v_mfma_f32_16x16x32_bf16 v[142:145], v[114:117], v[166:169], v[142:145]
	v_mfma_f32_16x16x32_bf16 v[62:65], v[122:125], v[166:169], v[62:65]
	v_mfma_f32_16x16x32_bf16 v[134:137], v[114:117], v[174:177], v[134:137]
	v_mfma_f32_16x16x32_bf16 v[54:57], v[122:125], v[174:177], v[54:57]
	v_mfma_f32_16x16x32_bf16 v[126:129], v[114:117], v[210:213], v[126:129]
	v_mfma_f32_16x16x32_bf16 v[46:49], v[122:125], v[210:213], v[46:49]
	v_mfma_f32_16x16x32_bf16 v[102:105], v[114:117], v[218:221], v[102:105]
	v_mfma_f32_16x16x32_bf16 v[38:41], v[122:125], v[218:221], v[38:41]
	v_mfma_f32_16x16x32_bf16 v[142:145], v[118:121], v[170:173], v[142:145]
	v_mfma_f32_16x16x32_bf16 v[62:65], v[146:149], v[170:173], v[62:65]
	v_mfma_f32_16x16x32_bf16 v[134:137], v[118:121], v[206:209], v[134:137]
	v_mfma_f32_16x16x32_bf16 v[54:57], v[146:149], v[206:209], v[54:57]
	v_mfma_f32_16x16x32_bf16 v[126:129], v[118:121], v[214:217], v[126:129]
	v_mfma_f32_16x16x32_bf16 v[46:49], v[146:149], v[214:217], v[46:49]
	v_mfma_f32_16x16x32_bf16 v[102:105], v[118:121], v[242:245], v[102:105]
	v_mfma_f32_16x16x32_bf16 v[38:41], v[146:149], v[242:245], v[38:41]
	v_mfma_f32_16x16x32_bf16 v[138:141], v[150:153], v[166:169], v[138:141]
	v_mfma_f32_16x16x32_bf16 v[58:61], v[158:161], v[166:169], v[58:61]
	v_mfma_f32_16x16x32_bf16 v[130:133], v[150:153], v[174:177], v[130:133]
	v_mfma_f32_16x16x32_bf16 v[50:53], v[158:161], v[174:177], v[50:53]
	v_mfma_f32_16x16x32_bf16 v[106:109], v[150:153], v[210:213], v[106:109]
	v_mfma_f32_16x16x32_bf16 v[42:45], v[158:161], v[210:213], v[42:45]
	v_mfma_f32_16x16x32_bf16 v[98:101], v[150:153], v[218:221], v[98:101]
	v_mfma_f32_16x16x32_bf16 v[34:37], v[158:161], v[218:221], v[34:37]
	v_mfma_f32_16x16x32_bf16 v[138:141], v[154:157], v[170:173], v[138:141]
	v_mfma_f32_16x16x32_bf16 v[58:61], v[162:165], v[170:173], v[58:61]
	v_mfma_f32_16x16x32_bf16 v[130:133], v[154:157], v[206:209], v[130:133]
	v_mfma_f32_16x16x32_bf16 v[50:53], v[162:165], v[206:209], v[50:53]
	v_mfma_f32_16x16x32_bf16 v[106:109], v[154:157], v[214:217], v[106:109]
	v_mfma_f32_16x16x32_bf16 v[42:45], v[162:165], v[214:217], v[42:45]
	v_mfma_f32_16x16x32_bf16 v[98:101], v[154:157], v[242:245], v[98:101]
	v_mfma_f32_16x16x32_bf16 v[34:37], v[162:165], v[242:245], v[34:37]
	s_barrier
	s_add_i32 s47, s47, s23
	v_lshl_add_u64 v[178:179], s[26:27], 0, v[180:181]
	s_mov_b32 m0, s47
	ds_read_b128 v[166:169], v240 offset:16384
	ds_read_b128 v[170:173], v240 offset:17408
	ds_read_b128 v[174:177], v240 offset:18432
	ds_read_b128 v[206:209], v240 offset:19456
	ds_read_b128 v[210:213], v240 offset:20480
	ds_read_b128 v[214:217], v240 offset:21504
	ds_read_b128 v[218:221], v240 offset:22528
	ds_read_b128 v[242:245], v240 offset:23552
	global_load_lds_dwordx4 v[178:179], off
	s_add_i32 m0, s47, 0x2000
	s_add_u32 s48, s26, 0x80000
	v_lshl_add_u64 v[222:223], s[26:27], 0, v[196:197]
	s_addc_u32 s49, s27, 0
	s_add_i32 s47, s69, s23
	global_load_lds_dwordx4 v[222:223], off
	v_lshl_add_u64 v[246:247], s[48:49], 0, v[180:181]
	s_mov_b32 m0, s47
	v_lshl_add_u64 v[248:249], s[42:43], 0, v[194:195]
	global_load_lds_dwordx4 v[246:247], off
	v_lshl_add_u64 v[246:247], s[48:49], 0, v[196:197]
	s_add_i32 m0, s47, 0x2000
	s_nop 0
	global_load_lds_dwordx4 v[246:247], off
	v_lshl_add_u64 v[246:247], s[42:43], 0, v[192:193]
	s_mov_b32 m0, s6
	s_nop 0
	global_load_lds_dwordx4 v[246:247], off
	s_mov_b32 m0, s9
	s_nop 0
	global_load_lds_dwordx4 v[248:249], off
	s_waitcnt vmcnt(8)
	s_waitcnt lgkmcnt(0)
	s_barrier
	s_waitcnt lgkmcnt(0)
	v_mfma_f32_16x16x32_bf16 v[94:97], v[114:117], v[166:169], v[94:97]
	v_mfma_f32_16x16x32_bf16 v[30:33], v[122:125], v[166:169], v[30:33]
	v_mfma_f32_16x16x32_bf16 v[86:89], v[114:117], v[174:177], v[86:89]
	v_mfma_f32_16x16x32_bf16 v[22:25], v[122:125], v[174:177], v[22:25]
	v_mfma_f32_16x16x32_bf16 v[78:81], v[114:117], v[210:213], v[78:81]
	v_mfma_f32_16x16x32_bf16 v[14:17], v[122:125], v[210:213], v[14:17]
	v_mfma_f32_16x16x32_bf16 v[70:73], v[114:117], v[218:221], v[70:73]
	v_mfma_f32_16x16x32_bf16 v[6:9], v[122:125], v[218:221], v[6:9]
	v_mfma_f32_16x16x32_bf16 v[94:97], v[118:121], v[170:173], v[94:97]
	v_mfma_f32_16x16x32_bf16 v[30:33], v[146:149], v[170:173], v[30:33]
	v_mfma_f32_16x16x32_bf16 v[86:89], v[118:121], v[206:209], v[86:89]
	v_mfma_f32_16x16x32_bf16 v[22:25], v[146:149], v[206:209], v[22:25]
	v_mfma_f32_16x16x32_bf16 v[78:81], v[118:121], v[214:217], v[78:81]
	v_mfma_f32_16x16x32_bf16 v[14:17], v[146:149], v[214:217], v[14:17]
	v_mfma_f32_16x16x32_bf16 v[70:73], v[118:121], v[242:245], v[70:73]
	v_mfma_f32_16x16x32_bf16 v[6:9], v[146:149], v[242:245], v[6:9]
	v_mfma_f32_16x16x32_bf16 v[90:93], v[150:153], v[166:169], v[90:93]
	v_mfma_f32_16x16x32_bf16 v[26:29], v[158:161], v[166:169], v[26:29]
	v_mfma_f32_16x16x32_bf16 v[82:85], v[150:153], v[174:177], v[82:85]
	v_mfma_f32_16x16x32_bf16 v[18:21], v[158:161], v[174:177], v[18:21]
	v_mfma_f32_16x16x32_bf16 v[74:77], v[150:153], v[210:213], v[74:77]
	v_mfma_f32_16x16x32_bf16 v[10:13], v[158:161], v[210:213], v[10:13]
	v_mfma_f32_16x16x32_bf16 v[66:69], v[150:153], v[218:221], v[66:69]
	v_mfma_f32_16x16x32_bf16 v[2:5], v[158:161], v[218:221], v[2:5]
	v_mfma_f32_16x16x32_bf16 v[90:93], v[154:157], v[170:173], v[90:93]
	v_mfma_f32_16x16x32_bf16 v[26:29], v[162:165], v[170:173], v[26:29]
	v_mfma_f32_16x16x32_bf16 v[82:85], v[154:157], v[206:209], v[82:85]
	v_mfma_f32_16x16x32_bf16 v[18:21], v[162:165], v[206:209], v[18:21]
	v_mfma_f32_16x16x32_bf16 v[74:77], v[154:157], v[214:217], v[74:77]
	v_mfma_f32_16x16x32_bf16 v[10:13], v[162:165], v[214:217], v[10:13]
	v_mfma_f32_16x16x32_bf16 v[66:69], v[154:157], v[242:245], v[66:69]
	v_mfma_f32_16x16x32_bf16 v[2:5], v[162:165], v[242:245], v[2:5]
	s_barrier
	s_add_i32 s47, 0, 0x18000
	s_add_i32 s48, 0, 0x1c000
	v_add_u32_e32 v146, s47, v239
	v_add_u32_e32 v162, s48, v239
	ds_read_b128 v[114:117], v146
	ds_read_b128 v[118:121], v146 offset:1024
	ds_read_b128 v[122:125], v146 offset:2048
	ds_read_b128 v[146:149], v146 offset:3072
	ds_read_b128 v[150:153], v162
	ds_read_b128 v[154:157], v162 offset:1024
	ds_read_b128 v[158:161], v162 offset:2048
	ds_read_b128 v[162:165], v162 offset:3072
	s_add_u32 s42, s42, 0x80000
	s_addc_u32 s43, s43, 0
	s_mov_b32 m0, s21
	v_lshl_add_u64 v[250:251], s[42:43], 0, v[192:193]
	ds_read_b128 v[166:169], v240 offset:32768
	ds_read_b128 v[170:173], v240 offset:33792
	ds_read_b128 v[174:177], v240 offset:34816
	ds_read_b128 v[206:209], v240 offset:35840
	ds_read_b128 v[210:213], v240 offset:36864
	ds_read_b128 v[214:217], v240 offset:37888
	ds_read_b128 v[218:221], v240 offset:38912
	ds_read_b128 v[242:245], v240 offset:39936
	global_load_lds_dwordx4 v[250:251], off
	v_lshl_add_u64 v[250:251], s[42:43], 0, v[194:195]
	s_mov_b32 m0, s7
	s_nop 0
	global_load_lds_dwordx4 v[250:251], off
	s_waitcnt vmcnt(8)
	s_waitcnt lgkmcnt(0)
	s_barrier
	s_waitcnt lgkmcnt(0)
	v_mfma_f32_16x16x32_bf16 v[142:145], v[114:117], v[166:169], v[142:145]
	v_mfma_f32_16x16x32_bf16 v[62:65], v[122:125], v[166:169], v[62:65]
	v_mfma_f32_16x16x32_bf16 v[134:137], v[114:117], v[174:177], v[134:137]
	v_mfma_f32_16x16x32_bf16 v[54:57], v[122:125], v[174:177], v[54:57]
	v_mfma_f32_16x16x32_bf16 v[126:129], v[114:117], v[210:213], v[126:129]
	v_mfma_f32_16x16x32_bf16 v[46:49], v[122:125], v[210:213], v[46:49]
	v_mfma_f32_16x16x32_bf16 v[102:105], v[114:117], v[218:221], v[102:105]
	v_mfma_f32_16x16x32_bf16 v[38:41], v[122:125], v[218:221], v[38:41]
	v_mfma_f32_16x16x32_bf16 v[142:145], v[118:121], v[170:173], v[142:145]
	v_mfma_f32_16x16x32_bf16 v[62:65], v[146:149], v[170:173], v[62:65]
	v_mfma_f32_16x16x32_bf16 v[134:137], v[118:121], v[206:209], v[134:137]
	v_mfma_f32_16x16x32_bf16 v[54:57], v[146:149], v[206:209], v[54:57]
	v_mfma_f32_16x16x32_bf16 v[126:129], v[118:121], v[214:217], v[126:129]
	v_mfma_f32_16x16x32_bf16 v[46:49], v[146:149], v[214:217], v[46:49]
	v_mfma_f32_16x16x32_bf16 v[102:105], v[118:121], v[242:245], v[102:105]
	v_mfma_f32_16x16x32_bf16 v[38:41], v[146:149], v[242:245], v[38:41]
	v_mfma_f32_16x16x32_bf16 v[138:141], v[150:153], v[166:169], v[138:141]
	v_mfma_f32_16x16x32_bf16 v[58:61], v[158:161], v[166:169], v[58:61]
	v_mfma_f32_16x16x32_bf16 v[130:133], v[150:153], v[174:177], v[130:133]
	v_mfma_f32_16x16x32_bf16 v[50:53], v[158:161], v[174:177], v[50:53]
	v_mfma_f32_16x16x32_bf16 v[106:109], v[150:153], v[210:213], v[106:109]
	v_mfma_f32_16x16x32_bf16 v[42:45], v[158:161], v[210:213], v[42:45]
	v_mfma_f32_16x16x32_bf16 v[98:101], v[150:153], v[218:221], v[98:101]
	v_mfma_f32_16x16x32_bf16 v[34:37], v[158:161], v[218:221], v[34:37]
	v_mfma_f32_16x16x32_bf16 v[138:141], v[154:157], v[170:173], v[138:141]
	v_mfma_f32_16x16x32_bf16 v[58:61], v[162:165], v[170:173], v[58:61]
	v_mfma_f32_16x16x32_bf16 v[130:133], v[154:157], v[206:209], v[130:133]
	v_mfma_f32_16x16x32_bf16 v[50:53], v[162:165], v[206:209], v[50:53]
	v_mfma_f32_16x16x32_bf16 v[106:109], v[154:157], v[214:217], v[106:109]
	v_mfma_f32_16x16x32_bf16 v[42:45], v[162:165], v[214:217], v[42:45]
	v_mfma_f32_16x16x32_bf16 v[98:101], v[154:157], v[242:245], v[98:101]
	v_mfma_f32_16x16x32_bf16 v[34:37], v[162:165], v[242:245], v[34:37]
	s_barrier
	s_add_i32 s42, s47, s23
	v_lshl_add_u64 v[178:179], v[178:179], 0, s[16:17]
	s_mov_b32 m0, s42
	ds_read_b128 v[166:169], v240 offset:49152
	ds_read_b128 v[170:173], v240 offset:50176
	ds_read_b128 v[174:177], v240 offset:51200
	ds_read_b128 v[206:209], v240 offset:52224
	ds_read_b128 v[210:213], v240 offset:53248
	ds_read_b128 v[214:217], v240 offset:54272
	ds_read_b128 v[218:221], v240 offset:55296
	ds_read_b128 v[242:245], v240 offset:56320
	global_load_lds_dwordx4 v[178:179], off
	s_add_i32 m0, s42, 0x2000
	s_add_u32 s26, s26, 0x80080
	v_lshl_add_u64 v[178:179], v[222:223], 0, s[16:17]
	s_addc_u32 s27, s27, 0
	s_add_i32 s42, s48, s23
	global_load_lds_dwordx4 v[178:179], off
	v_lshl_add_u64 v[178:179], s[26:27], 0, v[180:181]
	s_mov_b32 m0, s42
	s_nop 0
	global_load_lds_dwordx4 v[178:179], off
	v_lshl_add_u64 v[178:179], s[26:27], 0, v[196:197]
	s_add_i32 m0, s42, 0x2000
	s_nop 0
	global_load_lds_dwordx4 v[178:179], off
	v_lshl_add_u64 v[178:179], v[246:247], 0, s[16:17]
	s_mov_b32 m0, s54
	s_nop 0
	global_load_lds_dwordx4 v[178:179], off
	v_lshl_add_u64 v[178:179], v[248:249], 0, s[16:17]
	s_mov_b32 m0, s55
	s_nop 0
	global_load_lds_dwordx4 v[178:179], off
	s_waitcnt vmcnt(8)
	s_waitcnt lgkmcnt(0)
	s_barrier
	s_waitcnt lgkmcnt(0)
	v_mfma_f32_16x16x32_bf16 v[94:97], v[114:117], v[166:169], v[94:97]
	v_mfma_f32_16x16x32_bf16 v[30:33], v[122:125], v[166:169], v[30:33]
	v_mfma_f32_16x16x32_bf16 v[86:89], v[114:117], v[174:177], v[86:89]
	v_mfma_f32_16x16x32_bf16 v[22:25], v[122:125], v[174:177], v[22:25]
	v_mfma_f32_16x16x32_bf16 v[78:81], v[114:117], v[210:213], v[78:81]
	v_mfma_f32_16x16x32_bf16 v[14:17], v[122:125], v[210:213], v[14:17]
	v_mfma_f32_16x16x32_bf16 v[70:73], v[114:117], v[218:221], v[70:73]
	v_mfma_f32_16x16x32_bf16 v[6:9], v[122:125], v[218:221], v[6:9]
	v_mfma_f32_16x16x32_bf16 v[94:97], v[118:121], v[170:173], v[94:97]
	v_mfma_f32_16x16x32_bf16 v[30:33], v[146:149], v[170:173], v[30:33]
	v_mfma_f32_16x16x32_bf16 v[86:89], v[118:121], v[206:209], v[86:89]
	v_mfma_f32_16x16x32_bf16 v[22:25], v[146:149], v[206:209], v[22:25]
	v_mfma_f32_16x16x32_bf16 v[78:81], v[118:121], v[214:217], v[78:81]
	v_mfma_f32_16x16x32_bf16 v[14:17], v[146:149], v[214:217], v[14:17]
	v_mfma_f32_16x16x32_bf16 v[70:73], v[118:121], v[242:245], v[70:73]
	v_mfma_f32_16x16x32_bf16 v[6:9], v[146:149], v[242:245], v[6:9]
	v_mfma_f32_16x16x32_bf16 v[90:93], v[150:153], v[166:169], v[90:93]
	v_mfma_f32_16x16x32_bf16 v[26:29], v[158:161], v[166:169], v[26:29]
	v_mfma_f32_16x16x32_bf16 v[82:85], v[150:153], v[174:177], v[82:85]
	v_mfma_f32_16x16x32_bf16 v[18:21], v[158:161], v[174:177], v[18:21]
	v_mfma_f32_16x16x32_bf16 v[74:77], v[150:153], v[210:213], v[74:77]
	v_mfma_f32_16x16x32_bf16 v[10:13], v[158:161], v[210:213], v[10:13]
	v_mfma_f32_16x16x32_bf16 v[66:69], v[150:153], v[218:221], v[66:69]
	v_mfma_f32_16x16x32_bf16 v[2:5], v[158:161], v[218:221], v[2:5]
	v_mfma_f32_16x16x32_bf16 v[90:93], v[154:157], v[170:173], v[90:93]
	v_mfma_f32_16x16x32_bf16 v[26:29], v[162:165], v[170:173], v[26:29]
	v_mfma_f32_16x16x32_bf16 v[82:85], v[154:157], v[206:209], v[82:85]
	v_mfma_f32_16x16x32_bf16 v[18:21], v[162:165], v[206:209], v[18:21]
	v_mfma_f32_16x16x32_bf16 v[74:77], v[154:157], v[214:217], v[74:77]
	v_mfma_f32_16x16x32_bf16 v[10:13], v[162:165], v[214:217], v[10:13]
	v_mfma_f32_16x16x32_bf16 v[66:69], v[154:157], v[242:245], v[66:69]
	v_mfma_f32_16x16x32_bf16 v[2:5], v[162:165], v[242:245], v[2:5]
	s_barrier
	s_add_i32 s46, s46, 2
	s_add_u32 s40, s40, 0x100
	s_addc_u32 s41, s41, 0
	s_add_u32 s37, s37, 0x100
	s_addc_u32 s39, s39, 0
	s_cmp_gt_u32 s46, 29
	s_cbranch_scc1 .LBB0_1688

.LBB0_1761:
	s_add_u32 s26, s38, 0xfff80080
	s_addc_u32 s27, s39, -1
	s_add_i32 s64, 0, 0x10000
	s_cmp_eq_u32 s63, 28
	s_cselect_b32 s41, s57, s27
	s_cselect_b32 s40, s58, s26
	v_add_u32_e32 v155, s64, v153
	s_cselect_b32 s27, s59, s62
	s_cselect_b32 s26, s60, s61
	s_add_i32 s68, 0, 0x14000
	ds_read_b128 v[138:141], v155
	ds_read_b128 v[142:145], v155 offset:1024
	ds_read_b128 v[146:149], v155 offset:2048
	ds_read_b128 v[156:159], v155 offset:3072
	v_add_u32_e32 v155, s68, v153
	ds_read_b128 v[160:163], v155
	ds_read_b128 v[164:167], v155 offset:1024
	ds_read_b128 v[168:171], v155 offset:2048
	ds_read_b128 v[172:175], v155 offset:3072
	v_lshl_add_u64 v[220:221], s[38:39], 0, v[134:135]
	s_add_i32 m0, s3, 0xc000
	ds_read_b128 v[176:179], v154
	ds_read_b128 v[192:195], v154 offset:1024
	ds_read_b128 v[196:199], v154 offset:2048
	ds_read_b128 v[200:203], v154 offset:3072
	ds_read_b128 v[204:207], v154 offset:4096
	ds_read_b128 v[208:211], v154 offset:5120
	ds_read_b128 v[212:215], v154 offset:6144
	ds_read_b128 v[216:219], v154 offset:7168
	global_load_lds_dwordx4 v[220:221], off
	v_lshl_add_u64 v[220:221], s[38:39], 0, v[136:137]
	s_add_i32 m0, s3, 0xe000
	s_nop 0
	global_load_lds_dwordx4 v[220:221], off
	s_waitcnt vmcnt(8)
	s_waitcnt lgkmcnt(0)
	s_barrier
	s_waitcnt lgkmcnt(0)
	v_mfma_f32_16x16x32_bf16 v[126:129], v[138:141], v[176:179], v[126:129]
	v_mfma_f32_16x16x32_bf16 v[122:125], v[146:149], v[176:179], v[122:125]
	v_mfma_f32_16x16x32_bf16 v[110:113], v[138:141], v[196:199], v[110:113]
	v_mfma_f32_16x16x32_bf16 v[106:109], v[146:149], v[196:199], v[106:109]
	v_mfma_f32_16x16x32_bf16 v[94:97], v[138:141], v[204:207], v[94:97]
	v_mfma_f32_16x16x32_bf16 v[90:93], v[146:149], v[204:207], v[90:93]
	v_mfma_f32_16x16x32_bf16 v[78:81], v[138:141], v[212:215], v[78:81]
	v_mfma_f32_16x16x32_bf16 v[74:77], v[146:149], v[212:215], v[74:77]
	v_mfma_f32_16x16x32_bf16 v[126:129], v[142:145], v[192:195], v[126:129]
	v_mfma_f32_16x16x32_bf16 v[122:125], v[156:159], v[192:195], v[122:125]
	v_mfma_f32_16x16x32_bf16 v[110:113], v[142:145], v[200:203], v[110:113]
	v_mfma_f32_16x16x32_bf16 v[106:109], v[156:159], v[200:203], v[106:109]
	v_mfma_f32_16x16x32_bf16 v[94:97], v[142:145], v[208:211], v[94:97]
	v_mfma_f32_16x16x32_bf16 v[90:93], v[156:159], v[208:211], v[90:93]
	v_mfma_f32_16x16x32_bf16 v[78:81], v[142:145], v[216:219], v[78:81]
	v_mfma_f32_16x16x32_bf16 v[74:77], v[156:159], v[216:219], v[74:77]
	v_mfma_f32_16x16x32_bf16 v[118:121], v[160:163], v[176:179], v[118:121]
	v_mfma_f32_16x16x32_bf16 v[114:117], v[168:171], v[176:179], v[114:117]
	v_mfma_f32_16x16x32_bf16 v[102:105], v[160:163], v[196:199], v[102:105]
	v_mfma_f32_16x16x32_bf16 v[98:101], v[168:171], v[196:199], v[98:101]
	v_mfma_f32_16x16x32_bf16 v[86:89], v[160:163], v[204:207], v[86:89]
	v_mfma_f32_16x16x32_bf16 v[82:85], v[168:171], v[204:207], v[82:85]
	v_mfma_f32_16x16x32_bf16 v[70:73], v[160:163], v[212:215], v[70:73]
	v_mfma_f32_16x16x32_bf16 v[66:69], v[168:171], v[212:215], v[66:69]
	v_mfma_f32_16x16x32_bf16 v[118:121], v[164:167], v[192:195], v[118:121]
	v_mfma_f32_16x16x32_bf16 v[114:117], v[172:175], v[192:195], v[114:117]
	v_mfma_f32_16x16x32_bf16 v[102:105], v[164:167], v[200:203], v[102:105]
	v_mfma_f32_16x16x32_bf16 v[98:101], v[172:175], v[200:203], v[98:101]
	v_mfma_f32_16x16x32_bf16 v[86:89], v[164:167], v[208:211], v[86:89]
	v_mfma_f32_16x16x32_bf16 v[82:85], v[172:175], v[208:211], v[82:85]
	v_mfma_f32_16x16x32_bf16 v[70:73], v[164:167], v[216:219], v[70:73]
	v_mfma_f32_16x16x32_bf16 v[66:69], v[172:175], v[216:219], v[66:69]
	s_barrier
	s_add_i32 s64, s64, s43
	v_lshl_add_u64 v[220:221], s[26:27], 0, v[132:133]
	s_mov_b32 m0, s64
	ds_read_b128 v[176:179], v154 offset:16384
	ds_read_b128 v[192:195], v154 offset:17408
	ds_read_b128 v[196:199], v154 offset:18432
	ds_read_b128 v[200:203], v154 offset:19456
	ds_read_b128 v[204:207], v154 offset:20480
	ds_read_b128 v[208:211], v154 offset:21504
	ds_read_b128 v[212:215], v154 offset:22528
	ds_read_b128 v[216:219], v154 offset:23552
	global_load_lds_dwordx4 v[220:221], off
	s_add_i32 m0, s64, 0x2000
	s_add_u32 s66, s26, 0x80000
	v_lshl_add_u64 v[222:223], s[26:27], 0, v[130:131]
	s_addc_u32 s67, s27, 0
	s_add_i32 s64, s68, s43
	global_load_lds_dwordx4 v[222:223], off
	v_lshl_add_u64 v[238:239], s[66:67], 0, v[132:133]
	s_mov_b32 m0, s64
	v_lshl_add_u64 v[240:241], s[40:41], 0, v[130:131]
	global_load_lds_dwordx4 v[238:239], off
	v_lshl_add_u64 v[238:239], s[66:67], 0, v[130:131]
	s_add_i32 m0, s64, 0x2000
	s_nop 0
	global_load_lds_dwordx4 v[238:239], off
	v_lshl_add_u64 v[238:239], s[40:41], 0, v[132:133]
	s_mov_b32 m0, s3
	s_nop 0
	global_load_lds_dwordx4 v[238:239], off
	s_mov_b32 m0, s45
	s_nop 0
	global_load_lds_dwordx4 v[240:241], off
	s_waitcnt vmcnt(8)
	s_waitcnt lgkmcnt(0)
	s_barrier
	s_waitcnt lgkmcnt(0)
	v_mfma_f32_16x16x32_bf16 v[62:65], v[138:141], v[176:179], v[62:65]
	v_mfma_f32_16x16x32_bf16 v[58:61], v[146:149], v[176:179], v[58:61]
	v_mfma_f32_16x16x32_bf16 v[46:49], v[138:141], v[196:199], v[46:49]
	v_mfma_f32_16x16x32_bf16 v[42:45], v[146:149], v[196:199], v[42:45]
	v_mfma_f32_16x16x32_bf16 v[30:33], v[138:141], v[204:207], v[30:33]
	v_mfma_f32_16x16x32_bf16 v[26:29], v[146:149], v[204:207], v[26:29]
	v_mfma_f32_16x16x32_bf16 v[14:17], v[138:141], v[212:215], v[14:17]
	v_mfma_f32_16x16x32_bf16 v[10:13], v[146:149], v[212:215], v[10:13]
	v_mfma_f32_16x16x32_bf16 v[62:65], v[142:145], v[192:195], v[62:65]
	v_mfma_f32_16x16x32_bf16 v[58:61], v[156:159], v[192:195], v[58:61]
	v_mfma_f32_16x16x32_bf16 v[46:49], v[142:145], v[200:203], v[46:49]
	v_mfma_f32_16x16x32_bf16 v[42:45], v[156:159], v[200:203], v[42:45]
	v_mfma_f32_16x16x32_bf16 v[30:33], v[142:145], v[208:211], v[30:33]
	v_mfma_f32_16x16x32_bf16 v[26:29], v[156:159], v[208:211], v[26:29]
	v_mfma_f32_16x16x32_bf16 v[14:17], v[142:145], v[216:219], v[14:17]
	v_mfma_f32_16x16x32_bf16 v[10:13], v[156:159], v[216:219], v[10:13]
	v_mfma_f32_16x16x32_bf16 v[54:57], v[160:163], v[176:179], v[54:57]
	v_mfma_f32_16x16x32_bf16 v[50:53], v[168:171], v[176:179], v[50:53]
	v_mfma_f32_16x16x32_bf16 v[38:41], v[160:163], v[196:199], v[38:41]
	v_mfma_f32_16x16x32_bf16 v[34:37], v[168:171], v[196:199], v[34:37]
	v_mfma_f32_16x16x32_bf16 v[22:25], v[160:163], v[204:207], v[22:25]
	v_mfma_f32_16x16x32_bf16 v[18:21], v[168:171], v[204:207], v[18:21]
	v_mfma_f32_16x16x32_bf16 v[6:9], v[160:163], v[212:215], v[6:9]
	v_mfma_f32_16x16x32_bf16 v[2:5], v[168:171], v[212:215], v[2:5]
	v_mfma_f32_16x16x32_bf16 v[54:57], v[164:167], v[192:195], v[54:57]
	v_mfma_f32_16x16x32_bf16 v[50:53], v[172:175], v[192:195], v[50:53]
	v_mfma_f32_16x16x32_bf16 v[38:41], v[164:167], v[200:203], v[38:41]
	v_mfma_f32_16x16x32_bf16 v[34:37], v[172:175], v[200:203], v[34:37]
	v_mfma_f32_16x16x32_bf16 v[22:25], v[164:167], v[208:211], v[22:25]
	v_mfma_f32_16x16x32_bf16 v[18:21], v[172:175], v[208:211], v[18:21]
	v_mfma_f32_16x16x32_bf16 v[6:9], v[164:167], v[216:219], v[6:9]
	v_mfma_f32_16x16x32_bf16 v[2:5], v[172:175], v[216:219], v[2:5]
	s_barrier
	s_add_i32 s64, 0, 0x18000
	v_add_u32_e32 v155, s64, v153
	s_add_i32 s66, 0, 0x1c000
	ds_read_b128 v[138:141], v155
	ds_read_b128 v[142:145], v155 offset:1024
	ds_read_b128 v[146:149], v155 offset:2048
	ds_read_b128 v[156:159], v155 offset:3072
	v_add_u32_e32 v155, s66, v153
	ds_read_b128 v[160:163], v155
	ds_read_b128 v[164:167], v155 offset:1024
	ds_read_b128 v[168:171], v155 offset:2048
	ds_read_b128 v[172:175], v155 offset:3072
	s_add_u32 s40, s40, 0x80000
	s_addc_u32 s41, s41, 0
	s_mov_b32 m0, s46
	v_lshl_add_u64 v[242:243], s[40:41], 0, v[132:133]
	ds_read_b128 v[176:179], v154 offset:32768
	ds_read_b128 v[192:195], v154 offset:33792
	ds_read_b128 v[196:199], v154 offset:34816
	ds_read_b128 v[200:203], v154 offset:35840
	ds_read_b128 v[204:207], v154 offset:36864
	ds_read_b128 v[208:211], v154 offset:37888
	ds_read_b128 v[212:215], v154 offset:38912
	ds_read_b128 v[216:219], v154 offset:39936
	global_load_lds_dwordx4 v[242:243], off
	v_lshl_add_u64 v[242:243], s[40:41], 0, v[130:131]
	s_mov_b32 m0, s47
	s_nop 0
	global_load_lds_dwordx4 v[242:243], off
	s_waitcnt vmcnt(8)
	s_waitcnt lgkmcnt(0)
	s_barrier
	s_waitcnt lgkmcnt(0)
	v_mfma_f32_16x16x32_bf16 v[126:129], v[138:141], v[176:179], v[126:129]
	v_mfma_f32_16x16x32_bf16 v[122:125], v[146:149], v[176:179], v[122:125]
	v_mfma_f32_16x16x32_bf16 v[110:113], v[138:141], v[196:199], v[110:113]
	v_mfma_f32_16x16x32_bf16 v[106:109], v[146:149], v[196:199], v[106:109]
	v_mfma_f32_16x16x32_bf16 v[94:97], v[138:141], v[204:207], v[94:97]
	v_mfma_f32_16x16x32_bf16 v[90:93], v[146:149], v[204:207], v[90:93]
	v_mfma_f32_16x16x32_bf16 v[78:81], v[138:141], v[212:215], v[78:81]
	v_mfma_f32_16x16x32_bf16 v[74:77], v[146:149], v[212:215], v[74:77]
	v_mfma_f32_16x16x32_bf16 v[126:129], v[142:145], v[192:195], v[126:129]
	v_mfma_f32_16x16x32_bf16 v[122:125], v[156:159], v[192:195], v[122:125]
	v_mfma_f32_16x16x32_bf16 v[110:113], v[142:145], v[200:203], v[110:113]
	v_mfma_f32_16x16x32_bf16 v[106:109], v[156:159], v[200:203], v[106:109]
	v_mfma_f32_16x16x32_bf16 v[94:97], v[142:145], v[208:211], v[94:97]
	v_mfma_f32_16x16x32_bf16 v[90:93], v[156:159], v[208:211], v[90:93]
	v_mfma_f32_16x16x32_bf16 v[78:81], v[142:145], v[216:219], v[78:81]
	v_mfma_f32_16x16x32_bf16 v[74:77], v[156:159], v[216:219], v[74:77]
	v_mfma_f32_16x16x32_bf16 v[118:121], v[160:163], v[176:179], v[118:121]
	v_mfma_f32_16x16x32_bf16 v[114:117], v[168:171], v[176:179], v[114:117]
	v_mfma_f32_16x16x32_bf16 v[102:105], v[160:163], v[196:199], v[102:105]
	v_mfma_f32_16x16x32_bf16 v[98:101], v[168:171], v[196:199], v[98:101]
	v_mfma_f32_16x16x32_bf16 v[86:89], v[160:163], v[204:207], v[86:89]
	v_mfma_f32_16x16x32_bf16 v[82:85], v[168:171], v[204:207], v[82:85]
	v_mfma_f32_16x16x32_bf16 v[70:73], v[160:163], v[212:215], v[70:73]
	v_mfma_f32_16x16x32_bf16 v[66:69], v[168:171], v[212:215], v[66:69]
	v_mfma_f32_16x16x32_bf16 v[118:121], v[164:167], v[192:195], v[118:121]
	v_mfma_f32_16x16x32_bf16 v[114:117], v[172:175], v[192:195], v[114:117]
	v_mfma_f32_16x16x32_bf16 v[102:105], v[164:167], v[200:203], v[102:105]
	v_mfma_f32_16x16x32_bf16 v[98:101], v[172:175], v[200:203], v[98:101]
	v_mfma_f32_16x16x32_bf16 v[86:89], v[164:167], v[208:211], v[86:89]
	v_mfma_f32_16x16x32_bf16 v[82:85], v[172:175], v[208:211], v[82:85]
	v_mfma_f32_16x16x32_bf16 v[70:73], v[164:167], v[216:219], v[70:73]
	v_mfma_f32_16x16x32_bf16 v[66:69], v[172:175], v[216:219], v[66:69]
	s_barrier
	s_add_i32 s40, s64, s43
	v_lshl_add_u64 v[220:221], v[220:221], 0, s[16:17]
	s_mov_b32 m0, s40
	ds_read_b128 v[176:179], v154 offset:49152
	ds_read_b128 v[192:195], v154 offset:50176
	ds_read_b128 v[196:199], v154 offset:51200
	ds_read_b128 v[200:203], v154 offset:52224
	ds_read_b128 v[204:207], v154 offset:53248
	ds_read_b128 v[208:211], v154 offset:54272
	ds_read_b128 v[212:215], v154 offset:55296
	ds_read_b128 v[216:219], v154 offset:56320
	global_load_lds_dwordx4 v[220:221], off
	s_add_i32 m0, s40, 0x2000
	s_add_u32 s26, s26, 0x80080
	v_lshl_add_u64 v[220:221], v[222:223], 0, s[16:17]
	s_addc_u32 s27, s27, 0
	s_add_i32 s40, s66, s43
	global_load_lds_dwordx4 v[220:221], off
	v_lshl_add_u64 v[220:221], s[26:27], 0, v[132:133]
	s_mov_b32 m0, s40
	s_nop 0
	global_load_lds_dwordx4 v[220:221], off
	v_lshl_add_u64 v[220:221], s[26:27], 0, v[130:131]
	s_add_i32 m0, s40, 0x2000
	s_nop 0
	global_load_lds_dwordx4 v[220:221], off
	v_lshl_add_u64 v[220:221], v[238:239], 0, s[16:17]
	s_mov_b32 m0, s50
	s_nop 0
	global_load_lds_dwordx4 v[220:221], off
	v_lshl_add_u64 v[220:221], v[240:241], 0, s[16:17]
	s_mov_b32 m0, s51
	s_nop 0
	global_load_lds_dwordx4 v[220:221], off
	s_waitcnt vmcnt(8)
	s_waitcnt lgkmcnt(0)
	s_barrier
	s_waitcnt lgkmcnt(0)
	v_mfma_f32_16x16x32_bf16 v[62:65], v[138:141], v[176:179], v[62:65]
	v_mfma_f32_16x16x32_bf16 v[58:61], v[146:149], v[176:179], v[58:61]
	v_mfma_f32_16x16x32_bf16 v[46:49], v[138:141], v[196:199], v[46:49]
	v_mfma_f32_16x16x32_bf16 v[42:45], v[146:149], v[196:199], v[42:45]
	v_mfma_f32_16x16x32_bf16 v[30:33], v[138:141], v[204:207], v[30:33]
	v_mfma_f32_16x16x32_bf16 v[26:29], v[146:149], v[204:207], v[26:29]
	v_mfma_f32_16x16x32_bf16 v[14:17], v[138:141], v[212:215], v[14:17]
	v_mfma_f32_16x16x32_bf16 v[10:13], v[146:149], v[212:215], v[10:13]
	v_mfma_f32_16x16x32_bf16 v[62:65], v[142:145], v[192:195], v[62:65]
	v_mfma_f32_16x16x32_bf16 v[58:61], v[156:159], v[192:195], v[58:61]
	v_mfma_f32_16x16x32_bf16 v[46:49], v[142:145], v[200:203], v[46:49]
	v_mfma_f32_16x16x32_bf16 v[42:45], v[156:159], v[200:203], v[42:45]
	v_mfma_f32_16x16x32_bf16 v[30:33], v[142:145], v[208:211], v[30:33]
	v_mfma_f32_16x16x32_bf16 v[26:29], v[156:159], v[208:211], v[26:29]
	v_mfma_f32_16x16x32_bf16 v[14:17], v[142:145], v[216:219], v[14:17]
	v_mfma_f32_16x16x32_bf16 v[10:13], v[156:159], v[216:219], v[10:13]
	v_mfma_f32_16x16x32_bf16 v[54:57], v[160:163], v[176:179], v[54:57]
	v_mfma_f32_16x16x32_bf16 v[50:53], v[168:171], v[176:179], v[50:53]
	v_mfma_f32_16x16x32_bf16 v[38:41], v[160:163], v[196:199], v[38:41]
	v_mfma_f32_16x16x32_bf16 v[34:37], v[168:171], v[196:199], v[34:37]
	v_mfma_f32_16x16x32_bf16 v[22:25], v[160:163], v[204:207], v[22:25]
	v_mfma_f32_16x16x32_bf16 v[18:21], v[168:171], v[204:207], v[18:21]
	v_mfma_f32_16x16x32_bf16 v[6:9], v[160:163], v[212:215], v[6:9]
	v_mfma_f32_16x16x32_bf16 v[2:5], v[168:171], v[212:215], v[2:5]
	v_mfma_f32_16x16x32_bf16 v[54:57], v[164:167], v[192:195], v[54:57]
	v_mfma_f32_16x16x32_bf16 v[50:53], v[172:175], v[192:195], v[50:53]
	v_mfma_f32_16x16x32_bf16 v[38:41], v[164:167], v[200:203], v[38:41]
	v_mfma_f32_16x16x32_bf16 v[34:37], v[172:175], v[200:203], v[34:37]
	v_mfma_f32_16x16x32_bf16 v[22:25], v[164:167], v[208:211], v[22:25]
	v_mfma_f32_16x16x32_bf16 v[18:21], v[172:175], v[208:211], v[18:21]
	v_mfma_f32_16x16x32_bf16 v[6:9], v[164:167], v[216:219], v[6:9]
	v_mfma_f32_16x16x32_bf16 v[2:5], v[172:175], v[216:219], v[2:5]
	s_barrier
	s_add_i32 s63, s63, 2
	s_add_u32 s38, s38, 0x100
	s_addc_u32 s39, s39, 0
	s_add_u32 s61, s61, 0x100
	s_addc_u32 s62, s62, 0
	s_cmp_gt_u32 s63, 29
	s_cbranch_scc0 .LBB0_1761
	s_and_b64 vcc, exec, s[34:35]
	s_cbranch_vccz .LBB0_1764
	s_barrier

.LBB0_2241:
	s_add_u32 s28, s26, 0x100
	s_addc_u32 s29, s27, 0
	s_add_i32 s58, 0, 0x10000
	s_cmpk_eq_i32 s57, 0x52
	s_cselect_b32 s35, s23, s29
	s_cselect_b32 s34, s22, s28
	s_cselect_b32 s31, s25, s39
	s_cselect_b32 s30, s24, s38
	s_add_i32 s59, 0, 0x14000
	v_add_u32_e32 v166, s58, v156
	v_add_u32_e32 v178, s59, v156
	ds_read_b128 v[148:151], v166
	ds_read_b128 v[158:161], v166 offset:1024
	ds_read_b128 v[162:165], v166 offset:2048
	ds_read_b128 v[166:169], v166 offset:3072
	ds_read_b128 v[170:173], v178
	ds_read_b128 v[174:177], v178 offset:1024
	ds_read_b128 v[190:193], v178 offset:2048
	ds_read_b128 v[194:197], v178 offset:3072
	v_lshl_add_u64 v[178:179], s[26:27], 0, v[144:145]
	s_add_i32 m0, s43, 0xc000
	ds_read_b128 v[198:201], v157
	ds_read_b128 v[202:205], v157 offset:1024
	ds_read_b128 v[206:209], v157 offset:2048
	ds_read_b128 v[210:213], v157 offset:3072
	ds_read_b128 v[214:217], v157 offset:4096
	ds_read_b128 v[218:221], v157 offset:5120
	ds_read_b128 v[238:241], v157 offset:6144
	ds_read_b128 v[242:245], v157 offset:7168
	global_load_lds_dwordx4 v[178:179], off
	v_lshl_add_u64 v[178:179], s[26:27], 0, v[146:147]
	s_add_i32 m0, s43, 0xe000
	s_nop 0
	global_load_lds_dwordx4 v[178:179], off
	s_waitcnt vmcnt(8)
	s_waitcnt lgkmcnt(0)
	s_barrier
	s_waitcnt lgkmcnt(0)
	v_mfma_f32_16x16x32_bf16 v[126:129], v[148:151], v[198:201], v[126:129]
	v_mfma_f32_16x16x32_bf16 v[114:117], v[162:165], v[198:201], v[114:117]
	v_mfma_f32_16x16x32_bf16 v[106:109], v[148:151], v[206:209], v[106:109]
	v_mfma_f32_16x16x32_bf16 v[98:101], v[162:165], v[206:209], v[98:101]
	v_mfma_f32_16x16x32_bf16 v[90:93], v[148:151], v[214:217], v[90:93]
	v_mfma_f32_16x16x32_bf16 v[82:85], v[162:165], v[214:217], v[82:85]
	v_mfma_f32_16x16x32_bf16 v[74:77], v[148:151], v[238:241], v[74:77]
	v_mfma_f32_16x16x32_bf16 v[54:57], v[162:165], v[238:241], v[54:57]
	v_mfma_f32_16x16x32_bf16 v[126:129], v[158:161], v[202:205], v[126:129]
	v_mfma_f32_16x16x32_bf16 v[114:117], v[166:169], v[202:205], v[114:117]
	v_mfma_f32_16x16x32_bf16 v[106:109], v[158:161], v[210:213], v[106:109]
	v_mfma_f32_16x16x32_bf16 v[98:101], v[166:169], v[210:213], v[98:101]
	v_mfma_f32_16x16x32_bf16 v[90:93], v[158:161], v[218:221], v[90:93]
	v_mfma_f32_16x16x32_bf16 v[82:85], v[166:169], v[218:221], v[82:85]
	v_mfma_f32_16x16x32_bf16 v[74:77], v[158:161], v[242:245], v[74:77]
	v_mfma_f32_16x16x32_bf16 v[54:57], v[166:169], v[242:245], v[54:57]
	v_mfma_f32_16x16x32_bf16 v[118:121], v[170:173], v[198:201], v[118:121]
	v_mfma_f32_16x16x32_bf16 v[122:125], v[190:193], v[198:201], v[122:125]
	v_mfma_f32_16x16x32_bf16 v[102:105], v[170:173], v[206:209], v[102:105]
	v_mfma_f32_16x16x32_bf16 v[110:113], v[190:193], v[206:209], v[110:113]
	v_mfma_f32_16x16x32_bf16 v[86:89], v[170:173], v[214:217], v[86:89]
	v_mfma_f32_16x16x32_bf16 v[94:97], v[190:193], v[214:217], v[94:97]
	v_mfma_f32_16x16x32_bf16 v[70:73], v[170:173], v[238:241], v[70:73]
	v_mfma_f32_16x16x32_bf16 v[78:81], v[190:193], v[238:241], v[78:81]
	v_mfma_f32_16x16x32_bf16 v[118:121], v[174:177], v[202:205], v[118:121]
	v_mfma_f32_16x16x32_bf16 v[122:125], v[194:197], v[202:205], v[122:125]
	v_mfma_f32_16x16x32_bf16 v[102:105], v[174:177], v[210:213], v[102:105]
	v_mfma_f32_16x16x32_bf16 v[110:113], v[194:197], v[210:213], v[110:113]
	v_mfma_f32_16x16x32_bf16 v[86:89], v[174:177], v[218:221], v[86:89]
	v_mfma_f32_16x16x32_bf16 v[94:97], v[194:197], v[218:221], v[94:97]
	v_mfma_f32_16x16x32_bf16 v[70:73], v[174:177], v[242:245], v[70:73]
	v_mfma_f32_16x16x32_bf16 v[78:81], v[194:197], v[242:245], v[78:81]
	s_barrier
	s_add_i32 s26, s58, s40
	v_lshl_add_u64 v[178:179], s[30:31], 0, v[136:137]
	s_mov_b32 m0, s26
	ds_read_b128 v[198:201], v157 offset:16384
	ds_read_b128 v[202:205], v157 offset:17408
	ds_read_b128 v[206:209], v157 offset:18432
	ds_read_b128 v[210:213], v157 offset:19456
	ds_read_b128 v[214:217], v157 offset:20480
	ds_read_b128 v[218:221], v157 offset:21504
	ds_read_b128 v[238:241], v157 offset:22528
	ds_read_b128 v[242:245], v157 offset:23552
	global_load_lds_dwordx4 v[178:179], off
	s_add_i32 m0, s26, 0x2000
	s_add_u32 s26, s30, 0x158000
	v_lshl_add_u64 v[222:223], s[30:31], 0, v[140:141]
	s_addc_u32 s27, s31, 0
	s_add_i32 s58, s59, s40
	global_load_lds_dwordx4 v[222:223], off
	v_lshl_add_u64 v[246:247], s[26:27], 0, v[136:137]
	s_mov_b32 m0, s58
	v_lshl_add_u64 v[248:249], s[34:35], 0, v[138:139]
	global_load_lds_dwordx4 v[246:247], off
	v_lshl_add_u64 v[246:247], s[26:27], 0, v[140:141]
	s_add_i32 m0, s58, 0x2000
	s_nop 0
	global_load_lds_dwordx4 v[246:247], off
	v_lshl_add_u64 v[246:247], s[34:35], 0, v[134:135]
	s_mov_b32 m0, s43
	s_nop 0
	global_load_lds_dwordx4 v[246:247], off
	s_mov_b32 m0, s44
	s_nop 0
	global_load_lds_dwordx4 v[248:249], off
	s_waitcnt vmcnt(8)
	s_waitcnt lgkmcnt(0)
	s_barrier
	s_waitcnt lgkmcnt(0)
	v_mfma_f32_16x16x32_bf16 v[50:53], v[148:151], v[198:201], v[50:53]
	v_mfma_f32_16x16x32_bf16 v[38:41], v[162:165], v[198:201], v[38:41]
	v_mfma_f32_16x16x32_bf16 v[22:25], v[148:151], v[206:209], v[22:25]
	v_mfma_f32_16x16x32_bf16 v[42:45], v[162:165], v[206:209], v[42:45]
	v_mfma_f32_16x16x32_bf16 v[30:33], v[148:151], v[214:217], v[30:33]
	v_mfma_f32_16x16x32_bf16 v[18:21], v[162:165], v[214:217], v[18:21]
	v_mfma_f32_16x16x32_bf16 v[10:13], v[148:151], v[238:241], v[10:13]
	v_mfma_f32_16x16x32_bf16 v[2:5], v[162:165], v[238:241], v[2:5]
	v_mfma_f32_16x16x32_bf16 v[50:53], v[158:161], v[202:205], v[50:53]
	v_mfma_f32_16x16x32_bf16 v[38:41], v[166:169], v[202:205], v[38:41]
	v_mfma_f32_16x16x32_bf16 v[22:25], v[158:161], v[210:213], v[22:25]
	v_mfma_f32_16x16x32_bf16 v[42:45], v[166:169], v[210:213], v[42:45]
	v_mfma_f32_16x16x32_bf16 v[30:33], v[158:161], v[218:221], v[30:33]
	v_mfma_f32_16x16x32_bf16 v[18:21], v[166:169], v[218:221], v[18:21]
	v_mfma_f32_16x16x32_bf16 v[10:13], v[158:161], v[242:245], v[10:13]
	v_mfma_f32_16x16x32_bf16 v[2:5], v[166:169], v[242:245], v[2:5]
	v_mfma_f32_16x16x32_bf16 v[46:49], v[170:173], v[198:201], v[46:49]
	v_mfma_f32_16x16x32_bf16 v[58:61], v[190:193], v[198:201], v[58:61]
	v_mfma_f32_16x16x32_bf16 v[62:65], v[170:173], v[206:209], v[62:65]
	v_mfma_f32_16x16x32_bf16 v[66:69], v[190:193], v[206:209], v[66:69]
	v_mfma_f32_16x16x32_bf16 v[26:29], v[170:173], v[214:217], v[26:29]
	v_mfma_f32_16x16x32_bf16 v[34:37], v[190:193], v[214:217], v[34:37]
	v_mfma_f32_16x16x32_bf16 v[6:9], v[170:173], v[238:241], v[6:9]
	v_mfma_f32_16x16x32_bf16 v[14:17], v[190:193], v[238:241], v[14:17]
	v_mfma_f32_16x16x32_bf16 v[46:49], v[174:177], v[202:205], v[46:49]
	v_mfma_f32_16x16x32_bf16 v[58:61], v[194:197], v[202:205], v[58:61]
	v_mfma_f32_16x16x32_bf16 v[62:65], v[174:177], v[210:213], v[62:65]
	v_mfma_f32_16x16x32_bf16 v[66:69], v[194:197], v[210:213], v[66:69]
	v_mfma_f32_16x16x32_bf16 v[26:29], v[174:177], v[218:221], v[26:29]
	v_mfma_f32_16x16x32_bf16 v[34:37], v[194:197], v[218:221], v[34:37]
	v_mfma_f32_16x16x32_bf16 v[6:9], v[174:177], v[242:245], v[6:9]
	v_mfma_f32_16x16x32_bf16 v[14:17], v[194:197], v[242:245], v[14:17]
	s_barrier
	s_add_i32 s58, 0, 0x18000
	s_add_i32 s59, 0, 0x1c000
	v_add_u32_e32 v166, s58, v156
	v_add_u32_e32 v194, s59, v156
	ds_read_b128 v[148:151], v166
	ds_read_b128 v[158:161], v166 offset:1024
	ds_read_b128 v[162:165], v166 offset:2048
	ds_read_b128 v[166:169], v166 offset:3072
	ds_read_b128 v[170:173], v194
	ds_read_b128 v[174:177], v194 offset:1024
	ds_read_b128 v[190:193], v194 offset:2048
	ds_read_b128 v[194:197], v194 offset:3072
	s_add_u32 s26, s34, 0x158000
	s_addc_u32 s27, s35, 0
	s_mov_b32 m0, s45
	v_lshl_add_u64 v[250:251], s[26:27], 0, v[134:135]
	ds_read_b128 v[198:201], v157 offset:32768
	ds_read_b128 v[202:205], v157 offset:33792
	ds_read_b128 v[206:209], v157 offset:34816
	ds_read_b128 v[210:213], v157 offset:35840
	ds_read_b128 v[214:217], v157 offset:36864
	ds_read_b128 v[218:221], v157 offset:37888
	ds_read_b128 v[238:241], v157 offset:38912
	ds_read_b128 v[242:245], v157 offset:39936
	global_load_lds_dwordx4 v[250:251], off
	v_lshl_add_u64 v[250:251], s[26:27], 0, v[138:139]
	s_mov_b32 m0, s47
	s_nop 0
	global_load_lds_dwordx4 v[250:251], off
	s_waitcnt vmcnt(8)
	s_waitcnt lgkmcnt(0)
	s_barrier
	s_waitcnt lgkmcnt(0)
	v_mfma_f32_16x16x32_bf16 v[126:129], v[148:151], v[198:201], v[126:129]
	v_mfma_f32_16x16x32_bf16 v[114:117], v[162:165], v[198:201], v[114:117]
	v_mfma_f32_16x16x32_bf16 v[106:109], v[148:151], v[206:209], v[106:109]
	v_mfma_f32_16x16x32_bf16 v[98:101], v[162:165], v[206:209], v[98:101]
	v_mfma_f32_16x16x32_bf16 v[90:93], v[148:151], v[214:217], v[90:93]
	v_mfma_f32_16x16x32_bf16 v[82:85], v[162:165], v[214:217], v[82:85]
	v_mfma_f32_16x16x32_bf16 v[74:77], v[148:151], v[238:241], v[74:77]
	v_mfma_f32_16x16x32_bf16 v[54:57], v[162:165], v[238:241], v[54:57]
	v_mfma_f32_16x16x32_bf16 v[126:129], v[158:161], v[202:205], v[126:129]
	v_mfma_f32_16x16x32_bf16 v[114:117], v[166:169], v[202:205], v[114:117]
	v_mfma_f32_16x16x32_bf16 v[106:109], v[158:161], v[210:213], v[106:109]
	v_mfma_f32_16x16x32_bf16 v[98:101], v[166:169], v[210:213], v[98:101]
	v_mfma_f32_16x16x32_bf16 v[90:93], v[158:161], v[218:221], v[90:93]
	v_mfma_f32_16x16x32_bf16 v[82:85], v[166:169], v[218:221], v[82:85]
	v_mfma_f32_16x16x32_bf16 v[74:77], v[158:161], v[242:245], v[74:77]
	v_mfma_f32_16x16x32_bf16 v[54:57], v[166:169], v[242:245], v[54:57]
	v_mfma_f32_16x16x32_bf16 v[118:121], v[170:173], v[198:201], v[118:121]
	v_mfma_f32_16x16x32_bf16 v[122:125], v[190:193], v[198:201], v[122:125]
	v_mfma_f32_16x16x32_bf16 v[102:105], v[170:173], v[206:209], v[102:105]
	v_mfma_f32_16x16x32_bf16 v[110:113], v[190:193], v[206:209], v[110:113]
	v_mfma_f32_16x16x32_bf16 v[86:89], v[170:173], v[214:217], v[86:89]
	v_mfma_f32_16x16x32_bf16 v[94:97], v[190:193], v[214:217], v[94:97]
	v_mfma_f32_16x16x32_bf16 v[70:73], v[170:173], v[238:241], v[70:73]
	v_mfma_f32_16x16x32_bf16 v[78:81], v[190:193], v[238:241], v[78:81]
	v_mfma_f32_16x16x32_bf16 v[118:121], v[174:177], v[202:205], v[118:121]
	v_mfma_f32_16x16x32_bf16 v[122:125], v[194:197], v[202:205], v[122:125]
	v_mfma_f32_16x16x32_bf16 v[102:105], v[174:177], v[210:213], v[102:105]
	v_mfma_f32_16x16x32_bf16 v[110:113], v[194:197], v[210:213], v[110:113]
	v_mfma_f32_16x16x32_bf16 v[86:89], v[174:177], v[218:221], v[86:89]
	v_mfma_f32_16x16x32_bf16 v[94:97], v[194:197], v[218:221], v[94:97]
	v_mfma_f32_16x16x32_bf16 v[70:73], v[174:177], v[242:245], v[70:73]
	v_mfma_f32_16x16x32_bf16 v[78:81], v[194:197], v[242:245], v[78:81]
	s_barrier
	s_add_i32 s26, s58, s40
	v_lshl_add_u64 v[178:179], v[178:179], 0, s[16:17]
	s_mov_b32 m0, s26
	ds_read_b128 v[198:201], v157 offset:49152
	ds_read_b128 v[202:205], v157 offset:50176
	ds_read_b128 v[206:209], v157 offset:51200
	ds_read_b128 v[210:213], v157 offset:52224
	ds_read_b128 v[214:217], v157 offset:53248
	ds_read_b128 v[218:221], v157 offset:54272
	ds_read_b128 v[238:241], v157 offset:55296
	ds_read_b128 v[242:245], v157 offset:56320
	global_load_lds_dwordx4 v[178:179], off
	s_add_i32 m0, s26, 0x2000
	s_add_u32 s26, s30, 0x158080
	v_lshl_add_u64 v[178:179], v[222:223], 0, s[16:17]
	s_addc_u32 s27, s31, 0
	s_add_i32 s30, s59, s40
	global_load_lds_dwordx4 v[178:179], off
	v_lshl_add_u64 v[178:179], s[26:27], 0, v[136:137]
	s_mov_b32 m0, s30
	s_nop 0
	global_load_lds_dwordx4 v[178:179], off
	v_lshl_add_u64 v[178:179], s[26:27], 0, v[140:141]
	s_add_i32 m0, s30, 0x2000
	s_nop 0
	global_load_lds_dwordx4 v[178:179], off
	v_lshl_add_u64 v[178:179], v[246:247], 0, s[16:17]
	s_mov_b32 m0, s48
	s_nop 0
	global_load_lds_dwordx4 v[178:179], off
	v_lshl_add_u64 v[178:179], v[248:249], 0, s[16:17]
	s_mov_b32 m0, s49
	s_nop 0
	global_load_lds_dwordx4 v[178:179], off
	s_waitcnt vmcnt(8)
	s_waitcnt lgkmcnt(0)
	s_barrier
	s_waitcnt lgkmcnt(0)
	v_mfma_f32_16x16x32_bf16 v[50:53], v[148:151], v[198:201], v[50:53]
	v_mfma_f32_16x16x32_bf16 v[38:41], v[162:165], v[198:201], v[38:41]
	v_mfma_f32_16x16x32_bf16 v[22:25], v[148:151], v[206:209], v[22:25]
	v_mfma_f32_16x16x32_bf16 v[42:45], v[162:165], v[206:209], v[42:45]
	v_mfma_f32_16x16x32_bf16 v[30:33], v[148:151], v[214:217], v[30:33]
	v_mfma_f32_16x16x32_bf16 v[18:21], v[162:165], v[214:217], v[18:21]
	v_mfma_f32_16x16x32_bf16 v[10:13], v[148:151], v[238:241], v[10:13]
	v_mfma_f32_16x16x32_bf16 v[2:5], v[162:165], v[238:241], v[2:5]
	v_mfma_f32_16x16x32_bf16 v[50:53], v[158:161], v[202:205], v[50:53]
	v_mfma_f32_16x16x32_bf16 v[38:41], v[166:169], v[202:205], v[38:41]
	v_mfma_f32_16x16x32_bf16 v[22:25], v[158:161], v[210:213], v[22:25]
	v_mfma_f32_16x16x32_bf16 v[42:45], v[166:169], v[210:213], v[42:45]
	v_mfma_f32_16x16x32_bf16 v[30:33], v[158:161], v[218:221], v[30:33]
	v_mfma_f32_16x16x32_bf16 v[18:21], v[166:169], v[218:221], v[18:21]
	v_mfma_f32_16x16x32_bf16 v[10:13], v[158:161], v[242:245], v[10:13]
	v_mfma_f32_16x16x32_bf16 v[2:5], v[166:169], v[242:245], v[2:5]
	v_mfma_f32_16x16x32_bf16 v[46:49], v[170:173], v[198:201], v[46:49]
	v_mfma_f32_16x16x32_bf16 v[58:61], v[190:193], v[198:201], v[58:61]
	v_mfma_f32_16x16x32_bf16 v[62:65], v[170:173], v[206:209], v[62:65]
	v_mfma_f32_16x16x32_bf16 v[66:69], v[190:193], v[206:209], v[66:69]
	v_mfma_f32_16x16x32_bf16 v[26:29], v[170:173], v[214:217], v[26:29]
	v_mfma_f32_16x16x32_bf16 v[34:37], v[190:193], v[214:217], v[34:37]
	v_mfma_f32_16x16x32_bf16 v[6:9], v[170:173], v[238:241], v[6:9]
	v_mfma_f32_16x16x32_bf16 v[14:17], v[190:193], v[238:241], v[14:17]
	v_mfma_f32_16x16x32_bf16 v[46:49], v[174:177], v[202:205], v[46:49]
	v_mfma_f32_16x16x32_bf16 v[58:61], v[194:197], v[202:205], v[58:61]
	v_mfma_f32_16x16x32_bf16 v[62:65], v[174:177], v[210:213], v[62:65]
	v_mfma_f32_16x16x32_bf16 v[66:69], v[194:197], v[210:213], v[66:69]
	v_mfma_f32_16x16x32_bf16 v[26:29], v[174:177], v[218:221], v[26:29]
	v_mfma_f32_16x16x32_bf16 v[34:37], v[194:197], v[218:221], v[34:37]
	v_mfma_f32_16x16x32_bf16 v[6:9], v[174:177], v[242:245], v[6:9]
	v_mfma_f32_16x16x32_bf16 v[14:17], v[194:197], v[242:245], v[14:17]
	s_barrier
	s_add_i32 s57, s57, 2
	s_add_u32 s38, s38, 0x100
	s_addc_u32 s39, s39, 0
	s_cmpk_gt_u32 s57, 0x53
	s_mov_b64 s[26:27], s[28:29]
	s_cbranch_scc0 .LBB0_2241
	s_and_b64 vcc, exec, s[18:19]
	s_cbranch_vccz .LBB0_2244
	s_barrier

.LBB0_2293:
	s_add_u32 s30, s28, 0x100
	s_addc_u32 s31, s29, 0
	s_add_i32 s46, 0, 0x10000
	s_cmpk_eq_i32 s45, 0x52
	s_cselect_b32 s39, s25, s31
	s_cselect_b32 s38, s24, s30
	s_cselect_b32 s35, s27, s44
	s_cselect_b32 s34, s26, s43
	s_add_i32 s47, 0, 0x14000
	v_add_u32_e32 v142, s46, v200
	v_add_u32_e32 v176, s47, v200
	ds_read_b128 v[130:133], v142
	ds_read_b128 v[134:137], v142 offset:1024
	ds_read_b128 v[138:141], v142 offset:2048
	ds_read_b128 v[142:145], v142 offset:3072
	ds_read_b128 v[164:167], v176
	ds_read_b128 v[168:171], v176 offset:1024
	ds_read_b128 v[172:175], v176 offset:2048
	ds_read_b128 v[176:179], v176 offset:3072
	v_lshl_add_u64 v[222:223], s[28:29], 0, v[160:161]
	s_add_i32 m0, s56, 0xc000
	ds_read_b128 v[190:193], v201
	ds_read_b128 v[202:205], v201 offset:1024
	ds_read_b128 v[206:209], v201 offset:2048
	ds_read_b128 v[210:213], v201 offset:3072
	ds_read_b128 v[214:217], v201 offset:4096
	ds_read_b128 v[218:221], v201 offset:5120
	ds_read_b128 v[238:241], v201 offset:6144
	ds_read_b128 v[242:245], v201 offset:7168
	global_load_lds_dwordx4 v[222:223], off
	v_lshl_add_u64 v[222:223], s[28:29], 0, v[162:163]
	s_add_i32 m0, s56, 0xe000
	s_nop 0
	global_load_lds_dwordx4 v[222:223], off
	s_waitcnt vmcnt(8)
	s_waitcnt lgkmcnt(0)
	s_barrier
	s_waitcnt lgkmcnt(0)
	v_mfma_f32_16x16x32_bf16 v[118:121], v[130:133], v[190:193], v[118:121]
	v_mfma_f32_16x16x32_bf16 v[114:117], v[138:141], v[190:193], v[114:117]
	v_mfma_f32_16x16x32_bf16 v[98:101], v[130:133], v[206:209], v[98:101]
	v_mfma_f32_16x16x32_bf16 v[102:105], v[138:141], v[206:209], v[102:105]
	v_mfma_f32_16x16x32_bf16 v[70:73], v[130:133], v[214:217], v[70:73]
	v_mfma_f32_16x16x32_bf16 v[74:77], v[138:141], v[214:217], v[74:77]
	v_mfma_f32_16x16x32_bf16 v[30:33], v[130:133], v[238:241], v[30:33]
	v_mfma_f32_16x16x32_bf16 v[34:37], v[138:141], v[238:241], v[34:37]
	v_mfma_f32_16x16x32_bf16 v[118:121], v[134:137], v[202:205], v[118:121]
	v_mfma_f32_16x16x32_bf16 v[114:117], v[142:145], v[202:205], v[114:117]
	v_mfma_f32_16x16x32_bf16 v[98:101], v[134:137], v[210:213], v[98:101]
	v_mfma_f32_16x16x32_bf16 v[102:105], v[142:145], v[210:213], v[102:105]
	v_mfma_f32_16x16x32_bf16 v[70:73], v[134:137], v[218:221], v[70:73]
	v_mfma_f32_16x16x32_bf16 v[74:77], v[142:145], v[218:221], v[74:77]
	v_mfma_f32_16x16x32_bf16 v[30:33], v[134:137], v[242:245], v[30:33]
	v_mfma_f32_16x16x32_bf16 v[34:37], v[142:145], v[242:245], v[34:37]
	v_mfma_f32_16x16x32_bf16 v[126:129], v[164:167], v[190:193], v[126:129]
	v_mfma_f32_16x16x32_bf16 v[122:125], v[172:175], v[190:193], v[122:125]
	v_mfma_f32_16x16x32_bf16 v[106:109], v[164:167], v[206:209], v[106:109]
	v_mfma_f32_16x16x32_bf16 v[110:113], v[172:175], v[206:209], v[110:113]
	v_mfma_f32_16x16x32_bf16 v[82:85], v[164:167], v[214:217], v[82:85]
	v_mfma_f32_16x16x32_bf16 v[86:89], v[172:175], v[214:217], v[86:89]
	v_mfma_f32_16x16x32_bf16 v[54:57], v[164:167], v[238:241], v[54:57]
	v_mfma_f32_16x16x32_bf16 v[58:61], v[172:175], v[238:241], v[58:61]
	v_mfma_f32_16x16x32_bf16 v[126:129], v[168:171], v[202:205], v[126:129]
	v_mfma_f32_16x16x32_bf16 v[122:125], v[176:179], v[202:205], v[122:125]
	v_mfma_f32_16x16x32_bf16 v[106:109], v[168:171], v[210:213], v[106:109]
	v_mfma_f32_16x16x32_bf16 v[110:113], v[176:179], v[210:213], v[110:113]
	v_mfma_f32_16x16x32_bf16 v[82:85], v[168:171], v[218:221], v[82:85]
	v_mfma_f32_16x16x32_bf16 v[86:89], v[176:179], v[218:221], v[86:89]
	v_mfma_f32_16x16x32_bf16 v[54:57], v[168:171], v[242:245], v[54:57]
	v_mfma_f32_16x16x32_bf16 v[58:61], v[176:179], v[242:245], v[58:61]
	s_barrier
	s_add_i32 s28, s46, s21
	v_lshl_add_u64 v[222:223], s[34:35], 0, v[150:151]
	s_mov_b32 m0, s28
	ds_read_b128 v[190:193], v201 offset:16384
	ds_read_b128 v[202:205], v201 offset:17408
	ds_read_b128 v[206:209], v201 offset:18432
	ds_read_b128 v[210:213], v201 offset:19456
	ds_read_b128 v[214:217], v201 offset:20480
	ds_read_b128 v[218:221], v201 offset:21504
	ds_read_b128 v[238:241], v201 offset:22528
	ds_read_b128 v[242:245], v201 offset:23552
	global_load_lds_dwordx4 v[222:223], off
	s_add_i32 m0, s28, 0x2000
	s_add_u32 s28, s34, 0x158000
	v_lshl_add_u64 v[246:247], s[34:35], 0, v[154:155]
	s_addc_u32 s29, s35, 0
	s_add_i32 s46, s47, s21
	global_load_lds_dwordx4 v[246:247], off
	v_lshl_add_u64 v[248:249], s[28:29], 0, v[150:151]
	s_mov_b32 m0, s46
	v_lshl_add_u64 v[250:251], s[38:39], 0, v[152:153]
	global_load_lds_dwordx4 v[248:249], off
	v_lshl_add_u64 v[248:249], s[28:29], 0, v[154:155]
	s_add_i32 m0, s46, 0x2000
	s_nop 0
	global_load_lds_dwordx4 v[248:249], off
	v_lshl_add_u64 v[248:249], s[38:39], 0, v[148:149]
	s_mov_b32 m0, s56
	s_nop 0
	global_load_lds_dwordx4 v[248:249], off
	s_mov_b32 m0, s57
	s_nop 0
	global_load_lds_dwordx4 v[250:251], off
	s_waitcnt vmcnt(8)
	s_waitcnt lgkmcnt(0)
	s_barrier
	s_waitcnt lgkmcnt(0)
	v_mfma_f32_16x16x32_bf16 v[22:25], v[130:133], v[190:193], v[22:25]
	v_mfma_f32_16x16x32_bf16 v[26:29], v[138:141], v[190:193], v[26:29]
	v_mfma_f32_16x16x32_bf16 v[10:13], v[130:133], v[206:209], v[10:13]
	v_mfma_f32_16x16x32_bf16 v[78:81], v[138:141], v[206:209], v[78:81]
	v_mfma_f32_16x16x32_bf16 v[38:41], v[130:133], v[214:217], v[38:41]
	v_mfma_f32_16x16x32_bf16 v[42:45], v[138:141], v[214:217], v[42:45]
	v_mfma_f32_16x16x32_bf16 v[2:5], v[130:133], v[238:241], v[2:5]
	v_mfma_f32_16x16x32_bf16 v[6:9], v[138:141], v[238:241], v[6:9]
	v_mfma_f32_16x16x32_bf16 v[22:25], v[134:137], v[202:205], v[22:25]
	v_mfma_f32_16x16x32_bf16 v[26:29], v[142:145], v[202:205], v[26:29]
	v_mfma_f32_16x16x32_bf16 v[10:13], v[134:137], v[210:213], v[10:13]
	v_mfma_f32_16x16x32_bf16 v[78:81], v[142:145], v[210:213], v[78:81]
	v_mfma_f32_16x16x32_bf16 v[38:41], v[134:137], v[218:221], v[38:41]
	v_mfma_f32_16x16x32_bf16 v[42:45], v[142:145], v[218:221], v[42:45]
	v_mfma_f32_16x16x32_bf16 v[2:5], v[134:137], v[242:245], v[2:5]
	v_mfma_f32_16x16x32_bf16 v[6:9], v[142:145], v[242:245], v[6:9]
	v_mfma_f32_16x16x32_bf16 v[46:49], v[164:167], v[190:193], v[46:49]
	v_mfma_f32_16x16x32_bf16 v[50:53], v[172:175], v[190:193], v[50:53]
	v_mfma_f32_16x16x32_bf16 v[90:93], v[164:167], v[206:209], v[90:93]
	v_mfma_f32_16x16x32_bf16 v[94:97], v[172:175], v[206:209], v[94:97]
	v_mfma_f32_16x16x32_bf16 v[62:65], v[164:167], v[214:217], v[62:65]
	v_mfma_f32_16x16x32_bf16 v[66:69], v[172:175], v[214:217], v[66:69]
	v_mfma_f32_16x16x32_bf16 v[14:17], v[164:167], v[238:241], v[14:17]
	v_mfma_f32_16x16x32_bf16 v[18:21], v[172:175], v[238:241], v[18:21]
	v_mfma_f32_16x16x32_bf16 v[46:49], v[168:171], v[202:205], v[46:49]
	v_mfma_f32_16x16x32_bf16 v[50:53], v[176:179], v[202:205], v[50:53]
	v_mfma_f32_16x16x32_bf16 v[90:93], v[168:171], v[210:213], v[90:93]
	v_mfma_f32_16x16x32_bf16 v[94:97], v[176:179], v[210:213], v[94:97]
	v_mfma_f32_16x16x32_bf16 v[62:65], v[168:171], v[218:221], v[62:65]
	v_mfma_f32_16x16x32_bf16 v[66:69], v[176:179], v[218:221], v[66:69]
	v_mfma_f32_16x16x32_bf16 v[14:17], v[168:171], v[242:245], v[14:17]
	v_mfma_f32_16x16x32_bf16 v[18:21], v[176:179], v[242:245], v[18:21]
	s_barrier
	s_add_i32 s46, 0, 0x18000
	s_add_i32 s47, 0, 0x1c000
	v_add_u32_e32 v142, s46, v200
	v_add_u32_e32 v176, s47, v200
	ds_read_b128 v[130:133], v142
	ds_read_b128 v[134:137], v142 offset:1024
	ds_read_b128 v[138:141], v142 offset:2048
	ds_read_b128 v[142:145], v142 offset:3072
	ds_read_b128 v[164:167], v176
	ds_read_b128 v[168:171], v176 offset:1024
	ds_read_b128 v[172:175], v176 offset:2048
	ds_read_b128 v[176:179], v176 offset:3072
	s_add_u32 s28, s38, 0x158000
	s_addc_u32 s29, s39, 0
	s_mov_b32 m0, s58
	v_lshl_add_u64 v[252:253], s[28:29], 0, v[148:149]
	ds_read_b128 v[190:193], v201 offset:32768
	ds_read_b128 v[202:205], v201 offset:33792
	ds_read_b128 v[206:209], v201 offset:34816
	ds_read_b128 v[210:213], v201 offset:35840
	ds_read_b128 v[214:217], v201 offset:36864
	ds_read_b128 v[218:221], v201 offset:37888
	ds_read_b128 v[238:241], v201 offset:38912
	ds_read_b128 v[242:245], v201 offset:39936
	global_load_lds_dwordx4 v[252:253], off
	v_lshl_add_u64 v[252:253], s[28:29], 0, v[152:153]
	s_mov_b32 m0, s59
	s_nop 0
	global_load_lds_dwordx4 v[252:253], off
	s_waitcnt vmcnt(8)
	s_waitcnt lgkmcnt(0)
	s_barrier
	s_waitcnt lgkmcnt(0)
	v_mfma_f32_16x16x32_bf16 v[118:121], v[130:133], v[190:193], v[118:121]
	v_mfma_f32_16x16x32_bf16 v[114:117], v[138:141], v[190:193], v[114:117]
	v_mfma_f32_16x16x32_bf16 v[98:101], v[130:133], v[206:209], v[98:101]
	v_mfma_f32_16x16x32_bf16 v[102:105], v[138:141], v[206:209], v[102:105]
	v_mfma_f32_16x16x32_bf16 v[70:73], v[130:133], v[214:217], v[70:73]
	v_mfma_f32_16x16x32_bf16 v[74:77], v[138:141], v[214:217], v[74:77]
	v_mfma_f32_16x16x32_bf16 v[30:33], v[130:133], v[238:241], v[30:33]
	v_mfma_f32_16x16x32_bf16 v[34:37], v[138:141], v[238:241], v[34:37]
	v_mfma_f32_16x16x32_bf16 v[118:121], v[134:137], v[202:205], v[118:121]
	v_mfma_f32_16x16x32_bf16 v[114:117], v[142:145], v[202:205], v[114:117]
	v_mfma_f32_16x16x32_bf16 v[98:101], v[134:137], v[210:213], v[98:101]
	v_mfma_f32_16x16x32_bf16 v[102:105], v[142:145], v[210:213], v[102:105]
	v_mfma_f32_16x16x32_bf16 v[70:73], v[134:137], v[218:221], v[70:73]
	v_mfma_f32_16x16x32_bf16 v[74:77], v[142:145], v[218:221], v[74:77]
	v_mfma_f32_16x16x32_bf16 v[30:33], v[134:137], v[242:245], v[30:33]
	v_mfma_f32_16x16x32_bf16 v[34:37], v[142:145], v[242:245], v[34:37]
	v_mfma_f32_16x16x32_bf16 v[126:129], v[164:167], v[190:193], v[126:129]
	v_mfma_f32_16x16x32_bf16 v[122:125], v[172:175], v[190:193], v[122:125]
	v_mfma_f32_16x16x32_bf16 v[106:109], v[164:167], v[206:209], v[106:109]
	v_mfma_f32_16x16x32_bf16 v[110:113], v[172:175], v[206:209], v[110:113]
	v_mfma_f32_16x16x32_bf16 v[82:85], v[164:167], v[214:217], v[82:85]
	v_mfma_f32_16x16x32_bf16 v[86:89], v[172:175], v[214:217], v[86:89]
	v_mfma_f32_16x16x32_bf16 v[54:57], v[164:167], v[238:241], v[54:57]
	v_mfma_f32_16x16x32_bf16 v[58:61], v[172:175], v[238:241], v[58:61]
	v_mfma_f32_16x16x32_bf16 v[126:129], v[168:171], v[202:205], v[126:129]
	v_mfma_f32_16x16x32_bf16 v[122:125], v[176:179], v[202:205], v[122:125]
	v_mfma_f32_16x16x32_bf16 v[106:109], v[168:171], v[210:213], v[106:109]
	v_mfma_f32_16x16x32_bf16 v[110:113], v[176:179], v[210:213], v[110:113]
	v_mfma_f32_16x16x32_bf16 v[82:85], v[168:171], v[218:221], v[82:85]
	v_mfma_f32_16x16x32_bf16 v[86:89], v[176:179], v[218:221], v[86:89]
	v_mfma_f32_16x16x32_bf16 v[54:57], v[168:171], v[242:245], v[54:57]
	v_mfma_f32_16x16x32_bf16 v[58:61], v[176:179], v[242:245], v[58:61]
	s_barrier
	s_add_i32 s28, s46, s21
	v_lshl_add_u64 v[222:223], v[222:223], 0, s[16:17]
	s_mov_b32 m0, s28
	ds_read_b128 v[190:193], v201 offset:49152
	ds_read_b128 v[202:205], v201 offset:50176
	ds_read_b128 v[206:209], v201 offset:51200
	ds_read_b128 v[210:213], v201 offset:52224
	ds_read_b128 v[214:217], v201 offset:53248
	ds_read_b128 v[218:221], v201 offset:54272
	ds_read_b128 v[238:241], v201 offset:55296
	ds_read_b128 v[242:245], v201 offset:56320
	global_load_lds_dwordx4 v[222:223], off
	s_add_i32 m0, s28, 0x2000
	s_add_u32 s28, s34, 0x158080
	v_lshl_add_u64 v[222:223], v[246:247], 0, s[16:17]
	s_addc_u32 s29, s35, 0
	s_add_i32 s34, s47, s21
	global_load_lds_dwordx4 v[222:223], off
	v_lshl_add_u64 v[222:223], s[28:29], 0, v[150:151]
	s_mov_b32 m0, s34
	s_nop 0
	global_load_lds_dwordx4 v[222:223], off
	v_lshl_add_u64 v[222:223], s[28:29], 0, v[154:155]
	s_add_i32 m0, s34, 0x2000
	s_nop 0
	global_load_lds_dwordx4 v[222:223], off
	v_lshl_add_u64 v[222:223], v[248:249], 0, s[16:17]
	s_mov_b32 m0, s60
	s_nop 0
	global_load_lds_dwordx4 v[222:223], off
	v_lshl_add_u64 v[222:223], v[250:251], 0, s[16:17]
	s_mov_b32 m0, s61
	s_nop 0
	global_load_lds_dwordx4 v[222:223], off
	s_waitcnt vmcnt(8)
	s_waitcnt lgkmcnt(0)
	s_barrier
	s_waitcnt lgkmcnt(0)
	v_mfma_f32_16x16x32_bf16 v[22:25], v[130:133], v[190:193], v[22:25]
	v_mfma_f32_16x16x32_bf16 v[26:29], v[138:141], v[190:193], v[26:29]
	v_mfma_f32_16x16x32_bf16 v[10:13], v[130:133], v[206:209], v[10:13]
	v_mfma_f32_16x16x32_bf16 v[78:81], v[138:141], v[206:209], v[78:81]
	v_mfma_f32_16x16x32_bf16 v[38:41], v[130:133], v[214:217], v[38:41]
	v_mfma_f32_16x16x32_bf16 v[42:45], v[138:141], v[214:217], v[42:45]
	v_mfma_f32_16x16x32_bf16 v[2:5], v[130:133], v[238:241], v[2:5]
	v_mfma_f32_16x16x32_bf16 v[6:9], v[138:141], v[238:241], v[6:9]
	v_mfma_f32_16x16x32_bf16 v[22:25], v[134:137], v[202:205], v[22:25]
	v_mfma_f32_16x16x32_bf16 v[26:29], v[142:145], v[202:205], v[26:29]
	v_mfma_f32_16x16x32_bf16 v[10:13], v[134:137], v[210:213], v[10:13]
	v_mfma_f32_16x16x32_bf16 v[78:81], v[142:145], v[210:213], v[78:81]
	v_mfma_f32_16x16x32_bf16 v[38:41], v[134:137], v[218:221], v[38:41]
	v_mfma_f32_16x16x32_bf16 v[42:45], v[142:145], v[218:221], v[42:45]
	v_mfma_f32_16x16x32_bf16 v[2:5], v[134:137], v[242:245], v[2:5]
	v_mfma_f32_16x16x32_bf16 v[6:9], v[142:145], v[242:245], v[6:9]
	v_mfma_f32_16x16x32_bf16 v[46:49], v[164:167], v[190:193], v[46:49]
	v_mfma_f32_16x16x32_bf16 v[50:53], v[172:175], v[190:193], v[50:53]
	v_mfma_f32_16x16x32_bf16 v[90:93], v[164:167], v[206:209], v[90:93]
	v_mfma_f32_16x16x32_bf16 v[94:97], v[172:175], v[206:209], v[94:97]
	v_mfma_f32_16x16x32_bf16 v[62:65], v[164:167], v[214:217], v[62:65]
	v_mfma_f32_16x16x32_bf16 v[66:69], v[172:175], v[214:217], v[66:69]
	v_mfma_f32_16x16x32_bf16 v[14:17], v[164:167], v[238:241], v[14:17]
	v_mfma_f32_16x16x32_bf16 v[18:21], v[172:175], v[238:241], v[18:21]
	v_mfma_f32_16x16x32_bf16 v[46:49], v[168:171], v[202:205], v[46:49]
	v_mfma_f32_16x16x32_bf16 v[50:53], v[176:179], v[202:205], v[50:53]
	v_mfma_f32_16x16x32_bf16 v[90:93], v[168:171], v[210:213], v[90:93]
	v_mfma_f32_16x16x32_bf16 v[94:97], v[176:179], v[210:213], v[94:97]
	v_mfma_f32_16x16x32_bf16 v[62:65], v[168:171], v[218:221], v[62:65]
	v_mfma_f32_16x16x32_bf16 v[66:69], v[176:179], v[218:221], v[66:69]
	v_mfma_f32_16x16x32_bf16 v[14:17], v[168:171], v[242:245], v[14:17]
	v_mfma_f32_16x16x32_bf16 v[18:21], v[176:179], v[242:245], v[18:21]
	s_barrier
	s_add_i32 s45, s45, 2
	s_add_u32 s43, s43, 0x100
	s_addc_u32 s44, s44, 0
	s_cmpk_gt_u32 s45, 0x53
	s_mov_b64 s[28:29], s[30:31]
	s_cbranch_scc0 .LBB0_2293
	s_and_b64 vcc, exec, s[22:23]
	s_cbranch_vccz .LBB0_2296
	s_barrier
